# GEMM MFMA blocks: the s_setprio 0 / s_setprio 1 pair between the two 16-MFMA groups removed (priority stays raised across the block)
# speedup vs baseline: 1.0021x; 1.0021x over previous
.LBB0_329:
	s_waitcnt lgkmcnt(0)
	s_barrier
	s_setprio 1
	s_waitcnt lgkmcnt(0)
	v_mfma_f32_16x16x32_bf16 v[66:69], v[150:153], v[190:193], v[66:69]
	v_mfma_f32_16x16x32_bf16 v[58:61], v[158:161], v[190:193], v[58:61]
	v_mfma_f32_16x16x32_bf16 v[50:53], v[150:153], v[182:185], v[50:53]
	v_mfma_f32_16x16x32_bf16 v[42:45], v[158:161], v[182:185], v[42:45]
	v_mfma_f32_16x16x32_bf16 v[34:37], v[150:153], v[174:177], v[34:37]
	v_mfma_f32_16x16x32_bf16 v[26:29], v[158:161], v[174:177], v[26:29]
	v_mfma_f32_16x16x32_bf16 v[18:21], v[150:153], v[166:169], v[18:21]
	v_mfma_f32_16x16x32_bf16 v[10:13], v[158:161], v[166:169], v[10:13]
	v_mfma_f32_16x16x32_bf16 v[66:69], v[154:157], v[194:197], v[66:69]
	v_mfma_f32_16x16x32_bf16 v[58:61], v[162:165], v[194:197], v[58:61]
	v_mfma_f32_16x16x32_bf16 v[50:53], v[154:157], v[186:189], v[50:53]
	v_mfma_f32_16x16x32_bf16 v[42:45], v[162:165], v[186:189], v[42:45]
	v_mfma_f32_16x16x32_bf16 v[34:37], v[154:157], v[178:181], v[34:37]
	v_mfma_f32_16x16x32_bf16 v[26:29], v[162:165], v[178:181], v[26:29]
	v_mfma_f32_16x16x32_bf16 v[18:21], v[154:157], v[170:173], v[18:21]
	v_mfma_f32_16x16x32_bf16 v[10:13], v[162:165], v[170:173], v[10:13]
	v_mfma_f32_16x16x32_bf16 v[62:65], v[134:137], v[190:193], v[62:65]
	v_mfma_f32_16x16x32_bf16 v[54:57], v[142:145], v[190:193], v[54:57]
	v_mfma_f32_16x16x32_bf16 v[46:49], v[134:137], v[182:185], v[46:49]
	v_mfma_f32_16x16x32_bf16 v[38:41], v[142:145], v[182:185], v[38:41]
	v_mfma_f32_16x16x32_bf16 v[30:33], v[134:137], v[174:177], v[30:33]
	v_mfma_f32_16x16x32_bf16 v[22:25], v[142:145], v[174:177], v[22:25]
	v_mfma_f32_16x16x32_bf16 v[14:17], v[134:137], v[166:169], v[14:17]
	v_mfma_f32_16x16x32_bf16 v[6:9], v[142:145], v[166:169], v[6:9]
	v_mfma_f32_16x16x32_bf16 v[62:65], v[138:141], v[194:197], v[62:65]
	v_mfma_f32_16x16x32_bf16 v[54:57], v[146:149], v[194:197], v[54:57]
	v_mfma_f32_16x16x32_bf16 v[46:49], v[138:141], v[186:189], v[46:49]
	v_mfma_f32_16x16x32_bf16 v[38:41], v[146:149], v[186:189], v[38:41]
	v_mfma_f32_16x16x32_bf16 v[30:33], v[138:141], v[178:181], v[30:33]
	v_mfma_f32_16x16x32_bf16 v[22:25], v[146:149], v[178:181], v[22:25]
	v_mfma_f32_16x16x32_bf16 v[14:17], v[138:141], v[170:173], v[14:17]
	v_mfma_f32_16x16x32_bf16 v[6:9], v[146:149], v[170:173], v[6:9]
	s_setprio 0
	s_barrier
	s_add_i32 s61, s61, 2
	s_cmp_gt_u32 s61, 13
	s_cbranch_scc1 .Lkr1_exit

.LBB0_332:
	s_add_u32 s48, s28, 0xfffc0080
	s_addc_u32 s49, s29, -1
	s_and_b64 s[46:47], s[30:31], exec
	s_cselect_b32 s49, s23, s49
	s_cselect_b32 s48, s56, s48
	s_cselect_b32 s47, s57, s60
	s_cselect_b32 s46, s58, s59
	s_add_i32 m0, s40, 0xc000
	s_nop 0
	global_load_lds_dwordx4 v206, s[28:29]
	s_add_i32 m0, s40, 0xe000
	s_nop 0
	global_load_lds_dwordx4 v208, s[28:29]
	s_waitcnt vmcnt(8)
	s_waitcnt lgkmcnt(0)
	s_barrier
	s_setprio 1
	s_waitcnt lgkmcnt(0)
	v_mfma_f32_16x16x32_bf16 v[130:133], v[134:137], v[166:169], v[130:133]
	v_mfma_f32_16x16x32_bf16 v[122:125], v[142:145], v[166:169], v[122:125]
	v_mfma_f32_16x16x32_bf16 v[114:117], v[134:137], v[174:177], v[114:117]
	v_mfma_f32_16x16x32_bf16 v[106:109], v[142:145], v[174:177], v[106:109]
	v_mfma_f32_16x16x32_bf16 v[98:101], v[134:137], v[182:185], v[98:101]
	v_mfma_f32_16x16x32_bf16 v[90:93], v[142:145], v[182:185], v[90:93]
	v_mfma_f32_16x16x32_bf16 v[82:85], v[134:137], v[190:193], v[82:85]
	v_mfma_f32_16x16x32_bf16 v[74:77], v[142:145], v[190:193], v[74:77]
	v_mfma_f32_16x16x32_bf16 v[130:133], v[138:141], v[170:173], v[130:133]
	v_mfma_f32_16x16x32_bf16 v[122:125], v[146:149], v[170:173], v[122:125]
	v_mfma_f32_16x16x32_bf16 v[114:117], v[138:141], v[178:181], v[114:117]
	v_mfma_f32_16x16x32_bf16 v[106:109], v[146:149], v[178:181], v[106:109]
	v_mfma_f32_16x16x32_bf16 v[98:101], v[138:141], v[186:189], v[98:101]
	v_mfma_f32_16x16x32_bf16 v[90:93], v[146:149], v[186:189], v[90:93]
	v_mfma_f32_16x16x32_bf16 v[82:85], v[138:141], v[194:197], v[82:85]
	v_mfma_f32_16x16x32_bf16 v[74:77], v[146:149], v[194:197], v[74:77]
	v_mfma_f32_16x16x32_bf16 v[126:129], v[150:153], v[166:169], v[126:129]
	v_mfma_f32_16x16x32_bf16 v[118:121], v[158:161], v[166:169], v[118:121]
	v_mfma_f32_16x16x32_bf16 v[110:113], v[150:153], v[174:177], v[110:113]
	v_mfma_f32_16x16x32_bf16 v[102:105], v[158:161], v[174:177], v[102:105]
	v_mfma_f32_16x16x32_bf16 v[94:97], v[150:153], v[182:185], v[94:97]
	v_mfma_f32_16x16x32_bf16 v[86:89], v[158:161], v[182:185], v[86:89]
	v_mfma_f32_16x16x32_bf16 v[78:81], v[150:153], v[190:193], v[78:81]
	v_mfma_f32_16x16x32_bf16 v[70:73], v[158:161], v[190:193], v[70:73]
	v_mfma_f32_16x16x32_bf16 v[126:129], v[154:157], v[170:173], v[126:129]
	v_mfma_f32_16x16x32_bf16 v[118:121], v[162:165], v[170:173], v[118:121]
	v_mfma_f32_16x16x32_bf16 v[110:113], v[154:157], v[178:181], v[110:113]
	v_mfma_f32_16x16x32_bf16 v[102:105], v[162:165], v[178:181], v[102:105]
	v_mfma_f32_16x16x32_bf16 v[94:97], v[154:157], v[186:189], v[94:97]
	v_mfma_f32_16x16x32_bf16 v[86:89], v[162:165], v[186:189], v[86:89]
	v_mfma_f32_16x16x32_bf16 v[78:81], v[154:157], v[194:197], v[78:81]
	v_mfma_f32_16x16x32_bf16 v[70:73], v[162:165], v[194:197], v[70:73]
	s_setprio 0
	s_barrier
	ds_read_b128 v[166:169], v229 offset:16384
	ds_read_b128 v[170:173], v229 offset:17408
	ds_read_b128 v[174:177], v229 offset:18432
	ds_read_b128 v[178:181], v229 offset:19456
	ds_read_b128 v[182:185], v229 offset:20480
	ds_read_b128 v[186:189], v229 offset:21504
	ds_read_b128 v[190:193], v229 offset:22528
	ds_read_b128 v[194:197], v229 offset:23552
	s_add_i32 s62, s53, s12
	s_add_u32 s98, s46, s10
	s_addc_u32 s99, s47, s11
	s_mov_b32 m0, s62
	s_nop 0
	global_load_lds_dwordx4 v202, s[46:47]
	s_add_i32 m0, s62, 0x2000
	s_add_u32 s62, s46, 0x40000
	s_addc_u32 s63, s47, 0
	s_add_i32 s64, s54, s12
	global_load_lds_dwordx4 v198, s[46:47]
	s_mov_b32 m0, s64
	s_add_u32 s100, s48, s10
	s_addc_u32 s101, s49, s11
	global_load_lds_dwordx4 v202, s[62:63]
	s_add_i32 m0, s64, 0x2000
	s_nop 0
	global_load_lds_dwordx4 v198, s[62:63]
	s_mov_b32 m0, s40
	s_nop 0
	global_load_lds_dwordx4 v204, s[48:49]
	s_mov_b32 m0, s41
	s_nop 0
	global_load_lds_dwordx4 v200, s[48:49]
	s_waitcnt vmcnt(8)
	s_waitcnt lgkmcnt(0)
	s_barrier
	s_setprio 1
	s_waitcnt lgkmcnt(0)
	v_mfma_f32_16x16x32_bf16 v[66:69], v[134:137], v[166:169], v[66:69]
	v_mfma_f32_16x16x32_bf16 v[58:61], v[142:145], v[166:169], v[58:61]
	v_mfma_f32_16x16x32_bf16 v[50:53], v[134:137], v[174:177], v[50:53]
	v_mfma_f32_16x16x32_bf16 v[42:45], v[142:145], v[174:177], v[42:45]
	v_mfma_f32_16x16x32_bf16 v[34:37], v[134:137], v[182:185], v[34:37]
	v_mfma_f32_16x16x32_bf16 v[26:29], v[142:145], v[182:185], v[26:29]
	v_mfma_f32_16x16x32_bf16 v[18:21], v[134:137], v[190:193], v[18:21]
	v_mfma_f32_16x16x32_bf16 v[10:13], v[142:145], v[190:193], v[10:13]
	v_mfma_f32_16x16x32_bf16 v[66:69], v[138:141], v[170:173], v[66:69]
	v_mfma_f32_16x16x32_bf16 v[58:61], v[146:149], v[170:173], v[58:61]
	v_mfma_f32_16x16x32_bf16 v[50:53], v[138:141], v[178:181], v[50:53]
	v_mfma_f32_16x16x32_bf16 v[42:45], v[146:149], v[178:181], v[42:45]
	v_mfma_f32_16x16x32_bf16 v[34:37], v[138:141], v[186:189], v[34:37]
	v_mfma_f32_16x16x32_bf16 v[26:29], v[146:149], v[186:189], v[26:29]
	v_mfma_f32_16x16x32_bf16 v[18:21], v[138:141], v[194:197], v[18:21]
	v_mfma_f32_16x16x32_bf16 v[10:13], v[146:149], v[194:197], v[10:13]
	v_mfma_f32_16x16x32_bf16 v[62:65], v[150:153], v[166:169], v[62:65]
	v_mfma_f32_16x16x32_bf16 v[54:57], v[158:161], v[166:169], v[54:57]
	v_mfma_f32_16x16x32_bf16 v[46:49], v[150:153], v[174:177], v[46:49]
	v_mfma_f32_16x16x32_bf16 v[38:41], v[158:161], v[174:177], v[38:41]
	v_mfma_f32_16x16x32_bf16 v[30:33], v[150:153], v[182:185], v[30:33]
	v_mfma_f32_16x16x32_bf16 v[22:25], v[158:161], v[182:185], v[22:25]
	v_mfma_f32_16x16x32_bf16 v[14:17], v[150:153], v[190:193], v[14:17]
	v_mfma_f32_16x16x32_bf16 v[6:9], v[158:161], v[190:193], v[6:9]
	v_mfma_f32_16x16x32_bf16 v[62:65], v[154:157], v[170:173], v[62:65]
	v_mfma_f32_16x16x32_bf16 v[54:57], v[162:165], v[170:173], v[54:57]
	v_mfma_f32_16x16x32_bf16 v[46:49], v[154:157], v[178:181], v[46:49]
	v_mfma_f32_16x16x32_bf16 v[38:41], v[162:165], v[178:181], v[38:41]
	v_mfma_f32_16x16x32_bf16 v[30:33], v[154:157], v[186:189], v[30:33]
	v_mfma_f32_16x16x32_bf16 v[22:25], v[162:165], v[186:189], v[22:25]
	v_mfma_f32_16x16x32_bf16 v[14:17], v[154:157], v[194:197], v[14:17]
	v_mfma_f32_16x16x32_bf16 v[6:9], v[162:165], v[194:197], v[6:9]
	s_setprio 0
	s_barrier
	ds_read_b128 v[166:169], v229 offset:32768
	ds_read_b128 v[170:173], v229 offset:33792
	ds_read_b128 v[174:177], v229 offset:34816
	ds_read_b128 v[178:181], v229 offset:35840
	ds_read_b128 v[182:185], v229 offset:36864
	ds_read_b128 v[186:189], v229 offset:37888
	ds_read_b128 v[190:193], v229 offset:38912
	ds_read_b128 v[194:197], v229 offset:39936
	v_add_u32_e32 v134, 0x18000, v225
	v_add_u32_e32 v146, 0x1c000, v225
	ds_read_b128 v[150:153], v134
	ds_read_b128 v[154:157], v134 offset:1024
	ds_read_b128 v[158:161], v134 offset:2048
	ds_read_b128 v[162:165], v134 offset:3072
	ds_read_b128 v[134:137], v146
	ds_read_b128 v[138:141], v146 offset:1024
	ds_read_b128 v[142:145], v146 offset:2048
	ds_read_b128 v[146:149], v146 offset:3072
	s_add_i32 s62, 0, 0x18000
	s_add_i32 s63, 0, 0x1c000
	s_add_u32 s48, s48, 0x40000
	s_addc_u32 s49, s49, 0
	s_mov_b32 m0, s42
	s_nop 0
	global_load_lds_dwordx4 v204, s[48:49]
	s_mov_b32 m0, s43
	s_nop 0
	global_load_lds_dwordx4 v200, s[48:49]
	s_waitcnt vmcnt(8)
	s_waitcnt lgkmcnt(0)
	s_barrier
	s_setprio 1
	s_waitcnt lgkmcnt(0)
	v_mfma_f32_16x16x32_bf16 v[130:133], v[150:153], v[166:169], v[130:133]
	v_mfma_f32_16x16x32_bf16 v[122:125], v[158:161], v[166:169], v[122:125]
	v_mfma_f32_16x16x32_bf16 v[114:117], v[150:153], v[174:177], v[114:117]
	v_mfma_f32_16x16x32_bf16 v[106:109], v[158:161], v[174:177], v[106:109]
	v_mfma_f32_16x16x32_bf16 v[98:101], v[150:153], v[182:185], v[98:101]
	v_mfma_f32_16x16x32_bf16 v[90:93], v[158:161], v[182:185], v[90:93]
	v_mfma_f32_16x16x32_bf16 v[82:85], v[150:153], v[190:193], v[82:85]
	v_mfma_f32_16x16x32_bf16 v[74:77], v[158:161], v[190:193], v[74:77]
	v_mfma_f32_16x16x32_bf16 v[130:133], v[154:157], v[170:173], v[130:133]
	v_mfma_f32_16x16x32_bf16 v[122:125], v[162:165], v[170:173], v[122:125]
	v_mfma_f32_16x16x32_bf16 v[114:117], v[154:157], v[178:181], v[114:117]
	v_mfma_f32_16x16x32_bf16 v[106:109], v[162:165], v[178:181], v[106:109]
	v_mfma_f32_16x16x32_bf16 v[98:101], v[154:157], v[186:189], v[98:101]
	v_mfma_f32_16x16x32_bf16 v[90:93], v[162:165], v[186:189], v[90:93]
	v_mfma_f32_16x16x32_bf16 v[82:85], v[154:157], v[194:197], v[82:85]
	v_mfma_f32_16x16x32_bf16 v[74:77], v[162:165], v[194:197], v[74:77]
	v_mfma_f32_16x16x32_bf16 v[126:129], v[134:137], v[166:169], v[126:129]
	v_mfma_f32_16x16x32_bf16 v[118:121], v[142:145], v[166:169], v[118:121]
	v_mfma_f32_16x16x32_bf16 v[110:113], v[134:137], v[174:177], v[110:113]
	v_mfma_f32_16x16x32_bf16 v[102:105], v[142:145], v[174:177], v[102:105]
	v_mfma_f32_16x16x32_bf16 v[94:97], v[134:137], v[182:185], v[94:97]
	v_mfma_f32_16x16x32_bf16 v[86:89], v[142:145], v[182:185], v[86:89]
	v_mfma_f32_16x16x32_bf16 v[78:81], v[134:137], v[190:193], v[78:81]
	v_mfma_f32_16x16x32_bf16 v[70:73], v[142:145], v[190:193], v[70:73]
	v_mfma_f32_16x16x32_bf16 v[126:129], v[138:141], v[170:173], v[126:129]
	v_mfma_f32_16x16x32_bf16 v[118:121], v[146:149], v[170:173], v[118:121]
	v_mfma_f32_16x16x32_bf16 v[110:113], v[138:141], v[178:181], v[110:113]
	v_mfma_f32_16x16x32_bf16 v[102:105], v[146:149], v[178:181], v[102:105]
	v_mfma_f32_16x16x32_bf16 v[94:97], v[138:141], v[186:189], v[94:97]
	v_mfma_f32_16x16x32_bf16 v[86:89], v[146:149], v[186:189], v[86:89]
	v_mfma_f32_16x16x32_bf16 v[78:81], v[138:141], v[194:197], v[78:81]
	v_mfma_f32_16x16x32_bf16 v[70:73], v[146:149], v[194:197], v[70:73]
	s_setprio 0
	s_barrier
	ds_read_b128 v[190:193], v229 offset:49152
	ds_read_b128 v[194:197], v229 offset:50176
	ds_read_b128 v[182:185], v229 offset:51200
	ds_read_b128 v[186:189], v229 offset:52224
	ds_read_b128 v[174:177], v229 offset:53248
	ds_read_b128 v[178:181], v229 offset:54272
	ds_read_b128 v[166:169], v229 offset:55296
	ds_read_b128 v[170:173], v229 offset:56320
	s_add_i32 s48, s62, s12
	s_mov_b32 m0, s48
	s_nop 0
	global_load_lds_dwordx4 v202, s[98:99]
	s_add_i32 m0, s48, 0x2000
	s_add_u32 s46, s46, 0x40080
	s_addc_u32 s47, s47, 0
	s_add_i32 s48, s63, s12
	global_load_lds_dwordx4 v198, s[98:99]
	s_mov_b32 m0, s48
	s_andn2_b64 vcc, exec, s[30:31]
	global_load_lds_dwordx4 v202, s[46:47]
	s_add_i32 m0, s48, 0x2000
	s_nop 0
	global_load_lds_dwordx4 v198, s[46:47]
	s_mov_b32 m0, s51
	s_nop 0
	global_load_lds_dwordx4 v204, s[100:101]
	s_mov_b32 m0, s52
	s_nop 0
	global_load_lds_dwordx4 v200, s[100:101]
	s_waitcnt vmcnt(8)
	s_cbranch_vccnz .LBB0_329
	s_and_saveexec_b64 s[30:31], s[4:5]
	s_cbranch_execz .LBB0_328
	v_mov_b32_e32 v232, v3
	v_mov_b32_e32 v233, v4
	v_mov_b32_e32 v234, v2
	v_mov_b32_e32 v235, v5
	v_pk_add_f32 v[232:233], v[232:233], v[234:235]
	s_nop 0
	v_add_f32_e32 v226, v232, v233
	v_fmamk_f32 v226, v226, 0x3a800000, v230
	ds_write_b32 v228, v226
	s_branch .LBB0_328

.LBB0_370:
	ds_read_b128 v[2:5], v148
	ds_read_b128 v[6:9], v148 offset:1024
	ds_read_b128 v[10:13], v148 offset:2048
	ds_read_b128 v[14:17], v148 offset:3072
	ds_read_b128 v[18:21], v149
	ds_read_b128 v[22:25], v149 offset:1024
	ds_read_b128 v[26:29], v149 offset:2048
	ds_read_b128 v[30:33], v149 offset:3072
	s_ashr_i32 s47, s46, 31
	s_lshl_b64 s[52:53], s[46:47], 17
	s_add_u32 s52, s0, s52
	s_addc_u32 s53, s1, s53
	s_and_b64 s[6:7], s[6:7], exec
	s_cselect_b32 s7, s53, s61
	s_cselect_b32 s6, s52, s60
	s_add_u32 s66, s58, 0x10080
	s_addc_u32 s67, s59, 0
	s_add_i32 s65, s13, 0xc000
	v_lshl_add_u64 v[66:67], s[66:67], 0, v[130:131]
	s_mov_b32 m0, s65
	s_add_i32 s2, s13, 0xe000
	ds_read_b128 v[34:37], v150
	ds_read_b128 v[38:41], v150 offset:1024
	ds_read_b128 v[42:45], v150 offset:2048
	ds_read_b128 v[46:49], v150 offset:3072
	ds_read_b128 v[50:53], v150 offset:4096
	ds_read_b128 v[54:57], v150 offset:5120
	ds_read_b128 v[58:61], v150 offset:6144
	ds_read_b128 v[62:65], v150 offset:7168
	global_load_lds_dwordx4 v[66:67], off
	v_lshl_add_u64 v[66:67], s[66:67], 0, v[134:135]
	s_mov_b32 m0, s2
	s_nop 0
	global_load_lds_dwordx4 v[66:67], off
	s_waitcnt vmcnt(8)
	s_waitcnt lgkmcnt(0)
	s_barrier
	s_setprio 1
	s_waitcnt lgkmcnt(0)
	v_mfma_f32_16x16x32_bf16 v[66:69], v[2:5], v[34:37], 0
	v_mfma_f32_16x16x32_bf16 v[70:73], v[10:13], v[34:37], 0
	v_mfma_f32_16x16x32_bf16 v[74:77], v[2:5], v[42:45], 0
	v_mfma_f32_16x16x32_bf16 v[78:81], v[10:13], v[42:45], 0
	v_mfma_f32_16x16x32_bf16 v[82:85], v[2:5], v[50:53], 0
	v_mfma_f32_16x16x32_bf16 v[86:89], v[10:13], v[50:53], 0
	v_mfma_f32_16x16x32_bf16 v[90:93], v[2:5], v[58:61], 0
	v_mfma_f32_16x16x32_bf16 v[94:97], v[10:13], v[58:61], 0
	v_mfma_f32_16x16x32_bf16 v[66:69], v[6:9], v[38:41], v[66:69]
	v_mfma_f32_16x16x32_bf16 v[70:73], v[14:17], v[38:41], v[70:73]
	v_mfma_f32_16x16x32_bf16 v[74:77], v[6:9], v[46:49], v[74:77]
	v_mfma_f32_16x16x32_bf16 v[78:81], v[14:17], v[46:49], v[78:81]
	v_mfma_f32_16x16x32_bf16 v[82:85], v[6:9], v[54:57], v[82:85]
	v_mfma_f32_16x16x32_bf16 v[86:89], v[14:17], v[54:57], v[86:89]
	v_mfma_f32_16x16x32_bf16 v[90:93], v[6:9], v[62:65], v[90:93]
	v_mfma_f32_16x16x32_bf16 v[94:97], v[14:17], v[62:65], v[94:97]
	v_mfma_f32_16x16x32_bf16 v[98:101], v[18:21], v[34:37], 0
	v_mfma_f32_16x16x32_bf16 v[34:37], v[26:29], v[34:37], 0
	v_mfma_f32_16x16x32_bf16 v[98:101], v[22:25], v[38:41], v[98:101]
	v_mfma_f32_16x16x32_bf16 v[34:37], v[30:33], v[38:41], v[34:37]
	v_mfma_f32_16x16x32_bf16 v[38:41], v[18:21], v[42:45], 0
	v_mfma_f32_16x16x32_bf16 v[42:45], v[26:29], v[42:45], 0
	v_mfma_f32_16x16x32_bf16 v[38:41], v[22:25], v[46:49], v[38:41]
	v_mfma_f32_16x16x32_bf16 v[42:45], v[30:33], v[46:49], v[42:45]
	v_mfma_f32_16x16x32_bf16 v[46:49], v[18:21], v[50:53], 0
	v_mfma_f32_16x16x32_bf16 v[50:53], v[26:29], v[50:53], 0
	v_mfma_f32_16x16x32_bf16 v[46:49], v[22:25], v[54:57], v[46:49]
	v_mfma_f32_16x16x32_bf16 v[50:53], v[30:33], v[54:57], v[50:53]
	v_mfma_f32_16x16x32_bf16 v[54:57], v[18:21], v[58:61], 0
	v_mfma_f32_16x16x32_bf16 v[58:61], v[26:29], v[58:61], 0
	v_mfma_f32_16x16x32_bf16 v[54:57], v[22:25], v[62:65], v[54:57]
	v_mfma_f32_16x16x32_bf16 v[58:61], v[30:33], v[62:65], v[58:61]
	s_setprio 0
	s_barrier
	s_add_i32 s57, s62, s12
	v_lshl_add_u64 v[212:213], s[60:61], 0, v[132:133]
	s_add_i32 s47, s57, 0x2000
	v_lshl_add_u64 v[142:143], v[212:213], 0, s[28:29]
	s_mov_b32 m0, s57
	v_lshl_add_u64 v[214:215], s[60:61], 0, v[136:137]
	s_add_u32 s66, s60, 0x10100
	ds_read_b128 v[62:65], v150 offset:16384
	ds_read_b128 v[102:105], v150 offset:17408
	ds_read_b128 v[106:109], v150 offset:18432
	ds_read_b128 v[110:113], v150 offset:19456
	ds_read_b128 v[114:117], v150 offset:20480
	ds_read_b128 v[118:121], v150 offset:21504
	ds_read_b128 v[122:125], v150 offset:22528
	ds_read_b128 v[126:129], v150 offset:23552
	global_load_lds_dwordx4 v[142:143], off
	v_lshl_add_u64 v[142:143], v[214:215], 0, s[28:29]
	s_mov_b32 m0, s47
	s_addc_u32 s67, s61, 0
	s_add_i32 s49, s63, s12
	global_load_lds_dwordx4 v[142:143], off
	v_lshl_add_u64 v[142:143], s[66:67], 0, v[132:133]
	s_mov_b32 m0, s49
	s_add_i32 s55, s49, 0x2000
	global_load_lds_dwordx4 v[142:143], off
	v_lshl_add_u64 v[142:143], s[66:67], 0, v[136:137]
	s_mov_b32 m0, s55
	v_lshl_add_u64 v[218:219], s[58:59], 0, v[130:131]
	global_load_lds_dwordx4 v[142:143], off
	v_lshl_add_u64 v[142:143], v[218:219], 0, s[28:29]
	s_mov_b32 m0, s13
	v_lshl_add_u64 v[220:221], s[58:59], 0, v[134:135]
	global_load_lds_dwordx4 v[142:143], off
	v_lshl_add_u64 v[142:143], v[220:221], 0, s[28:29]
	s_mov_b32 m0, s14
	s_nop 0
	global_load_lds_dwordx4 v[142:143], off
	s_waitcnt vmcnt(8)
	s_waitcnt lgkmcnt(0)
	s_barrier
	s_setprio 1
	s_waitcnt lgkmcnt(0)
	v_mfma_f32_16x16x32_bf16 v[142:145], v[2:5], v[62:65], 0
	v_mfma_f32_16x16x32_bf16 v[156:159], v[2:5], v[106:109], 0
	v_mfma_f32_16x16x32_bf16 v[164:167], v[2:5], v[114:117], 0
	v_mfma_f32_16x16x32_bf16 v[2:5], v[2:5], v[122:125], 0
	v_mfma_f32_16x16x32_bf16 v[142:145], v[6:9], v[102:105], v[142:145]
	v_mfma_f32_16x16x32_bf16 v[156:159], v[6:9], v[110:113], v[156:159]
	v_mfma_f32_16x16x32_bf16 v[164:167], v[6:9], v[118:121], v[164:167]
	v_mfma_f32_16x16x32_bf16 v[2:5], v[6:9], v[126:129], v[2:5]
	v_mfma_f32_16x16x32_bf16 v[6:9], v[10:13], v[122:125], 0
	v_mfma_f32_16x16x32_bf16 v[152:155], v[10:13], v[62:65], 0
	v_mfma_f32_16x16x32_bf16 v[160:163], v[10:13], v[106:109], 0
	v_mfma_f32_16x16x32_bf16 v[168:171], v[10:13], v[114:117], 0
	v_mfma_f32_16x16x32_bf16 v[6:9], v[14:17], v[126:129], v[6:9]
	v_mfma_f32_16x16x32_bf16 v[152:155], v[14:17], v[102:105], v[152:155]
	v_mfma_f32_16x16x32_bf16 v[160:163], v[14:17], v[110:113], v[160:163]
	v_mfma_f32_16x16x32_bf16 v[168:171], v[14:17], v[118:121], v[168:171]
	v_mfma_f32_16x16x32_bf16 v[10:13], v[18:21], v[62:65], 0
	v_mfma_f32_16x16x32_bf16 v[14:17], v[26:29], v[62:65], 0
	v_mfma_f32_16x16x32_bf16 v[10:13], v[22:25], v[102:105], v[10:13]
	v_mfma_f32_16x16x32_bf16 v[14:17], v[30:33], v[102:105], v[14:17]
	v_mfma_f32_16x16x32_bf16 v[62:65], v[18:21], v[106:109], 0
	v_mfma_f32_16x16x32_bf16 v[102:105], v[26:29], v[106:109], 0
	v_mfma_f32_16x16x32_bf16 v[106:109], v[18:21], v[114:117], 0
	v_mfma_f32_16x16x32_bf16 v[18:21], v[18:21], v[122:125], 0
	v_mfma_f32_16x16x32_bf16 v[62:65], v[22:25], v[110:113], v[62:65]
	v_mfma_f32_16x16x32_bf16 v[102:105], v[30:33], v[110:113], v[102:105]
	v_mfma_f32_16x16x32_bf16 v[106:109], v[22:25], v[118:121], v[106:109]
	v_mfma_f32_16x16x32_bf16 v[110:113], v[26:29], v[114:117], 0
	v_mfma_f32_16x16x32_bf16 v[18:21], v[22:25], v[126:129], v[18:21]
	v_mfma_f32_16x16x32_bf16 v[22:25], v[26:29], v[122:125], 0
	v_mfma_f32_16x16x32_bf16 v[110:113], v[30:33], v[118:121], v[110:113]
	v_mfma_f32_16x16x32_bf16 v[22:25], v[30:33], v[126:129], v[22:25]
	s_setprio 0
	s_barrier
	s_add_i32 s64, 0, 0x18000
	s_add_i32 s70, 0, 0x1c000
	v_add_u32_e32 v151, s64, v147
	v_add_u32_e32 v217, s70, v147
	ds_read_b128 v[26:29], v151
	ds_read_b128 v[30:33], v151 offset:1024
	ds_read_b128 v[114:117], v151 offset:2048
	ds_read_b128 v[118:121], v151 offset:3072
	ds_read_b128 v[122:125], v217
	ds_read_b128 v[126:129], v217 offset:1024
	ds_read_b128 v[172:175], v217 offset:2048
	ds_read_b128 v[176:179], v217 offset:3072
	s_add_u32 s66, s58, 0x10100
	s_addc_u32 s67, s59, 0
	s_mov_b32 m0, s15
	v_lshl_add_u64 v[222:223], s[66:67], 0, v[130:131]
	ds_read_b128 v[180:183], v150 offset:32768
	ds_read_b128 v[184:187], v150 offset:33792
	ds_read_b128 v[188:191], v150 offset:34816
	ds_read_b128 v[192:195], v150 offset:35840
	ds_read_b128 v[196:199], v150 offset:36864
	ds_read_b128 v[200:203], v150 offset:37888
	ds_read_b128 v[204:207], v150 offset:38912
	ds_read_b128 v[208:211], v150 offset:39936
	global_load_lds_dwordx4 v[222:223], off
	v_lshl_add_u64 v[222:223], s[66:67], 0, v[134:135]
	s_mov_b32 m0, s33
	s_nop 0
	global_load_lds_dwordx4 v[222:223], off
	s_waitcnt vmcnt(8)
	s_waitcnt lgkmcnt(0)
	s_barrier
	s_setprio 1
	s_waitcnt lgkmcnt(0)
	v_mfma_f32_16x16x32_bf16 v[66:69], v[26:29], v[180:183], v[66:69]
	v_mfma_f32_16x16x32_bf16 v[70:73], v[114:117], v[180:183], v[70:73]
	v_mfma_f32_16x16x32_bf16 v[74:77], v[26:29], v[188:191], v[74:77]
	v_mfma_f32_16x16x32_bf16 v[78:81], v[114:117], v[188:191], v[78:81]
	v_mfma_f32_16x16x32_bf16 v[82:85], v[26:29], v[196:199], v[82:85]
	v_mfma_f32_16x16x32_bf16 v[86:89], v[114:117], v[196:199], v[86:89]
	v_mfma_f32_16x16x32_bf16 v[90:93], v[26:29], v[204:207], v[90:93]
	v_mfma_f32_16x16x32_bf16 v[94:97], v[114:117], v[204:207], v[94:97]
	v_mfma_f32_16x16x32_bf16 v[66:69], v[30:33], v[184:187], v[66:69]
	v_mfma_f32_16x16x32_bf16 v[70:73], v[118:121], v[184:187], v[70:73]
	v_mfma_f32_16x16x32_bf16 v[74:77], v[30:33], v[192:195], v[74:77]
	v_mfma_f32_16x16x32_bf16 v[78:81], v[118:121], v[192:195], v[78:81]
	v_mfma_f32_16x16x32_bf16 v[82:85], v[30:33], v[200:203], v[82:85]
	v_mfma_f32_16x16x32_bf16 v[86:89], v[118:121], v[200:203], v[86:89]
	v_mfma_f32_16x16x32_bf16 v[90:93], v[30:33], v[208:211], v[90:93]
	v_mfma_f32_16x16x32_bf16 v[94:97], v[118:121], v[208:211], v[94:97]
	v_mfma_f32_16x16x32_bf16 v[98:101], v[122:125], v[180:183], v[98:101]
	v_mfma_f32_16x16x32_bf16 v[34:37], v[172:175], v[180:183], v[34:37]
	v_mfma_f32_16x16x32_bf16 v[38:41], v[122:125], v[188:191], v[38:41]
	v_mfma_f32_16x16x32_bf16 v[42:45], v[172:175], v[188:191], v[42:45]
	v_mfma_f32_16x16x32_bf16 v[46:49], v[122:125], v[196:199], v[46:49]
	v_mfma_f32_16x16x32_bf16 v[50:53], v[172:175], v[196:199], v[50:53]
	v_mfma_f32_16x16x32_bf16 v[54:57], v[122:125], v[204:207], v[54:57]
	v_mfma_f32_16x16x32_bf16 v[58:61], v[172:175], v[204:207], v[58:61]
	v_mfma_f32_16x16x32_bf16 v[98:101], v[126:129], v[184:187], v[98:101]
	v_mfma_f32_16x16x32_bf16 v[34:37], v[176:179], v[184:187], v[34:37]
	v_mfma_f32_16x16x32_bf16 v[38:41], v[126:129], v[192:195], v[38:41]
	v_mfma_f32_16x16x32_bf16 v[42:45], v[176:179], v[192:195], v[42:45]
	v_mfma_f32_16x16x32_bf16 v[46:49], v[126:129], v[200:203], v[46:49]
	v_mfma_f32_16x16x32_bf16 v[50:53], v[176:179], v[200:203], v[50:53]
	v_mfma_f32_16x16x32_bf16 v[54:57], v[126:129], v[208:211], v[54:57]
	v_mfma_f32_16x16x32_bf16 v[58:61], v[176:179], v[208:211], v[58:61]
	s_setprio 0
	s_barrier
	s_add_i32 s66, s64, s12
	s_add_i32 s64, s66, 0x2000
	v_lshl_add_u64 v[212:213], v[212:213], 0, s[30:31]
	s_mov_b32 m0, s66
	s_add_u32 s68, s60, 0x10180
	ds_read_b128 v[180:183], v150 offset:49152
	ds_read_b128 v[184:187], v150 offset:50176
	ds_read_b128 v[188:191], v150 offset:51200
	ds_read_b128 v[192:195], v150 offset:52224
	ds_read_b128 v[196:199], v150 offset:53248
	ds_read_b128 v[200:203], v150 offset:54272
	ds_read_b128 v[204:207], v150 offset:55296
	ds_read_b128 v[208:211], v150 offset:56320
	global_load_lds_dwordx4 v[212:213], off
	v_lshl_add_u64 v[212:213], v[214:215], 0, s[30:31]
	s_mov_b32 m0, s64
	s_addc_u32 s69, s61, 0
	s_add_i32 s60, s70, s12
	global_load_lds_dwordx4 v[212:213], off
	v_lshl_add_u64 v[212:213], s[68:69], 0, v[132:133]
	s_mov_b32 m0, s60
	s_add_i32 s61, s60, 0x2000
	global_load_lds_dwordx4 v[212:213], off
	v_lshl_add_u64 v[212:213], s[68:69], 0, v[136:137]
	s_mov_b32 m0, s61
	s_nop 0
	global_load_lds_dwordx4 v[212:213], off
	v_lshl_add_u64 v[212:213], v[218:219], 0, s[30:31]
	s_mov_b32 m0, s42
	s_nop 0
	global_load_lds_dwordx4 v[212:213], off
	v_lshl_add_u64 v[212:213], v[220:221], 0, s[30:31]
	s_mov_b32 m0, s43
	s_nop 0
	global_load_lds_dwordx4 v[212:213], off
	s_waitcnt vmcnt(8)
	s_waitcnt lgkmcnt(0)
	s_barrier
	s_setprio 1
	s_waitcnt lgkmcnt(0)
	v_mfma_f32_16x16x32_bf16 v[2:5], v[26:29], v[204:207], v[2:5]
	v_mfma_f32_16x16x32_bf16 v[6:9], v[114:117], v[204:207], v[6:9]
	v_mfma_f32_16x16x32_bf16 v[142:145], v[26:29], v[180:183], v[142:145]
	v_mfma_f32_16x16x32_bf16 v[152:155], v[114:117], v[180:183], v[152:155]
	v_mfma_f32_16x16x32_bf16 v[156:159], v[26:29], v[188:191], v[156:159]
	v_mfma_f32_16x16x32_bf16 v[160:163], v[114:117], v[188:191], v[160:163]
	v_mfma_f32_16x16x32_bf16 v[164:167], v[26:29], v[196:199], v[164:167]
	v_mfma_f32_16x16x32_bf16 v[168:171], v[114:117], v[196:199], v[168:171]
	v_mfma_f32_16x16x32_bf16 v[2:5], v[30:33], v[208:211], v[2:5]
	v_mfma_f32_16x16x32_bf16 v[6:9], v[118:121], v[208:211], v[6:9]
	v_mfma_f32_16x16x32_bf16 v[142:145], v[30:33], v[184:187], v[142:145]
	v_mfma_f32_16x16x32_bf16 v[152:155], v[118:121], v[184:187], v[152:155]
	v_mfma_f32_16x16x32_bf16 v[156:159], v[30:33], v[192:195], v[156:159]
	v_mfma_f32_16x16x32_bf16 v[160:163], v[118:121], v[192:195], v[160:163]
	v_mfma_f32_16x16x32_bf16 v[164:167], v[30:33], v[200:203], v[164:167]
	v_mfma_f32_16x16x32_bf16 v[168:171], v[118:121], v[200:203], v[168:171]
	v_mfma_f32_16x16x32_bf16 v[10:13], v[122:125], v[180:183], v[10:13]
	v_mfma_f32_16x16x32_bf16 v[14:17], v[172:175], v[180:183], v[14:17]
	v_mfma_f32_16x16x32_bf16 v[26:29], v[122:125], v[188:191], v[62:65]
	v_mfma_f32_16x16x32_bf16 v[30:33], v[172:175], v[188:191], v[102:105]
	v_mfma_f32_16x16x32_bf16 v[62:65], v[122:125], v[196:199], v[106:109]
	v_mfma_f32_16x16x32_bf16 v[102:105], v[172:175], v[196:199], v[110:113]
	v_mfma_f32_16x16x32_bf16 v[18:21], v[122:125], v[204:207], v[18:21]
	v_mfma_f32_16x16x32_bf16 v[22:25], v[172:175], v[204:207], v[22:25]
	v_mfma_f32_16x16x32_bf16 v[10:13], v[126:129], v[184:187], v[10:13]
	v_mfma_f32_16x16x32_bf16 v[14:17], v[176:179], v[184:187], v[14:17]
	v_mfma_f32_16x16x32_bf16 v[26:29], v[126:129], v[192:195], v[26:29]
	v_mfma_f32_16x16x32_bf16 v[30:33], v[176:179], v[192:195], v[30:33]
	v_mfma_f32_16x16x32_bf16 v[62:65], v[126:129], v[200:203], v[62:65]
	v_mfma_f32_16x16x32_bf16 v[102:105], v[176:179], v[200:203], v[102:105]
	v_mfma_f32_16x16x32_bf16 v[18:21], v[126:129], v[208:211], v[18:21]
	v_mfma_f32_16x16x32_bf16 v[22:25], v[176:179], v[208:211], v[22:25]
	s_setprio 0
	s_barrier
	ds_read_b128 v[106:109], v148
	ds_read_b128 v[110:113], v148 offset:1024
	ds_read_b128 v[114:117], v148 offset:2048
	ds_read_b128 v[118:121], v148 offset:3072
	ds_read_b128 v[122:125], v149
	ds_read_b128 v[126:129], v149 offset:1024
	ds_read_b128 v[172:175], v149 offset:2048
	ds_read_b128 v[176:179], v149 offset:3072
	s_add_u32 s58, s58, 0x10180
	s_addc_u32 s59, s59, 0
	s_mov_b32 m0, s65
	v_lshl_add_u64 v[212:213], s[58:59], 0, v[130:131]
	ds_read_b128 v[180:183], v150
	ds_read_b128 v[184:187], v150 offset:1024
	ds_read_b128 v[188:191], v150 offset:2048
	ds_read_b128 v[192:195], v150 offset:3072
	ds_read_b128 v[196:199], v150 offset:4096
	ds_read_b128 v[200:203], v150 offset:5120
	ds_read_b128 v[204:207], v150 offset:6144
	ds_read_b128 v[208:211], v150 offset:7168
	global_load_lds_dwordx4 v[212:213], off
	v_lshl_add_u64 v[212:213], s[58:59], 0, v[134:135]
	s_mov_b32 m0, s2
	s_nop 0
	global_load_lds_dwordx4 v[212:213], off
	s_waitcnt vmcnt(8)
	s_waitcnt lgkmcnt(0)
	s_barrier
	s_setprio 1
	s_waitcnt lgkmcnt(0)
	v_mfma_f32_16x16x32_bf16 v[90:93], v[106:109], v[204:207], v[90:93]
	v_mfma_f32_16x16x32_bf16 v[66:69], v[106:109], v[180:183], v[66:69]
	v_mfma_f32_16x16x32_bf16 v[70:73], v[114:117], v[180:183], v[70:73]
	v_mfma_f32_16x16x32_bf16 v[74:77], v[106:109], v[188:191], v[74:77]
	v_mfma_f32_16x16x32_bf16 v[78:81], v[114:117], v[188:191], v[78:81]
	v_mfma_f32_16x16x32_bf16 v[82:85], v[106:109], v[196:199], v[82:85]
	v_mfma_f32_16x16x32_bf16 v[86:89], v[114:117], v[196:199], v[86:89]
	v_mfma_f32_16x16x32_bf16 v[212:215], v[110:113], v[208:211], v[90:93]
	v_mfma_f32_16x16x32_bf16 v[90:93], v[114:117], v[204:207], v[94:97]
	v_mfma_f32_16x16x32_bf16 v[66:69], v[110:113], v[184:187], v[66:69]
	v_mfma_f32_16x16x32_bf16 v[70:73], v[118:121], v[184:187], v[70:73]
	v_mfma_f32_16x16x32_bf16 v[74:77], v[110:113], v[192:195], v[74:77]
	v_mfma_f32_16x16x32_bf16 v[78:81], v[118:121], v[192:195], v[78:81]
	v_mfma_f32_16x16x32_bf16 v[82:85], v[110:113], v[200:203], v[82:85]
	v_mfma_f32_16x16x32_bf16 v[86:89], v[118:121], v[200:203], v[86:89]
	v_mfma_f32_16x16x32_bf16 v[94:97], v[118:121], v[208:211], v[90:93]
	v_mfma_f32_16x16x32_bf16 v[34:37], v[172:175], v[180:183], v[34:37]
	v_mfma_f32_16x16x32_bf16 v[38:41], v[122:125], v[188:191], v[38:41]
	v_mfma_f32_16x16x32_bf16 v[42:45], v[172:175], v[188:191], v[42:45]
	v_mfma_f32_16x16x32_bf16 v[46:49], v[122:125], v[196:199], v[46:49]
	v_mfma_f32_16x16x32_bf16 v[50:53], v[172:175], v[196:199], v[50:53]
	v_mfma_f32_16x16x32_bf16 v[54:57], v[122:125], v[204:207], v[54:57]
	v_mfma_f32_16x16x32_bf16 v[58:61], v[172:175], v[204:207], v[58:61]
	v_mfma_f32_16x16x32_bf16 v[90:93], v[122:125], v[180:183], v[98:101]
	v_mfma_f32_16x16x32_bf16 v[34:37], v[176:179], v[184:187], v[34:37]
	v_mfma_f32_16x16x32_bf16 v[38:41], v[126:129], v[192:195], v[38:41]
	v_mfma_f32_16x16x32_bf16 v[42:45], v[176:179], v[192:195], v[42:45]
	v_mfma_f32_16x16x32_bf16 v[46:49], v[126:129], v[200:203], v[46:49]
	v_mfma_f32_16x16x32_bf16 v[50:53], v[176:179], v[200:203], v[50:53]
	v_mfma_f32_16x16x32_bf16 v[54:57], v[126:129], v[208:211], v[54:57]
	v_mfma_f32_16x16x32_bf16 v[58:61], v[176:179], v[208:211], v[58:61]
	v_mfma_f32_16x16x32_bf16 v[218:221], v[126:129], v[184:187], v[90:93]
	s_setprio 0
	s_barrier
	s_mov_b32 m0, s57
	v_lshl_add_u64 v[248:249], s[6:7], 0, v[132:133]
	s_add_u32 s58, s6, 0x10000
	ds_read_b128 v[90:93], v150 offset:16384
	ds_read_b128 v[98:101], v150 offset:17408
	ds_read_b128 v[180:183], v150 offset:18432
	ds_read_b128 v[184:187], v150 offset:19456
	ds_read_b128 v[188:191], v150 offset:20480
	ds_read_b128 v[192:195], v150 offset:21504
	ds_read_b128 v[196:199], v150 offset:22528
	ds_read_b128 v[200:203], v150 offset:23552
	global_load_lds_dwordx4 v[248:249], off
	v_lshl_add_u64 v[250:251], s[6:7], 0, v[136:137]
	s_mov_b32 m0, s47
	s_addc_u32 s59, s7, 0
	global_load_lds_dwordx4 v[250:251], off
	v_lshl_add_u64 v[204:205], s[58:59], 0, v[132:133]
	s_mov_b32 m0, s49
	v_lshl_add_u64 v[252:253], s[50:51], 0, v[130:131]
	global_load_lds_dwordx4 v[204:205], off
	v_lshl_add_u64 v[204:205], s[58:59], 0, v[136:137]
	s_mov_b32 m0, s55
	v_lshl_add_u64 v[226:227], s[50:51], 0, v[134:135]
	global_load_lds_dwordx4 v[204:205], off
	s_mov_b32 m0, s13
	s_nop 0
	global_load_lds_dwordx4 v[252:253], off
	s_mov_b32 m0, s14
	s_nop 0
	global_load_lds_dwordx4 v[226:227], off
	s_waitcnt vmcnt(8)
	s_waitcnt lgkmcnt(0)
	s_barrier
	s_setprio 1
	s_waitcnt lgkmcnt(0)
	v_mfma_f32_16x16x32_bf16 v[2:5], v[106:109], v[196:199], v[2:5]
	v_mfma_f32_16x16x32_bf16 v[6:9], v[114:117], v[196:199], v[6:9]
	v_mfma_f32_16x16x32_bf16 v[142:145], v[106:109], v[90:93], v[142:145]
	v_mfma_f32_16x16x32_bf16 v[152:155], v[114:117], v[90:93], v[152:155]
	v_mfma_f32_16x16x32_bf16 v[156:159], v[106:109], v[180:183], v[156:159]
	v_mfma_f32_16x16x32_bf16 v[160:163], v[114:117], v[180:183], v[160:163]
	v_mfma_f32_16x16x32_bf16 v[164:167], v[106:109], v[188:191], v[164:167]
	v_mfma_f32_16x16x32_bf16 v[168:171], v[114:117], v[188:191], v[168:171]
	v_mfma_f32_16x16x32_bf16 v[2:5], v[110:113], v[200:203], v[2:5]
	v_mfma_f32_16x16x32_bf16 v[6:9], v[118:121], v[200:203], v[6:9]
	v_mfma_f32_16x16x32_bf16 v[142:145], v[110:113], v[98:101], v[142:145]
	v_mfma_f32_16x16x32_bf16 v[152:155], v[118:121], v[98:101], v[152:155]
	v_mfma_f32_16x16x32_bf16 v[156:159], v[110:113], v[184:187], v[156:159]
	v_mfma_f32_16x16x32_bf16 v[160:163], v[118:121], v[184:187], v[160:163]
	v_mfma_f32_16x16x32_bf16 v[164:167], v[110:113], v[192:195], v[164:167]
	v_mfma_f32_16x16x32_bf16 v[168:171], v[118:121], v[192:195], v[168:171]
	v_mfma_f32_16x16x32_bf16 v[10:13], v[122:125], v[90:93], v[10:13]
	v_mfma_f32_16x16x32_bf16 v[204:207], v[126:129], v[98:101], v[10:13]
	v_mfma_f32_16x16x32_bf16 v[10:13], v[172:175], v[90:93], v[14:17]
	v_mfma_f32_16x16x32_bf16 v[14:17], v[176:179], v[98:101], v[10:13]
	v_mfma_f32_16x16x32_bf16 v[10:13], v[122:125], v[180:183], v[26:29]
	v_mfma_f32_16x16x32_bf16 v[208:211], v[126:129], v[184:187], v[10:13]
	v_mfma_f32_16x16x32_bf16 v[10:13], v[172:175], v[180:183], v[30:33]
	v_mfma_f32_16x16x32_bf16 v[30:33], v[176:179], v[184:187], v[10:13]
	v_mfma_f32_16x16x32_bf16 v[10:13], v[122:125], v[188:191], v[62:65]
	v_mfma_f32_16x16x32_bf16 v[180:183], v[126:129], v[192:195], v[10:13]
	v_mfma_f32_16x16x32_bf16 v[10:13], v[172:175], v[188:191], v[102:105]
	v_mfma_f32_16x16x32_bf16 v[184:187], v[176:179], v[192:195], v[10:13]
	v_mfma_f32_16x16x32_bf16 v[10:13], v[122:125], v[196:199], v[18:21]
	v_mfma_f32_16x16x32_bf16 v[188:191], v[126:129], v[200:203], v[10:13]
	v_mfma_f32_16x16x32_bf16 v[10:13], v[172:175], v[196:199], v[22:25]
	v_mfma_f32_16x16x32_bf16 v[172:175], v[176:179], v[200:203], v[10:13]
	s_setprio 0
	s_barrier
	s_nop 4
	ds_read_b128 v[10:13], v151
	ds_read_b128 v[22:25], v151 offset:1024
	ds_read_b128 v[62:65], v151 offset:2048
	ds_read_b128 v[176:179], v151 offset:3072
	ds_read_b128 v[192:195], v217
	ds_read_b128 v[196:199], v217 offset:1024
	ds_read_b128 v[200:203], v217 offset:2048
	ds_read_b128 v[222:225], v217 offset:3072
	s_add_u32 s58, s50, 0x10000
	s_addc_u32 s59, s51, 0
	s_mov_b32 m0, s15
	v_lshl_add_u64 v[90:91], s[58:59], 0, v[130:131]
	ds_read_b128 v[18:21], v150 offset:32768
	ds_read_b128 v[26:29], v150 offset:33792
	ds_read_b128 v[102:105], v150 offset:34816
	ds_read_b128 v[228:231], v150 offset:35840
	ds_read_b128 v[232:235], v150 offset:36864
	ds_read_b128 v[236:239], v150 offset:37888
	ds_read_b128 v[240:243], v150 offset:38912
	ds_read_b128 v[244:247], v150 offset:39936
	global_load_lds_dwordx4 v[90:91], off
	v_lshl_add_u64 v[90:91], s[58:59], 0, v[134:135]
	s_mov_b32 m0, s33
	s_nop 0
	global_load_lds_dwordx4 v[90:91], off
	s_waitcnt vmcnt(8)
	s_waitcnt lgkmcnt(0)
	s_barrier
	s_setprio 1
	s_waitcnt lgkmcnt(0)
	v_mfma_f32_16x16x32_bf16 v[66:69], v[10:13], v[18:21], v[66:69]
	v_mfma_f32_16x16x32_bf16 v[122:125], v[22:25], v[26:29], v[66:69]
	v_mfma_f32_16x16x32_bf16 v[66:69], v[62:65], v[18:21], v[70:73]
	v_mfma_f32_16x16x32_bf16 v[114:117], v[176:179], v[26:29], v[66:69]
	v_mfma_f32_16x16x32_bf16 v[66:69], v[10:13], v[102:105], v[74:77]
	v_mfma_f32_16x16x32_bf16 v[106:109], v[22:25], v[228:231], v[66:69]
	v_mfma_f32_16x16x32_bf16 v[66:69], v[62:65], v[102:105], v[78:81]
	v_mfma_f32_16x16x32_bf16 v[98:101], v[176:179], v[228:231], v[66:69]
	v_mfma_f32_16x16x32_bf16 v[66:69], v[10:13], v[232:235], v[82:85]
	v_mfma_f32_16x16x32_bf16 v[90:93], v[22:25], v[236:239], v[66:69]
	v_mfma_f32_16x16x32_bf16 v[66:69], v[62:65], v[232:235], v[86:89]
	v_mfma_f32_16x16x32_bf16 v[82:85], v[176:179], v[236:239], v[66:69]
	v_mfma_f32_16x16x32_bf16 v[66:69], v[10:13], v[240:243], v[212:215]
	v_mfma_f32_16x16x32_bf16 v[74:77], v[22:25], v[244:247], v[66:69]
	v_mfma_f32_16x16x32_bf16 v[66:69], v[62:65], v[240:243], v[94:97]
	v_mfma_f32_16x16x32_bf16 v[66:69], v[176:179], v[244:247], v[66:69]
	v_mfma_f32_16x16x32_bf16 v[70:73], v[192:195], v[18:21], v[218:221]
	v_mfma_f32_16x16x32_bf16 v[18:21], v[200:203], v[18:21], v[34:37]
	v_mfma_f32_16x16x32_bf16 v[118:121], v[222:225], v[26:29], v[18:21]
	v_mfma_f32_16x16x32_bf16 v[18:21], v[192:195], v[102:105], v[38:41]
	v_mfma_f32_16x16x32_bf16 v[110:113], v[196:199], v[228:231], v[18:21]
	v_mfma_f32_16x16x32_bf16 v[18:21], v[200:203], v[102:105], v[42:45]
	v_mfma_f32_16x16x32_bf16 v[102:105], v[222:225], v[228:231], v[18:21]
	v_mfma_f32_16x16x32_bf16 v[18:21], v[192:195], v[232:235], v[46:49]
	v_mfma_f32_16x16x32_bf16 v[94:97], v[196:199], v[236:239], v[18:21]
	v_mfma_f32_16x16x32_bf16 v[18:21], v[200:203], v[232:235], v[50:53]
	v_mfma_f32_16x16x32_bf16 v[86:89], v[222:225], v[236:239], v[18:21]
	v_mfma_f32_16x16x32_bf16 v[18:21], v[192:195], v[240:243], v[54:57]
	v_mfma_f32_16x16x32_bf16 v[78:81], v[196:199], v[244:247], v[18:21]
	v_mfma_f32_16x16x32_bf16 v[18:21], v[200:203], v[240:243], v[58:61]
	v_mfma_f32_16x16x32_bf16 v[126:129], v[196:199], v[26:29], v[70:73]
	v_mfma_f32_16x16x32_bf16 v[70:73], v[222:225], v[244:247], v[18:21]
	s_setprio 0
	s_barrier
	s_mov_b32 m0, s66
	s_nop 2
	v_lshl_add_u64 v[18:19], v[248:249], 0, s[22:23]
	s_add_u32 s6, s6, 0x10080
	ds_read_b128 v[38:41], v150 offset:49152
	ds_read_b128 v[46:49], v150 offset:50176
	ds_read_b128 v[212:215], v150 offset:51200
	ds_read_b128 v[218:221], v150 offset:52224
	ds_read_b128 v[228:231], v150 offset:53248
	ds_read_b128 v[232:235], v150 offset:54272
	ds_read_b128 v[236:239], v150 offset:55296
	ds_read_b128 v[240:243], v150 offset:56320
	global_load_lds_dwordx4 v[18:19], off
	v_lshl_add_u64 v[18:19], v[250:251], 0, s[22:23]
	s_mov_b32 m0, s64
	s_addc_u32 s7, s7, 0
	global_load_lds_dwordx4 v[18:19], off
	v_lshl_add_u64 v[18:19], s[6:7], 0, v[132:133]
	s_mov_b32 m0, s60
	s_nop 0
	global_load_lds_dwordx4 v[18:19], off
	v_lshl_add_u64 v[18:19], s[6:7], 0, v[136:137]
	s_mov_b32 m0, s61
	s_nop 0
	global_load_lds_dwordx4 v[18:19], off
	v_lshl_add_u64 v[18:19], v[252:253], 0, s[22:23]
	s_mov_b32 m0, s42
	s_nop 0
	global_load_lds_dwordx4 v[18:19], off
	v_lshl_add_u64 v[18:19], v[226:227], 0, s[22:23]
	s_mov_b32 m0, s43
	s_nop 0
	global_load_lds_dwordx4 v[18:19], off
	s_waitcnt vmcnt(8)
	s_waitcnt lgkmcnt(0)
	s_barrier
	s_setprio 1
	s_waitcnt lgkmcnt(0)
	v_mfma_f32_16x16x32_bf16 v[18:21], v[10:13], v[38:41], v[142:145]
	v_mfma_f32_16x16x32_bf16 v[58:61], v[22:25], v[46:49], v[18:21]
	v_mfma_f32_16x16x32_bf16 v[18:21], v[62:65], v[38:41], v[152:155]
	v_mfma_f32_16x16x32_bf16 v[50:53], v[176:179], v[46:49], v[18:21]
	v_mfma_f32_16x16x32_bf16 v[18:21], v[10:13], v[212:215], v[156:159]
	v_mfma_f32_16x16x32_bf16 v[42:45], v[22:25], v[218:221], v[18:21]
	v_mfma_f32_16x16x32_bf16 v[18:21], v[62:65], v[212:215], v[160:163]
	v_mfma_f32_16x16x32_bf16 v[34:37], v[176:179], v[218:221], v[18:21]
	v_mfma_f32_16x16x32_bf16 v[18:21], v[10:13], v[228:231], v[164:167]
	v_mfma_f32_16x16x32_bf16 v[2:5], v[10:13], v[236:239], v[2:5]
	v_mfma_f32_16x16x32_bf16 v[26:29], v[22:25], v[232:235], v[18:21]
	v_mfma_f32_16x16x32_bf16 v[18:21], v[62:65], v[228:231], v[168:171]
	v_mfma_f32_16x16x32_bf16 v[10:13], v[22:25], v[240:243], v[2:5]
	v_mfma_f32_16x16x32_bf16 v[2:5], v[62:65], v[236:239], v[6:9]
	v_mfma_f32_16x16x32_bf16 v[18:21], v[176:179], v[232:235], v[18:21]
	v_mfma_f32_16x16x32_bf16 v[2:5], v[176:179], v[240:243], v[2:5]
	v_mfma_f32_16x16x32_bf16 v[6:9], v[192:195], v[38:41], v[204:207]
	v_mfma_f32_16x16x32_bf16 v[62:65], v[196:199], v[46:49], v[6:9]
	v_mfma_f32_16x16x32_bf16 v[6:9], v[200:203], v[38:41], v[14:17]
	v_mfma_f32_16x16x32_bf16 v[54:57], v[222:225], v[46:49], v[6:9]
	v_mfma_f32_16x16x32_bf16 v[6:9], v[192:195], v[212:215], v[208:211]
	v_mfma_f32_16x16x32_bf16 v[46:49], v[196:199], v[218:221], v[6:9]
	v_mfma_f32_16x16x32_bf16 v[6:9], v[200:203], v[212:215], v[30:33]
	v_mfma_f32_16x16x32_bf16 v[38:41], v[222:225], v[218:221], v[6:9]
	v_mfma_f32_16x16x32_bf16 v[6:9], v[192:195], v[228:231], v[180:183]
	v_mfma_f32_16x16x32_bf16 v[30:33], v[196:199], v[232:235], v[6:9]
	v_mfma_f32_16x16x32_bf16 v[6:9], v[200:203], v[228:231], v[184:187]
	v_mfma_f32_16x16x32_bf16 v[22:25], v[222:225], v[232:235], v[6:9]
	v_mfma_f32_16x16x32_bf16 v[6:9], v[192:195], v[236:239], v[188:191]
	v_mfma_f32_16x16x32_bf16 v[14:17], v[196:199], v[240:243], v[6:9]
	v_mfma_f32_16x16x32_bf16 v[6:9], v[200:203], v[236:239], v[172:175]
	v_mfma_f32_16x16x32_bf16 v[6:9], v[222:225], v[240:243], v[6:9]
	s_setprio 0
	s_barrier
	s_andn2_b64 vcc, exec, s[24:25]
	s_cbranch_vccnz .LBB0_372
	s_barrier

.LBB0_619:
	v_add_u32_e32 v153, s44, v151
	ds_read_b128 v[154:157], v153
	ds_read_b128 v[158:161], v153 offset:1024
	ds_read_b128 v[162:165], v153 offset:2048
	ds_read_b128 v[166:169], v153 offset:3072
	v_add_u32_e32 v153, s45, v151
	s_add_u32 s26, s18, s24
	ds_read_b128 v[170:173], v153
	ds_read_b128 v[174:177], v153 offset:1024
	ds_read_b128 v[178:181], v153 offset:2048
	ds_read_b128 v[182:185], v153 offset:3072
	s_addc_u32 s27, s19, s25
	s_add_u32 s26, s26, 0x100
	s_addc_u32 s27, s27, 0
	s_add_u32 s51, s48, s24
	s_addc_u32 s52, s49, s25
	s_cmpk_eq_i32 s24, 0x1500
	s_cselect_b32 s29, s23, s27
	s_cselect_b32 s28, s22, s26
	s_cselect_b32 s27, s9, s52
	s_cselect_b32 s26, s8, s51
	v_lshl_add_u64 v[218:219], v[146:147], 0, s[24:25]
	s_add_i32 m0, s33, 0xc000
	ds_read_b128 v[186:189], v152
	ds_read_b128 v[190:193], v152 offset:1024
	ds_read_b128 v[194:197], v152 offset:2048
	ds_read_b128 v[198:201], v152 offset:3072
	ds_read_b128 v[202:205], v152 offset:4096
	ds_read_b128 v[206:209], v152 offset:5120
	ds_read_b128 v[210:213], v152 offset:6144
	ds_read_b128 v[214:217], v152 offset:7168
	global_load_lds_dwordx4 v[218:219], off
	v_lshl_add_u64 v[218:219], v[148:149], 0, s[24:25]
	s_add_i32 m0, s33, 0xe000
	s_nop 0
	global_load_lds_dwordx4 v[218:219], off
	s_waitcnt vmcnt(8)
	s_waitcnt lgkmcnt(0)
	s_barrier
	s_setprio 1
	s_waitcnt lgkmcnt(0)
	v_mfma_f32_16x16x32_bf16 v[126:129], v[154:157], v[186:189], v[126:129]
	v_mfma_f32_16x16x32_bf16 v[122:125], v[162:165], v[186:189], v[122:125]
	v_mfma_f32_16x16x32_bf16 v[110:113], v[154:157], v[194:197], v[110:113]
	v_mfma_f32_16x16x32_bf16 v[106:109], v[162:165], v[194:197], v[106:109]
	v_mfma_f32_16x16x32_bf16 v[94:97], v[154:157], v[202:205], v[94:97]
	v_mfma_f32_16x16x32_bf16 v[90:93], v[162:165], v[202:205], v[90:93]
	v_mfma_f32_16x16x32_bf16 v[78:81], v[154:157], v[210:213], v[78:81]
	v_mfma_f32_16x16x32_bf16 v[74:77], v[162:165], v[210:213], v[74:77]
	v_mfma_f32_16x16x32_bf16 v[126:129], v[158:161], v[190:193], v[126:129]
	v_mfma_f32_16x16x32_bf16 v[122:125], v[166:169], v[190:193], v[122:125]
	v_mfma_f32_16x16x32_bf16 v[110:113], v[158:161], v[198:201], v[110:113]
	v_mfma_f32_16x16x32_bf16 v[106:109], v[166:169], v[198:201], v[106:109]
	v_mfma_f32_16x16x32_bf16 v[94:97], v[158:161], v[206:209], v[94:97]
	v_mfma_f32_16x16x32_bf16 v[90:93], v[166:169], v[206:209], v[90:93]
	v_mfma_f32_16x16x32_bf16 v[78:81], v[158:161], v[214:217], v[78:81]
	v_mfma_f32_16x16x32_bf16 v[74:77], v[166:169], v[214:217], v[74:77]
	v_mfma_f32_16x16x32_bf16 v[118:121], v[170:173], v[186:189], v[118:121]
	v_mfma_f32_16x16x32_bf16 v[114:117], v[178:181], v[186:189], v[114:117]
	v_mfma_f32_16x16x32_bf16 v[102:105], v[170:173], v[194:197], v[102:105]
	v_mfma_f32_16x16x32_bf16 v[98:101], v[178:181], v[194:197], v[98:101]
	v_mfma_f32_16x16x32_bf16 v[86:89], v[170:173], v[202:205], v[86:89]
	v_mfma_f32_16x16x32_bf16 v[82:85], v[178:181], v[202:205], v[82:85]
	v_mfma_f32_16x16x32_bf16 v[70:73], v[170:173], v[210:213], v[70:73]
	v_mfma_f32_16x16x32_bf16 v[66:69], v[178:181], v[210:213], v[66:69]
	v_mfma_f32_16x16x32_bf16 v[118:121], v[174:177], v[190:193], v[118:121]
	v_mfma_f32_16x16x32_bf16 v[114:117], v[182:185], v[190:193], v[114:117]
	v_mfma_f32_16x16x32_bf16 v[102:105], v[174:177], v[198:201], v[102:105]
	v_mfma_f32_16x16x32_bf16 v[98:101], v[182:185], v[198:201], v[98:101]
	v_mfma_f32_16x16x32_bf16 v[86:89], v[174:177], v[206:209], v[86:89]
	v_mfma_f32_16x16x32_bf16 v[82:85], v[182:185], v[206:209], v[82:85]
	v_mfma_f32_16x16x32_bf16 v[70:73], v[174:177], v[214:217], v[70:73]
	v_mfma_f32_16x16x32_bf16 v[66:69], v[182:185], v[214:217], v[66:69]
	s_setprio 0
	s_barrier
	s_add_i32 s51, s44, s13
	s_add_u32 s98, s26, s20
	s_addc_u32 s99, s27, s21
	s_mov_b32 m0, s51
	ds_read_b128 v[186:189], v152 offset:16384
	ds_read_b128 v[190:193], v152 offset:17408
	ds_read_b128 v[194:197], v152 offset:18432
	ds_read_b128 v[198:201], v152 offset:19456
	ds_read_b128 v[202:205], v152 offset:20480
	ds_read_b128 v[206:209], v152 offset:21504
	ds_read_b128 v[210:213], v152 offset:22528
	ds_read_b128 v[214:217], v152 offset:23552
	global_load_lds_dwordx4 v132, s[26:27]
	s_add_i32 m0, s51, 0x2000
	s_add_u32 s52, s26, 0xb0000
	s_addc_u32 s53, s27, 0
	s_add_i32 s51, s45, s13
	global_load_lds_dwordx4 v136, s[26:27]
	s_mov_b32 m0, s51
	s_nop 0
	global_load_lds_dwordx4 v132, s[52:53]
	s_add_i32 m0, s51, 0x2000
	s_nop 0
	global_load_lds_dwordx4 v136, s[52:53]
	s_add_u32 s100, s28, s20
	s_addc_u32 s101, s29, s21
	s_mov_b32 m0, s33
	s_nop 0
	global_load_lds_dwordx4 v130, s[28:29]
	s_mov_b32 m0, s14
	s_nop 0
	global_load_lds_dwordx4 v134, s[28:29]
	s_waitcnt vmcnt(8)
	s_waitcnt lgkmcnt(0)
	s_barrier
	s_setprio 1
	s_waitcnt lgkmcnt(0)
	v_mfma_f32_16x16x32_bf16 v[62:65], v[154:157], v[186:189], v[62:65]
	v_mfma_f32_16x16x32_bf16 v[58:61], v[162:165], v[186:189], v[58:61]
	v_mfma_f32_16x16x32_bf16 v[46:49], v[154:157], v[194:197], v[46:49]
	v_mfma_f32_16x16x32_bf16 v[42:45], v[162:165], v[194:197], v[42:45]
	v_mfma_f32_16x16x32_bf16 v[30:33], v[154:157], v[202:205], v[30:33]
	v_mfma_f32_16x16x32_bf16 v[26:29], v[162:165], v[202:205], v[26:29]
	v_mfma_f32_16x16x32_bf16 v[14:17], v[154:157], v[210:213], v[14:17]
	v_mfma_f32_16x16x32_bf16 v[10:13], v[162:165], v[210:213], v[10:13]
	v_mfma_f32_16x16x32_bf16 v[62:65], v[158:161], v[190:193], v[62:65]
	v_mfma_f32_16x16x32_bf16 v[58:61], v[166:169], v[190:193], v[58:61]
	v_mfma_f32_16x16x32_bf16 v[46:49], v[158:161], v[198:201], v[46:49]
	v_mfma_f32_16x16x32_bf16 v[42:45], v[166:169], v[198:201], v[42:45]
	v_mfma_f32_16x16x32_bf16 v[30:33], v[158:161], v[206:209], v[30:33]
	v_mfma_f32_16x16x32_bf16 v[26:29], v[166:169], v[206:209], v[26:29]
	v_mfma_f32_16x16x32_bf16 v[14:17], v[158:161], v[214:217], v[14:17]
	v_mfma_f32_16x16x32_bf16 v[10:13], v[166:169], v[214:217], v[10:13]
	v_mfma_f32_16x16x32_bf16 v[54:57], v[170:173], v[186:189], v[54:57]
	v_mfma_f32_16x16x32_bf16 v[50:53], v[178:181], v[186:189], v[50:53]
	v_mfma_f32_16x16x32_bf16 v[38:41], v[170:173], v[194:197], v[38:41]
	v_mfma_f32_16x16x32_bf16 v[34:37], v[178:181], v[194:197], v[34:37]
	v_mfma_f32_16x16x32_bf16 v[22:25], v[170:173], v[202:205], v[22:25]
	v_mfma_f32_16x16x32_bf16 v[18:21], v[178:181], v[202:205], v[18:21]
	v_mfma_f32_16x16x32_bf16 v[6:9], v[170:173], v[210:213], v[6:9]
	v_mfma_f32_16x16x32_bf16 v[2:5], v[178:181], v[210:213], v[2:5]
	v_mfma_f32_16x16x32_bf16 v[54:57], v[174:177], v[190:193], v[54:57]
	v_mfma_f32_16x16x32_bf16 v[50:53], v[182:185], v[190:193], v[50:53]
	v_mfma_f32_16x16x32_bf16 v[38:41], v[174:177], v[198:201], v[38:41]
	v_mfma_f32_16x16x32_bf16 v[34:37], v[182:185], v[198:201], v[34:37]
	v_mfma_f32_16x16x32_bf16 v[22:25], v[174:177], v[206:209], v[22:25]
	v_mfma_f32_16x16x32_bf16 v[18:21], v[182:185], v[206:209], v[18:21]
	v_mfma_f32_16x16x32_bf16 v[6:9], v[174:177], v[214:217], v[6:9]
	v_mfma_f32_16x16x32_bf16 v[2:5], v[182:185], v[214:217], v[2:5]
	s_setprio 0
	s_barrier
	s_add_i32 s51, 0, 0x18000
	v_add_u32_e32 v153, s51, v151
	s_add_i32 s52, 0, 0x1c000
	ds_read_b128 v[154:157], v153
	ds_read_b128 v[158:161], v153 offset:1024
	ds_read_b128 v[162:165], v153 offset:2048
	ds_read_b128 v[166:169], v153 offset:3072
	v_add_u32_e32 v153, s52, v151
	ds_read_b128 v[170:173], v153
	ds_read_b128 v[174:177], v153 offset:1024
	ds_read_b128 v[178:181], v153 offset:2048
	ds_read_b128 v[182:185], v153 offset:3072
	s_add_u32 s28, s28, 0xb0000
	s_addc_u32 s29, s29, 0
	s_mov_b32 m0, s15
	ds_read_b128 v[186:189], v152 offset:32768
	ds_read_b128 v[190:193], v152 offset:33792
	ds_read_b128 v[194:197], v152 offset:34816
	ds_read_b128 v[198:201], v152 offset:35840
	ds_read_b128 v[202:205], v152 offset:36864
	ds_read_b128 v[206:209], v152 offset:37888
	ds_read_b128 v[210:213], v152 offset:38912
	ds_read_b128 v[214:217], v152 offset:39936
	global_load_lds_dwordx4 v130, s[28:29]
	s_mov_b32 m0, s40
	s_nop 0
	global_load_lds_dwordx4 v134, s[28:29]
	s_waitcnt vmcnt(8)
	s_waitcnt lgkmcnt(0)
	s_barrier
	s_setprio 1
	s_waitcnt lgkmcnt(0)
	v_mfma_f32_16x16x32_bf16 v[126:129], v[154:157], v[186:189], v[126:129]
	v_mfma_f32_16x16x32_bf16 v[122:125], v[162:165], v[186:189], v[122:125]
	v_mfma_f32_16x16x32_bf16 v[110:113], v[154:157], v[194:197], v[110:113]
	v_mfma_f32_16x16x32_bf16 v[106:109], v[162:165], v[194:197], v[106:109]
	v_mfma_f32_16x16x32_bf16 v[94:97], v[154:157], v[202:205], v[94:97]
	v_mfma_f32_16x16x32_bf16 v[90:93], v[162:165], v[202:205], v[90:93]
	v_mfma_f32_16x16x32_bf16 v[78:81], v[154:157], v[210:213], v[78:81]
	v_mfma_f32_16x16x32_bf16 v[74:77], v[162:165], v[210:213], v[74:77]
	v_mfma_f32_16x16x32_bf16 v[126:129], v[158:161], v[190:193], v[126:129]
	v_mfma_f32_16x16x32_bf16 v[122:125], v[166:169], v[190:193], v[122:125]
	v_mfma_f32_16x16x32_bf16 v[110:113], v[158:161], v[198:201], v[110:113]
	v_mfma_f32_16x16x32_bf16 v[106:109], v[166:169], v[198:201], v[106:109]
	v_mfma_f32_16x16x32_bf16 v[94:97], v[158:161], v[206:209], v[94:97]
	v_mfma_f32_16x16x32_bf16 v[90:93], v[166:169], v[206:209], v[90:93]
	v_mfma_f32_16x16x32_bf16 v[78:81], v[158:161], v[214:217], v[78:81]
	v_mfma_f32_16x16x32_bf16 v[74:77], v[166:169], v[214:217], v[74:77]
	v_mfma_f32_16x16x32_bf16 v[118:121], v[170:173], v[186:189], v[118:121]
	v_mfma_f32_16x16x32_bf16 v[114:117], v[178:181], v[186:189], v[114:117]
	v_mfma_f32_16x16x32_bf16 v[102:105], v[170:173], v[194:197], v[102:105]
	v_mfma_f32_16x16x32_bf16 v[98:101], v[178:181], v[194:197], v[98:101]
	v_mfma_f32_16x16x32_bf16 v[86:89], v[170:173], v[202:205], v[86:89]
	v_mfma_f32_16x16x32_bf16 v[82:85], v[178:181], v[202:205], v[82:85]
	v_mfma_f32_16x16x32_bf16 v[70:73], v[170:173], v[210:213], v[70:73]
	v_mfma_f32_16x16x32_bf16 v[66:69], v[178:181], v[210:213], v[66:69]
	v_mfma_f32_16x16x32_bf16 v[118:121], v[174:177], v[190:193], v[118:121]
	v_mfma_f32_16x16x32_bf16 v[114:117], v[182:185], v[190:193], v[114:117]
	v_mfma_f32_16x16x32_bf16 v[102:105], v[174:177], v[198:201], v[102:105]
	v_mfma_f32_16x16x32_bf16 v[98:101], v[182:185], v[198:201], v[98:101]
	v_mfma_f32_16x16x32_bf16 v[86:89], v[174:177], v[206:209], v[86:89]
	v_mfma_f32_16x16x32_bf16 v[82:85], v[182:185], v[206:209], v[82:85]
	v_mfma_f32_16x16x32_bf16 v[70:73], v[174:177], v[214:217], v[70:73]
	v_mfma_f32_16x16x32_bf16 v[66:69], v[182:185], v[214:217], v[66:69]
	s_setprio 0
	s_barrier
	s_add_i32 s28, s51, s13
	s_mov_b32 m0, s28
	ds_read_b128 v[186:189], v152 offset:49152
	ds_read_b128 v[190:193], v152 offset:50176
	ds_read_b128 v[194:197], v152 offset:51200
	ds_read_b128 v[198:201], v152 offset:52224
	ds_read_b128 v[202:205], v152 offset:53248
	ds_read_b128 v[206:209], v152 offset:54272
	ds_read_b128 v[210:213], v152 offset:55296
	ds_read_b128 v[214:217], v152 offset:56320
	global_load_lds_dwordx4 v132, s[98:99]
	s_add_i32 m0, s28, 0x2000
	s_add_u32 s26, s26, 0xb0080
	s_addc_u32 s27, s27, 0
	s_add_i32 s28, s52, s13
	global_load_lds_dwordx4 v136, s[98:99]
	s_mov_b32 m0, s28
	s_nop 0
	global_load_lds_dwordx4 v132, s[26:27]
	s_add_i32 m0, s28, 0x2000
	s_nop 0
	global_load_lds_dwordx4 v136, s[26:27]
	s_mov_b32 m0, s42
	s_nop 0
	global_load_lds_dwordx4 v130, s[100:101]
	s_mov_b32 m0, s43
	s_nop 0
	global_load_lds_dwordx4 v134, s[100:101]
	s_waitcnt vmcnt(8)
	s_waitcnt lgkmcnt(0)
	s_barrier
	s_setprio 1
	s_waitcnt lgkmcnt(0)
	v_mfma_f32_16x16x32_bf16 v[62:65], v[154:157], v[186:189], v[62:65]
	v_mfma_f32_16x16x32_bf16 v[58:61], v[162:165], v[186:189], v[58:61]
	v_mfma_f32_16x16x32_bf16 v[46:49], v[154:157], v[194:197], v[46:49]
	v_mfma_f32_16x16x32_bf16 v[42:45], v[162:165], v[194:197], v[42:45]
	v_mfma_f32_16x16x32_bf16 v[30:33], v[154:157], v[202:205], v[30:33]
	v_mfma_f32_16x16x32_bf16 v[26:29], v[162:165], v[202:205], v[26:29]
	v_mfma_f32_16x16x32_bf16 v[14:17], v[154:157], v[210:213], v[14:17]
	v_mfma_f32_16x16x32_bf16 v[10:13], v[162:165], v[210:213], v[10:13]
	v_mfma_f32_16x16x32_bf16 v[62:65], v[158:161], v[190:193], v[62:65]
	v_mfma_f32_16x16x32_bf16 v[58:61], v[166:169], v[190:193], v[58:61]
	v_mfma_f32_16x16x32_bf16 v[46:49], v[158:161], v[198:201], v[46:49]
	v_mfma_f32_16x16x32_bf16 v[42:45], v[166:169], v[198:201], v[42:45]
	v_mfma_f32_16x16x32_bf16 v[30:33], v[158:161], v[206:209], v[30:33]
	v_mfma_f32_16x16x32_bf16 v[26:29], v[166:169], v[206:209], v[26:29]
	v_mfma_f32_16x16x32_bf16 v[14:17], v[158:161], v[214:217], v[14:17]
	v_mfma_f32_16x16x32_bf16 v[10:13], v[166:169], v[214:217], v[10:13]
	v_mfma_f32_16x16x32_bf16 v[54:57], v[170:173], v[186:189], v[54:57]
	v_mfma_f32_16x16x32_bf16 v[50:53], v[178:181], v[186:189], v[50:53]
	v_mfma_f32_16x16x32_bf16 v[38:41], v[170:173], v[194:197], v[38:41]
	v_mfma_f32_16x16x32_bf16 v[34:37], v[178:181], v[194:197], v[34:37]
	v_mfma_f32_16x16x32_bf16 v[22:25], v[170:173], v[202:205], v[22:25]
	v_mfma_f32_16x16x32_bf16 v[18:21], v[178:181], v[202:205], v[18:21]
	v_mfma_f32_16x16x32_bf16 v[6:9], v[170:173], v[210:213], v[6:9]
	v_mfma_f32_16x16x32_bf16 v[2:5], v[178:181], v[210:213], v[2:5]
	v_mfma_f32_16x16x32_bf16 v[54:57], v[174:177], v[190:193], v[54:57]
	v_mfma_f32_16x16x32_bf16 v[50:53], v[182:185], v[190:193], v[50:53]
	v_mfma_f32_16x16x32_bf16 v[38:41], v[174:177], v[198:201], v[38:41]
	v_mfma_f32_16x16x32_bf16 v[34:37], v[182:185], v[198:201], v[34:37]
	v_mfma_f32_16x16x32_bf16 v[22:25], v[174:177], v[206:209], v[22:25]
	v_mfma_f32_16x16x32_bf16 v[18:21], v[182:185], v[206:209], v[18:21]
	v_mfma_f32_16x16x32_bf16 v[6:9], v[174:177], v[214:217], v[6:9]
	v_mfma_f32_16x16x32_bf16 v[2:5], v[182:185], v[214:217], v[2:5]
	s_setprio 0
	s_barrier
	s_add_i32 s50, s50, 2
	s_add_u32 s24, s24, 0x100
	s_addc_u32 s25, s25, 0
	s_cmp_gt_u32 s50, 41
	s_cbranch_scc0 .LBB0_619
	s_add_u32 s24, s48, 0xffffff00
	s_addc_u32 s25, s49, -1
	s_and_b64 vcc, exec, s[6:7]
	s_cbranch_vccnz .LBB0_622
	v_mov_b32_e32 v2, 0
	s_mov_b32 s10, s46
	s_mov_b32 s31, s47
	s_mov_b64 s[18:19], s[22:23]
	s_mov_b32 s41, s2
	v_mov_b32_e32 v3, v2
	v_mov_b32_e32 v4, v2
	v_mov_b32_e32 v5, v2
	v_mov_b32_e32 v6, v2
	v_mov_b32_e32 v7, v2
	v_mov_b32_e32 v8, v2
	v_mov_b32_e32 v9, v2
	v_mov_b32_e32 v18, v2
	v_mov_b32_e32 v19, v2
	v_mov_b32_e32 v20, v2
	v_mov_b32_e32 v21, v2
	v_mov_b32_e32 v22, v2
	v_mov_b32_e32 v23, v2
	v_mov_b32_e32 v24, v2
	v_mov_b32_e32 v25, v2
	v_mov_b32_e32 v34, v2
	v_mov_b32_e32 v35, v2
	v_mov_b32_e32 v36, v2
	v_mov_b32_e32 v37, v2
	v_mov_b32_e32 v38, v2
	v_mov_b32_e32 v39, v2
	v_mov_b32_e32 v40, v2
	v_mov_b32_e32 v41, v2
	v_mov_b32_e32 v50, v2
	v_mov_b32_e32 v51, v2
	v_mov_b32_e32 v52, v2
	v_mov_b32_e32 v53, v2
	v_mov_b32_e32 v54, v2
	v_mov_b32_e32 v55, v2
	v_mov_b32_e32 v56, v2
	v_mov_b32_e32 v57, v2
	v_mov_b32_e32 v10, v2
	v_mov_b32_e32 v11, v2
	v_mov_b32_e32 v12, v2
	v_mov_b32_e32 v13, v2
	v_mov_b32_e32 v14, v2
	v_mov_b32_e32 v15, v2
	v_mov_b32_e32 v16, v2
	v_mov_b32_e32 v17, v2
	v_mov_b32_e32 v26, v2
	v_mov_b32_e32 v27, v2
	v_mov_b32_e32 v28, v2
	v_mov_b32_e32 v29, v2
	v_mov_b32_e32 v30, v2
	v_mov_b32_e32 v31, v2
	v_mov_b32_e32 v32, v2
	v_mov_b32_e32 v33, v2
	v_mov_b32_e32 v42, v2
	v_mov_b32_e32 v43, v2
	v_mov_b32_e32 v44, v2
	v_mov_b32_e32 v45, v2
	v_mov_b32_e32 v46, v2
	v_mov_b32_e32 v47, v2
	v_mov_b32_e32 v48, v2
	v_mov_b32_e32 v49, v2
	v_mov_b32_e32 v58, v2
	v_mov_b32_e32 v59, v2
	v_mov_b32_e32 v60, v2
	v_mov_b32_e32 v61, v2
	v_mov_b32_e32 v62, v2
	v_mov_b32_e32 v63, v2
	v_mov_b32_e32 v64, v2
	v_mov_b32_e32 v65, v2
	v_mov_b32_e32 v66, v2
	v_mov_b32_e32 v67, v2
	v_mov_b32_e32 v68, v2
	v_mov_b32_e32 v69, v2
	v_mov_b32_e32 v70, v2
	v_mov_b32_e32 v71, v2
	v_mov_b32_e32 v72, v2
	v_mov_b32_e32 v73, v2
	v_mov_b32_e32 v82, v2
	v_mov_b32_e32 v83, v2
	v_mov_b32_e32 v84, v2
	v_mov_b32_e32 v85, v2
	v_mov_b32_e32 v86, v2
	v_mov_b32_e32 v87, v2
	v_mov_b32_e32 v88, v2
	v_mov_b32_e32 v89, v2
	v_mov_b32_e32 v98, v2
	v_mov_b32_e32 v99, v2
	v_mov_b32_e32 v100, v2
	v_mov_b32_e32 v101, v2
	v_mov_b32_e32 v102, v2
	v_mov_b32_e32 v103, v2
	v_mov_b32_e32 v104, v2
	v_mov_b32_e32 v105, v2
	v_mov_b32_e32 v114, v2
	v_mov_b32_e32 v115, v2
	v_mov_b32_e32 v116, v2
	v_mov_b32_e32 v117, v2
	v_mov_b32_e32 v118, v2
	v_mov_b32_e32 v119, v2
	v_mov_b32_e32 v120, v2
	v_mov_b32_e32 v121, v2
	v_mov_b32_e32 v74, v2
	v_mov_b32_e32 v75, v2
	v_mov_b32_e32 v76, v2
	v_mov_b32_e32 v77, v2
	v_mov_b32_e32 v78, v2
	v_mov_b32_e32 v79, v2
	v_mov_b32_e32 v80, v2
	v_mov_b32_e32 v81, v2
	v_mov_b32_e32 v90, v2
	v_mov_b32_e32 v91, v2
	v_mov_b32_e32 v92, v2
	v_mov_b32_e32 v93, v2
	v_mov_b32_e32 v94, v2
	v_mov_b32_e32 v95, v2
	v_mov_b32_e32 v96, v2
	v_mov_b32_e32 v97, v2
	v_mov_b32_e32 v106, v2
	v_mov_b32_e32 v107, v2
	v_mov_b32_e32 v108, v2
	v_mov_b32_e32 v109, v2
	v_mov_b32_e32 v110, v2
	v_mov_b32_e32 v111, v2
	v_mov_b32_e32 v112, v2
	v_mov_b32_e32 v113, v2
	v_mov_b32_e32 v122, v2
	v_mov_b32_e32 v123, v2
	v_mov_b32_e32 v124, v2
	v_mov_b32_e32 v125, v2
	v_mov_b32_e32 v126, v2
	v_mov_b32_e32 v127, v2
	v_mov_b32_e32 v128, v2
	v_mov_b32_e32 v129, v2
	s_andn2_b64 vcc, exec, s[4:5]
	s_cbranch_vccnz .LBB0_623
	s_branch .LBB0_624

.LBB0_774:
	ds_read_b128 v[38:41], v231
	ds_read_b128 v[42:45], v231 offset:1024
	ds_read_b128 v[54:57], v231 offset:2048
	ds_read_b128 v[58:61], v231 offset:3072
	ds_read_b128 v[126:129], v232
	ds_read_b128 v[146:149], v232 offset:1024
	ds_read_b128 v[166:169], v232 offset:2048
	ds_read_b128 v[170:173], v232 offset:3072
	s_add_u32 s14, s10, 0xfffc0080
	s_addc_u32 s15, s11, -1
	s_cmp_eq_u32 s13, 12
	s_cselect_b32 s59, s0, s15
	s_cselect_b32 s58, s1, s14
	s_cselect_b32 s57, s2, s12
	s_cselect_b32 s56, s7, s9
	s_add_i32 m0, s67, 0xc000
	ds_read_b128 v[174:177], v233
	ds_read_b128 v[194:197], v233 offset:1024
	ds_read_b128 v[198:201], v233 offset:2048
	ds_read_b128 v[202:205], v233 offset:3072
	ds_read_b128 v[206:209], v233 offset:4096
	ds_read_b128 v[210:213], v233 offset:5120
	ds_read_b128 v[214:217], v233 offset:6144
	ds_read_b128 v[218:221], v233 offset:7168
	global_load_lds_dwordx4 v186, s[10:11]
	s_add_i32 m0, s67, 0xe000
	s_nop 0
	global_load_lds_dwordx4 v188, s[10:11]
	s_waitcnt vmcnt(8)
	s_waitcnt lgkmcnt(0)
	s_barrier
	s_setprio 1
	s_waitcnt lgkmcnt(0)
	v_mfma_f32_16x16x32_bf16 v[162:165], v[38:41], v[174:177], v[162:165]
	v_mfma_f32_16x16x32_bf16 v[158:161], v[54:57], v[174:177], v[158:161]
	v_mfma_f32_16x16x32_bf16 v[142:145], v[38:41], v[198:201], v[142:145]
	v_mfma_f32_16x16x32_bf16 v[138:141], v[54:57], v[198:201], v[138:141]
	v_mfma_f32_16x16x32_bf16 v[122:125], v[38:41], v[206:209], v[122:125]
	v_mfma_f32_16x16x32_bf16 v[118:121], v[54:57], v[206:209], v[118:121]
	v_mfma_f32_16x16x32_bf16 v[106:109], v[38:41], v[214:217], v[106:109]
	v_mfma_f32_16x16x32_bf16 v[102:105], v[54:57], v[214:217], v[102:105]
	v_mfma_f32_16x16x32_bf16 v[162:165], v[42:45], v[194:197], v[162:165]
	v_mfma_f32_16x16x32_bf16 v[158:161], v[58:61], v[194:197], v[158:161]
	v_mfma_f32_16x16x32_bf16 v[142:145], v[42:45], v[202:205], v[142:145]
	v_mfma_f32_16x16x32_bf16 v[138:141], v[58:61], v[202:205], v[138:141]
	v_mfma_f32_16x16x32_bf16 v[122:125], v[42:45], v[210:213], v[122:125]
	v_mfma_f32_16x16x32_bf16 v[118:121], v[58:61], v[210:213], v[118:121]
	v_mfma_f32_16x16x32_bf16 v[106:109], v[42:45], v[218:221], v[106:109]
	v_mfma_f32_16x16x32_bf16 v[102:105], v[58:61], v[218:221], v[102:105]
	v_mfma_f32_16x16x32_bf16 v[154:157], v[126:129], v[174:177], v[154:157]
	v_mfma_f32_16x16x32_bf16 v[150:153], v[166:169], v[174:177], v[150:153]
	v_mfma_f32_16x16x32_bf16 v[134:137], v[126:129], v[198:201], v[134:137]
	v_mfma_f32_16x16x32_bf16 v[130:133], v[166:169], v[198:201], v[130:133]
	v_mfma_f32_16x16x32_bf16 v[114:117], v[126:129], v[206:209], v[114:117]
	v_mfma_f32_16x16x32_bf16 v[110:113], v[166:169], v[206:209], v[110:113]
	v_mfma_f32_16x16x32_bf16 v[98:101], v[126:129], v[214:217], v[98:101]
	v_mfma_f32_16x16x32_bf16 v[94:97], v[166:169], v[214:217], v[94:97]
	v_mfma_f32_16x16x32_bf16 v[154:157], v[146:149], v[194:197], v[154:157]
	v_mfma_f32_16x16x32_bf16 v[150:153], v[170:173], v[194:197], v[150:153]
	v_mfma_f32_16x16x32_bf16 v[134:137], v[146:149], v[202:205], v[134:137]
	v_mfma_f32_16x16x32_bf16 v[130:133], v[170:173], v[202:205], v[130:133]
	v_mfma_f32_16x16x32_bf16 v[114:117], v[146:149], v[210:213], v[114:117]
	v_mfma_f32_16x16x32_bf16 v[110:113], v[170:173], v[210:213], v[110:113]
	v_mfma_f32_16x16x32_bf16 v[98:101], v[146:149], v[218:221], v[98:101]
	v_mfma_f32_16x16x32_bf16 v[94:97], v[170:173], v[218:221], v[94:97]
	s_setprio 0
	s_barrier
	s_add_i32 s14, s84, s66
	s_add_u32 s98, s56, s20
	s_addc_u32 s99, s57, s21
	s_mov_b32 m0, s14
	ds_read_b128 v[174:177], v233 offset:16384
	ds_read_b128 v[194:197], v233 offset:17408
	ds_read_b128 v[198:201], v233 offset:18432
	ds_read_b128 v[202:205], v233 offset:19456
	ds_read_b128 v[206:209], v233 offset:20480
	ds_read_b128 v[210:213], v233 offset:21504
	ds_read_b128 v[214:217], v233 offset:22528
	ds_read_b128 v[218:221], v233 offset:23552
	global_load_lds_dwordx4 v180, s[56:57]
	s_add_i32 m0, s14, 0x2000
	s_add_u32 s14, s56, 0x40000
	s_addc_u32 s15, s57, 0
	s_add_i32 s33, s85, s66
	global_load_lds_dwordx4 v184, s[56:57]
	s_mov_b32 m0, s33
	s_add_u32 s100, s58, s20
	s_addc_u32 s101, s59, s21
	global_load_lds_dwordx4 v180, s[14:15]
	s_add_i32 m0, s33, 0x2000
	s_nop 0
	global_load_lds_dwordx4 v184, s[14:15]
	s_mov_b32 m0, s67
	s_nop 0
	global_load_lds_dwordx4 v178, s[58:59]
	s_mov_b32 m0, s68
	s_nop 0
	global_load_lds_dwordx4 v182, s[58:59]
	s_waitcnt vmcnt(8)
	s_waitcnt lgkmcnt(0)
	s_barrier
	s_setprio 1
	s_waitcnt lgkmcnt(0)
	v_mfma_f32_16x16x32_bf16 v[90:93], v[38:41], v[174:177], v[90:93]
	v_mfma_f32_16x16x32_bf16 v[86:89], v[54:57], v[174:177], v[86:89]
	v_mfma_f32_16x16x32_bf16 v[74:77], v[38:41], v[198:201], v[74:77]
	v_mfma_f32_16x16x32_bf16 v[70:73], v[54:57], v[198:201], v[70:73]
	v_mfma_f32_16x16x32_bf16 v[50:53], v[38:41], v[206:209], v[50:53]
	v_mfma_f32_16x16x32_bf16 v[46:49], v[54:57], v[206:209], v[46:49]
	v_mfma_f32_16x16x32_bf16 v[26:29], v[38:41], v[214:217], v[26:29]
	v_mfma_f32_16x16x32_bf16 v[22:25], v[54:57], v[214:217], v[22:25]
	v_mfma_f32_16x16x32_bf16 v[90:93], v[42:45], v[194:197], v[90:93]
	v_mfma_f32_16x16x32_bf16 v[86:89], v[58:61], v[194:197], v[86:89]
	v_mfma_f32_16x16x32_bf16 v[74:77], v[42:45], v[202:205], v[74:77]
	v_mfma_f32_16x16x32_bf16 v[70:73], v[58:61], v[202:205], v[70:73]
	v_mfma_f32_16x16x32_bf16 v[50:53], v[42:45], v[210:213], v[50:53]
	v_mfma_f32_16x16x32_bf16 v[46:49], v[58:61], v[210:213], v[46:49]
	v_mfma_f32_16x16x32_bf16 v[26:29], v[42:45], v[218:221], v[26:29]
	v_mfma_f32_16x16x32_bf16 v[22:25], v[58:61], v[218:221], v[22:25]
	v_mfma_f32_16x16x32_bf16 v[34:37], v[126:129], v[206:209], v[34:37]
	v_mfma_f32_16x16x32_bf16 v[30:33], v[166:169], v[206:209], v[30:33]
	v_mfma_f32_16x16x32_bf16 v[18:21], v[126:129], v[214:217], v[18:21]
	v_mfma_f32_16x16x32_bf16 v[12:15], v[166:169], v[214:217], v[14:17]
	v_mfma_f32_16x16x32_bf16 v[38:41], v[126:129], v[174:177], v[82:85]
	v_mfma_f32_16x16x32_bf16 v[42:45], v[166:169], v[174:177], v[78:81]
	v_mfma_f32_16x16x32_bf16 v[54:57], v[126:129], v[198:201], v[66:69]
	v_mfma_f32_16x16x32_bf16 v[58:61], v[166:169], v[198:201], v[62:65]
	v_mfma_f32_16x16x32_bf16 v[34:37], v[146:149], v[210:213], v[34:37]
	v_mfma_f32_16x16x32_bf16 v[30:33], v[170:173], v[210:213], v[30:33]
	v_mfma_f32_16x16x32_bf16 v[18:21], v[146:149], v[218:221], v[18:21]
	v_mfma_f32_16x16x32_bf16 v[12:15], v[170:173], v[218:221], v[12:15]
	v_mfma_f32_16x16x32_bf16 v[38:41], v[146:149], v[194:197], v[38:41]
	v_mfma_f32_16x16x32_bf16 v[42:45], v[170:173], v[194:197], v[42:45]
	v_mfma_f32_16x16x32_bf16 v[54:57], v[146:149], v[202:205], v[54:57]
	v_mfma_f32_16x16x32_bf16 v[58:61], v[170:173], v[202:205], v[58:61]
	s_setprio 0
	s_barrier
	s_add_i32 s33, 0, 0x18000
	v_add_u32_e32 v3, s33, v230
	s_add_i32 s40, 0, 0x1c000
	ds_read_b128 v[62:65], v3
	ds_read_b128 v[66:69], v3 offset:1024
	ds_read_b128 v[78:81], v3 offset:2048
	ds_read_b128 v[82:85], v3 offset:3072
	v_add_u32_e32 v3, s40, v230
	ds_read_b128 v[126:129], v3
	ds_read_b128 v[146:149], v3 offset:1024
	ds_read_b128 v[166:169], v3 offset:2048
	ds_read_b128 v[170:173], v3 offset:3072
	s_add_u32 s14, s58, 0x40000
	s_addc_u32 s15, s59, 0
	s_mov_b32 m0, s69
	ds_read_b128 v[174:177], v233 offset:32768
	ds_read_b128 v[194:197], v233 offset:33792
	ds_read_b128 v[198:201], v233 offset:34816
	ds_read_b128 v[202:205], v233 offset:35840
	ds_read_b128 v[206:209], v233 offset:36864
	ds_read_b128 v[210:213], v233 offset:37888
	ds_read_b128 v[214:217], v233 offset:38912
	ds_read_b128 v[218:221], v233 offset:39936
	global_load_lds_dwordx4 v178, s[14:15]
	s_mov_b32 m0, s70
	s_nop 0
	global_load_lds_dwordx4 v182, s[14:15]
	s_waitcnt vmcnt(8)
	s_waitcnt lgkmcnt(0)
	s_barrier
	s_setprio 1
	s_waitcnt lgkmcnt(0)
	v_mfma_f32_16x16x32_bf16 v[162:165], v[62:65], v[174:177], v[162:165]
	v_mfma_f32_16x16x32_bf16 v[158:161], v[78:81], v[174:177], v[158:161]
	v_mfma_f32_16x16x32_bf16 v[142:145], v[62:65], v[198:201], v[142:145]
	v_mfma_f32_16x16x32_bf16 v[138:141], v[78:81], v[198:201], v[138:141]
	v_mfma_f32_16x16x32_bf16 v[122:125], v[62:65], v[206:209], v[122:125]
	v_mfma_f32_16x16x32_bf16 v[118:121], v[78:81], v[206:209], v[118:121]
	v_mfma_f32_16x16x32_bf16 v[106:109], v[62:65], v[214:217], v[106:109]
	v_mfma_f32_16x16x32_bf16 v[102:105], v[78:81], v[214:217], v[102:105]
	v_mfma_f32_16x16x32_bf16 v[162:165], v[66:69], v[194:197], v[162:165]
	v_mfma_f32_16x16x32_bf16 v[158:161], v[82:85], v[194:197], v[158:161]
	v_mfma_f32_16x16x32_bf16 v[142:145], v[66:69], v[202:205], v[142:145]
	v_mfma_f32_16x16x32_bf16 v[138:141], v[82:85], v[202:205], v[138:141]
	v_mfma_f32_16x16x32_bf16 v[122:125], v[66:69], v[210:213], v[122:125]
	v_mfma_f32_16x16x32_bf16 v[118:121], v[82:85], v[210:213], v[118:121]
	v_mfma_f32_16x16x32_bf16 v[106:109], v[66:69], v[218:221], v[106:109]
	v_mfma_f32_16x16x32_bf16 v[102:105], v[82:85], v[218:221], v[102:105]
	v_mfma_f32_16x16x32_bf16 v[154:157], v[126:129], v[174:177], v[154:157]
	v_mfma_f32_16x16x32_bf16 v[150:153], v[166:169], v[174:177], v[150:153]
	v_mfma_f32_16x16x32_bf16 v[134:137], v[126:129], v[198:201], v[134:137]
	v_mfma_f32_16x16x32_bf16 v[130:133], v[166:169], v[198:201], v[130:133]
	v_mfma_f32_16x16x32_bf16 v[114:117], v[126:129], v[206:209], v[114:117]
	v_mfma_f32_16x16x32_bf16 v[110:113], v[166:169], v[206:209], v[110:113]
	v_mfma_f32_16x16x32_bf16 v[98:101], v[126:129], v[214:217], v[98:101]
	v_mfma_f32_16x16x32_bf16 v[94:97], v[166:169], v[214:217], v[94:97]
	v_mfma_f32_16x16x32_bf16 v[154:157], v[146:149], v[194:197], v[154:157]
	v_mfma_f32_16x16x32_bf16 v[150:153], v[170:173], v[194:197], v[150:153]
	v_mfma_f32_16x16x32_bf16 v[134:137], v[146:149], v[202:205], v[134:137]
	v_mfma_f32_16x16x32_bf16 v[130:133], v[170:173], v[202:205], v[130:133]
	v_mfma_f32_16x16x32_bf16 v[114:117], v[146:149], v[210:213], v[114:117]
	v_mfma_f32_16x16x32_bf16 v[110:113], v[170:173], v[210:213], v[110:113]
	v_mfma_f32_16x16x32_bf16 v[98:101], v[146:149], v[218:221], v[98:101]
	v_mfma_f32_16x16x32_bf16 v[94:97], v[170:173], v[218:221], v[94:97]
	s_setprio 0
	s_barrier
	s_add_i32 s14, s33, s66
	s_mov_b32 m0, s14
	ds_read_b128 v[174:177], v233 offset:49152
	ds_read_b128 v[194:197], v233 offset:50176
	ds_read_b128 v[198:201], v233 offset:51200
	ds_read_b128 v[202:205], v233 offset:52224
	ds_read_b128 v[206:209], v233 offset:53248
	ds_read_b128 v[210:213], v233 offset:54272
	ds_read_b128 v[214:217], v233 offset:55296
	ds_read_b128 v[218:221], v233 offset:56320
	global_load_lds_dwordx4 v180, s[98:99]
	s_add_i32 m0, s14, 0x2000
	s_add_u32 s14, s56, 0x40080
	s_addc_u32 s15, s57, 0
	s_add_i32 s33, s40, s66
	global_load_lds_dwordx4 v184, s[98:99]
	s_mov_b32 m0, s33
	s_nop 0
	global_load_lds_dwordx4 v180, s[14:15]
	s_add_i32 m0, s33, 0x2000
	s_nop 0
	global_load_lds_dwordx4 v184, s[14:15]
	s_mov_b32 m0, s76
	s_nop 0
	global_load_lds_dwordx4 v178, s[100:101]
	s_mov_b32 m0, s77
	s_nop 0
	global_load_lds_dwordx4 v182, s[100:101]
	s_waitcnt vmcnt(8)
	s_waitcnt lgkmcnt(0)
	s_barrier
	s_setprio 1
	s_waitcnt lgkmcnt(0)
	v_mfma_f32_16x16x32_bf16 v[90:93], v[62:65], v[174:177], v[90:93]
	v_mfma_f32_16x16x32_bf16 v[86:89], v[78:81], v[174:177], v[86:89]
	v_mfma_f32_16x16x32_bf16 v[74:77], v[62:65], v[198:201], v[74:77]
	v_mfma_f32_16x16x32_bf16 v[70:73], v[78:81], v[198:201], v[70:73]
	v_mfma_f32_16x16x32_bf16 v[50:53], v[62:65], v[206:209], v[50:53]
	v_mfma_f32_16x16x32_bf16 v[46:49], v[78:81], v[206:209], v[46:49]
	v_mfma_f32_16x16x32_bf16 v[26:29], v[62:65], v[214:217], v[26:29]
	v_mfma_f32_16x16x32_bf16 v[22:25], v[78:81], v[214:217], v[22:25]
	v_mfma_f32_16x16x32_bf16 v[90:93], v[66:69], v[194:197], v[90:93]
	v_mfma_f32_16x16x32_bf16 v[86:89], v[82:85], v[194:197], v[86:89]
	v_mfma_f32_16x16x32_bf16 v[74:77], v[66:69], v[202:205], v[74:77]
	v_mfma_f32_16x16x32_bf16 v[70:73], v[82:85], v[202:205], v[70:73]
	v_mfma_f32_16x16x32_bf16 v[50:53], v[66:69], v[210:213], v[50:53]
	v_mfma_f32_16x16x32_bf16 v[46:49], v[82:85], v[210:213], v[46:49]
	v_mfma_f32_16x16x32_bf16 v[26:29], v[66:69], v[218:221], v[26:29]
	v_mfma_f32_16x16x32_bf16 v[22:25], v[82:85], v[218:221], v[22:25]
	v_mfma_f32_16x16x32_bf16 v[38:41], v[126:129], v[174:177], v[38:41]
	v_mfma_f32_16x16x32_bf16 v[82:85], v[146:149], v[194:197], v[38:41]
	v_mfma_f32_16x16x32_bf16 v[38:41], v[166:169], v[174:177], v[42:45]
	v_mfma_f32_16x16x32_bf16 v[78:81], v[170:173], v[194:197], v[38:41]
	v_mfma_f32_16x16x32_bf16 v[38:41], v[126:129], v[198:201], v[54:57]
	v_mfma_f32_16x16x32_bf16 v[66:69], v[146:149], v[202:205], v[38:41]
	v_mfma_f32_16x16x32_bf16 v[38:41], v[166:169], v[198:201], v[58:61]
	v_mfma_f32_16x16x32_bf16 v[34:37], v[126:129], v[206:209], v[34:37]
	v_mfma_f32_16x16x32_bf16 v[30:33], v[166:169], v[206:209], v[30:33]
	v_mfma_f32_16x16x32_bf16 v[16:19], v[126:129], v[214:217], v[18:21]
	v_mfma_f32_16x16x32_bf16 v[12:15], v[166:169], v[214:217], v[12:15]
	v_mfma_f32_16x16x32_bf16 v[62:65], v[170:173], v[202:205], v[38:41]
	v_mfma_f32_16x16x32_bf16 v[34:37], v[146:149], v[210:213], v[34:37]
	v_mfma_f32_16x16x32_bf16 v[30:33], v[170:173], v[210:213], v[30:33]
	v_mfma_f32_16x16x32_bf16 v[18:21], v[146:149], v[218:221], v[16:19]
	v_mfma_f32_16x16x32_bf16 v[14:17], v[170:173], v[218:221], v[12:15]
	s_setprio 0
	s_barrier
	s_add_i32 s13, s13, 2
	s_add_u32 s10, s10, 0x100
	s_addc_u32 s11, s11, 0
	s_add_u32 s9, s9, 0x100
	s_addc_u32 s12, s12, 0
	s_cmp_gt_u32 s13, 13
	s_cbranch_scc0 .LBB0_774
	s_and_b64 vcc, exec, s[22:23]
	s_cbranch_vccz .LBB0_777
	s_barrier

.LBB0_1038:
	ds_read_b128 v[26:29], v214
	ds_read_b128 v[30:33], v214 offset:1024
	ds_read_b128 v[34:37], v214 offset:2048
	ds_read_b128 v[38:41], v214 offset:3072
	ds_read_b128 v[122:125], v215
	ds_read_b128 v[142:145], v215 offset:1024
	ds_read_b128 v[162:165], v215 offset:2048
	ds_read_b128 v[166:169], v215 offset:3072
	s_add_i32 s33, s31, 2
	s_add_u32 s40, s6, 0xfffd0080
	s_addc_u32 s41, s7, -1
	s_cmp_eq_u32 s13, s31
	s_cselect_b32 s55, s47, s41
	s_cselect_b32 s54, s46, s40
	s_cselect_b32 s53, s1, s15
	s_cselect_b32 s52, s2, s14
	s_add_i32 m0, s66, 0xc000
	ds_read_b128 v[170:173], v216
	ds_read_b128 v[174:177], v216 offset:1024
	ds_read_b128 v[178:181], v216 offset:2048
	ds_read_b128 v[198:201], v216 offset:3072
	ds_read_b128 v[202:205], v216 offset:4096
	ds_read_b128 v[206:209], v216 offset:5120
	ds_read_b128 v[220:223], v216 offset:6144
	ds_read_b128 v[228:231], v216 offset:7168
	global_load_lds_dwordx4 v190, s[6:7]
	s_add_i32 m0, s66, 0xe000
	s_nop 0
	global_load_lds_dwordx4 v192, s[6:7]
	s_waitcnt vmcnt(8)
	s_waitcnt lgkmcnt(0)
	s_barrier
	s_setprio 1
	s_waitcnt lgkmcnt(0)
	v_mfma_f32_16x16x32_bf16 v[158:161], v[26:29], v[170:173], v[158:161]
	v_mfma_f32_16x16x32_bf16 v[154:157], v[34:37], v[170:173], v[154:157]
	v_mfma_f32_16x16x32_bf16 v[138:141], v[26:29], v[178:181], v[138:141]
	v_mfma_f32_16x16x32_bf16 v[134:137], v[34:37], v[178:181], v[134:137]
	v_mfma_f32_16x16x32_bf16 v[118:121], v[26:29], v[202:205], v[118:121]
	v_mfma_f32_16x16x32_bf16 v[114:117], v[34:37], v[202:205], v[114:117]
	v_mfma_f32_16x16x32_bf16 v[102:105], v[26:29], v[220:223], v[102:105]
	v_mfma_f32_16x16x32_bf16 v[98:101], v[34:37], v[220:223], v[98:101]
	v_mfma_f32_16x16x32_bf16 v[158:161], v[30:33], v[174:177], v[158:161]
	v_mfma_f32_16x16x32_bf16 v[154:157], v[38:41], v[174:177], v[154:157]
	v_mfma_f32_16x16x32_bf16 v[138:141], v[30:33], v[198:201], v[138:141]
	v_mfma_f32_16x16x32_bf16 v[134:137], v[38:41], v[198:201], v[134:137]
	v_mfma_f32_16x16x32_bf16 v[118:121], v[30:33], v[206:209], v[118:121]
	v_mfma_f32_16x16x32_bf16 v[114:117], v[38:41], v[206:209], v[114:117]
	v_mfma_f32_16x16x32_bf16 v[102:105], v[30:33], v[228:231], v[102:105]
	v_mfma_f32_16x16x32_bf16 v[98:101], v[38:41], v[228:231], v[98:101]
	v_mfma_f32_16x16x32_bf16 v[150:153], v[122:125], v[170:173], v[150:153]
	v_mfma_f32_16x16x32_bf16 v[146:149], v[162:165], v[170:173], v[146:149]
	v_mfma_f32_16x16x32_bf16 v[130:133], v[122:125], v[178:181], v[130:133]
	v_mfma_f32_16x16x32_bf16 v[126:129], v[162:165], v[178:181], v[126:129]
	v_mfma_f32_16x16x32_bf16 v[110:113], v[122:125], v[202:205], v[110:113]
	v_mfma_f32_16x16x32_bf16 v[106:109], v[162:165], v[202:205], v[106:109]
	v_mfma_f32_16x16x32_bf16 v[94:97], v[122:125], v[220:223], v[94:97]
	v_mfma_f32_16x16x32_bf16 v[90:93], v[162:165], v[220:223], v[90:93]
	v_mfma_f32_16x16x32_bf16 v[150:153], v[142:145], v[174:177], v[150:153]
	v_mfma_f32_16x16x32_bf16 v[146:149], v[166:169], v[174:177], v[146:149]
	v_mfma_f32_16x16x32_bf16 v[130:133], v[142:145], v[198:201], v[130:133]
	v_mfma_f32_16x16x32_bf16 v[126:129], v[166:169], v[198:201], v[126:129]
	v_mfma_f32_16x16x32_bf16 v[110:113], v[142:145], v[206:209], v[110:113]
	v_mfma_f32_16x16x32_bf16 v[106:109], v[166:169], v[206:209], v[106:109]
	v_mfma_f32_16x16x32_bf16 v[94:97], v[142:145], v[228:231], v[94:97]
	v_mfma_f32_16x16x32_bf16 v[90:93], v[166:169], v[228:231], v[90:93]
	s_setprio 0
	s_barrier
	s_add_i32 s31, s85, s64
	s_add_u32 s98, s52, s18
	s_addc_u32 s99, s53, s19
	s_mov_b32 m0, s31
	ds_read_b128 v[170:173], v216 offset:16384
	ds_read_b128 v[174:177], v216 offset:17408
	ds_read_b128 v[178:181], v216 offset:18432
	ds_read_b128 v[198:201], v216 offset:19456
	ds_read_b128 v[202:205], v216 offset:20480
	ds_read_b128 v[206:209], v216 offset:21504
	ds_read_b128 v[220:223], v216 offset:22528
	ds_read_b128 v[228:231], v216 offset:23552
	global_load_lds_dwordx4 v184, s[52:53]
	s_add_i32 m0, s31, 0x2000
	s_add_u32 s40, s52, 0x10000
	s_addc_u32 s41, s53, 0
	s_add_i32 s31, s86, s64
	global_load_lds_dwordx4 v188, s[52:53]
	s_mov_b32 m0, s31
	s_add_u32 s100, s54, s18
	s_addc_u32 s101, s55, s19
	global_load_lds_dwordx4 v184, s[40:41]
	s_add_i32 m0, s31, 0x2000
	s_nop 0
	global_load_lds_dwordx4 v188, s[40:41]
	s_mov_b32 m0, s66
	s_nop 0
	global_load_lds_dwordx4 v182, s[54:55]
	s_mov_b32 m0, s67
	s_nop 0
	global_load_lds_dwordx4 v186, s[54:55]
	s_waitcnt vmcnt(8)
	s_waitcnt lgkmcnt(0)
	s_barrier
	s_setprio 1
	s_waitcnt lgkmcnt(0)
	v_mfma_f32_16x16x32_bf16 v[86:89], v[26:29], v[170:173], v[86:89]
	v_mfma_f32_16x16x32_bf16 v[82:85], v[34:37], v[170:173], v[82:85]
	v_mfma_f32_16x16x32_bf16 v[70:73], v[26:29], v[178:181], v[70:73]
	v_mfma_f32_16x16x32_bf16 v[66:69], v[34:37], v[178:181], v[66:69]
	v_mfma_f32_16x16x32_bf16 v[54:57], v[26:29], v[202:205], v[54:57]
	v_mfma_f32_16x16x32_bf16 v[50:53], v[34:37], v[202:205], v[50:53]
	v_mfma_f32_16x16x32_bf16 v[22:25], v[26:29], v[220:223], v[22:25]
	v_mfma_f32_16x16x32_bf16 v[18:21], v[34:37], v[220:223], v[18:21]
	v_mfma_f32_16x16x32_bf16 v[86:89], v[30:33], v[174:177], v[86:89]
	v_mfma_f32_16x16x32_bf16 v[82:85], v[38:41], v[174:177], v[82:85]
	v_mfma_f32_16x16x32_bf16 v[70:73], v[30:33], v[198:201], v[70:73]
	v_mfma_f32_16x16x32_bf16 v[66:69], v[38:41], v[198:201], v[66:69]
	v_mfma_f32_16x16x32_bf16 v[54:57], v[30:33], v[206:209], v[54:57]
	v_mfma_f32_16x16x32_bf16 v[50:53], v[38:41], v[206:209], v[50:53]
	v_mfma_f32_16x16x32_bf16 v[22:25], v[30:33], v[228:231], v[22:25]
	v_mfma_f32_16x16x32_bf16 v[18:21], v[38:41], v[228:231], v[18:21]
	v_mfma_f32_16x16x32_bf16 v[46:49], v[122:125], v[202:205], v[46:49]
	v_mfma_f32_16x16x32_bf16 v[42:45], v[162:165], v[202:205], v[42:45]
	v_mfma_f32_16x16x32_bf16 v[14:17], v[122:125], v[220:223], v[14:17]
	v_mfma_f32_16x16x32_bf16 v[8:11], v[162:165], v[220:223], v[10:13]
	v_mfma_f32_16x16x32_bf16 v[26:29], v[122:125], v[170:173], v[78:81]
	v_mfma_f32_16x16x32_bf16 v[30:33], v[162:165], v[170:173], v[74:77]
	v_mfma_f32_16x16x32_bf16 v[34:37], v[122:125], v[178:181], v[62:65]
	v_mfma_f32_16x16x32_bf16 v[38:41], v[162:165], v[178:181], v[58:61]
	v_mfma_f32_16x16x32_bf16 v[46:49], v[142:145], v[206:209], v[46:49]
	v_mfma_f32_16x16x32_bf16 v[42:45], v[166:169], v[206:209], v[42:45]
	v_mfma_f32_16x16x32_bf16 v[14:17], v[142:145], v[228:231], v[14:17]
	v_mfma_f32_16x16x32_bf16 v[8:11], v[166:169], v[228:231], v[8:11]
	v_mfma_f32_16x16x32_bf16 v[26:29], v[142:145], v[174:177], v[26:29]
	v_mfma_f32_16x16x32_bf16 v[30:33], v[166:169], v[174:177], v[30:33]
	v_mfma_f32_16x16x32_bf16 v[34:37], v[142:145], v[198:201], v[34:37]
	v_mfma_f32_16x16x32_bf16 v[38:41], v[166:169], v[198:201], v[38:41]
	s_setprio 0
	s_barrier
	s_add_i32 s31, 0, 0x18000
	v_add_u32_e32 v3, s31, v213
	s_add_i32 s42, 0, 0x1c000
	ds_read_b128 v[58:61], v3
	ds_read_b128 v[62:65], v3 offset:1024
	ds_read_b128 v[74:77], v3 offset:2048
	ds_read_b128 v[78:81], v3 offset:3072
	v_add_u32_e32 v3, s42, v213
	ds_read_b128 v[122:125], v3
	ds_read_b128 v[142:145], v3 offset:1024
	ds_read_b128 v[162:165], v3 offset:2048
	ds_read_b128 v[166:169], v3 offset:3072
	s_add_u32 s40, s54, 0x30000
	s_addc_u32 s41, s55, 0
	s_mov_b32 m0, s68
	ds_read_b128 v[170:173], v216 offset:32768
	ds_read_b128 v[174:177], v216 offset:33792
	ds_read_b128 v[178:181], v216 offset:34816
	ds_read_b128 v[198:201], v216 offset:35840
	ds_read_b128 v[202:205], v216 offset:36864
	ds_read_b128 v[206:209], v216 offset:37888
	ds_read_b128 v[220:223], v216 offset:38912
	ds_read_b128 v[228:231], v216 offset:39936
	global_load_lds_dwordx4 v182, s[40:41]
	s_mov_b32 m0, s69
	s_nop 0
	global_load_lds_dwordx4 v186, s[40:41]
	s_waitcnt vmcnt(8)
	s_waitcnt lgkmcnt(0)
	s_barrier
	s_setprio 1
	s_waitcnt lgkmcnt(0)
	v_mfma_f32_16x16x32_bf16 v[158:161], v[58:61], v[170:173], v[158:161]
	v_mfma_f32_16x16x32_bf16 v[154:157], v[74:77], v[170:173], v[154:157]
	v_mfma_f32_16x16x32_bf16 v[138:141], v[58:61], v[178:181], v[138:141]
	v_mfma_f32_16x16x32_bf16 v[134:137], v[74:77], v[178:181], v[134:137]
	v_mfma_f32_16x16x32_bf16 v[118:121], v[58:61], v[202:205], v[118:121]
	v_mfma_f32_16x16x32_bf16 v[114:117], v[74:77], v[202:205], v[114:117]
	v_mfma_f32_16x16x32_bf16 v[102:105], v[58:61], v[220:223], v[102:105]
	v_mfma_f32_16x16x32_bf16 v[98:101], v[74:77], v[220:223], v[98:101]
	v_mfma_f32_16x16x32_bf16 v[158:161], v[62:65], v[174:177], v[158:161]
	v_mfma_f32_16x16x32_bf16 v[154:157], v[78:81], v[174:177], v[154:157]
	v_mfma_f32_16x16x32_bf16 v[138:141], v[62:65], v[198:201], v[138:141]
	v_mfma_f32_16x16x32_bf16 v[134:137], v[78:81], v[198:201], v[134:137]
	v_mfma_f32_16x16x32_bf16 v[118:121], v[62:65], v[206:209], v[118:121]
	v_mfma_f32_16x16x32_bf16 v[114:117], v[78:81], v[206:209], v[114:117]
	v_mfma_f32_16x16x32_bf16 v[102:105], v[62:65], v[228:231], v[102:105]
	v_mfma_f32_16x16x32_bf16 v[98:101], v[78:81], v[228:231], v[98:101]
	v_mfma_f32_16x16x32_bf16 v[150:153], v[122:125], v[170:173], v[150:153]
	v_mfma_f32_16x16x32_bf16 v[146:149], v[162:165], v[170:173], v[146:149]
	v_mfma_f32_16x16x32_bf16 v[130:133], v[122:125], v[178:181], v[130:133]
	v_mfma_f32_16x16x32_bf16 v[126:129], v[162:165], v[178:181], v[126:129]
	v_mfma_f32_16x16x32_bf16 v[110:113], v[122:125], v[202:205], v[110:113]
	v_mfma_f32_16x16x32_bf16 v[106:109], v[162:165], v[202:205], v[106:109]
	v_mfma_f32_16x16x32_bf16 v[94:97], v[122:125], v[220:223], v[94:97]
	v_mfma_f32_16x16x32_bf16 v[90:93], v[162:165], v[220:223], v[90:93]
	v_mfma_f32_16x16x32_bf16 v[150:153], v[142:145], v[174:177], v[150:153]
	v_mfma_f32_16x16x32_bf16 v[146:149], v[166:169], v[174:177], v[146:149]
	v_mfma_f32_16x16x32_bf16 v[130:133], v[142:145], v[198:201], v[130:133]
	v_mfma_f32_16x16x32_bf16 v[126:129], v[166:169], v[198:201], v[126:129]
	v_mfma_f32_16x16x32_bf16 v[110:113], v[142:145], v[206:209], v[110:113]
	v_mfma_f32_16x16x32_bf16 v[106:109], v[166:169], v[206:209], v[106:109]
	v_mfma_f32_16x16x32_bf16 v[94:97], v[142:145], v[228:231], v[94:97]
	v_mfma_f32_16x16x32_bf16 v[90:93], v[166:169], v[228:231], v[90:93]
	s_setprio 0
	s_barrier
	s_add_i32 s31, s31, s64
	s_mov_b32 m0, s31
	ds_read_b128 v[170:173], v216 offset:49152
	ds_read_b128 v[174:177], v216 offset:50176
	ds_read_b128 v[178:181], v216 offset:51200
	ds_read_b128 v[198:201], v216 offset:52224
	ds_read_b128 v[202:205], v216 offset:53248
	ds_read_b128 v[206:209], v216 offset:54272
	ds_read_b128 v[220:223], v216 offset:55296
	ds_read_b128 v[228:231], v216 offset:56320
	global_load_lds_dwordx4 v184, s[98:99]
	s_add_i32 m0, s31, 0x2000
	s_add_u32 s40, s52, 0x10080
	s_addc_u32 s41, s53, 0
	s_add_i32 s31, s42, s64
	global_load_lds_dwordx4 v188, s[98:99]
	s_mov_b32 m0, s31
	s_nop 0
	global_load_lds_dwordx4 v184, s[40:41]
	s_add_i32 m0, s31, 0x2000
	s_nop 0
	global_load_lds_dwordx4 v188, s[40:41]
	s_mov_b32 m0, s76
	s_nop 0
	global_load_lds_dwordx4 v182, s[100:101]
	s_mov_b32 m0, s77
	s_nop 0
	global_load_lds_dwordx4 v186, s[100:101]
	s_waitcnt vmcnt(8)
	s_waitcnt lgkmcnt(0)
	s_barrier
	s_setprio 1
	s_waitcnt lgkmcnt(0)
	v_mfma_f32_16x16x32_bf16 v[86:89], v[58:61], v[170:173], v[86:89]
	v_mfma_f32_16x16x32_bf16 v[82:85], v[74:77], v[170:173], v[82:85]
	v_mfma_f32_16x16x32_bf16 v[70:73], v[58:61], v[178:181], v[70:73]
	v_mfma_f32_16x16x32_bf16 v[66:69], v[74:77], v[178:181], v[66:69]
	v_mfma_f32_16x16x32_bf16 v[54:57], v[58:61], v[202:205], v[54:57]
	v_mfma_f32_16x16x32_bf16 v[50:53], v[74:77], v[202:205], v[50:53]
	v_mfma_f32_16x16x32_bf16 v[22:25], v[58:61], v[220:223], v[22:25]
	v_mfma_f32_16x16x32_bf16 v[18:21], v[74:77], v[220:223], v[18:21]
	v_mfma_f32_16x16x32_bf16 v[86:89], v[62:65], v[174:177], v[86:89]
	v_mfma_f32_16x16x32_bf16 v[82:85], v[78:81], v[174:177], v[82:85]
	v_mfma_f32_16x16x32_bf16 v[70:73], v[62:65], v[198:201], v[70:73]
	v_mfma_f32_16x16x32_bf16 v[66:69], v[78:81], v[198:201], v[66:69]
	v_mfma_f32_16x16x32_bf16 v[54:57], v[62:65], v[206:209], v[54:57]
	v_mfma_f32_16x16x32_bf16 v[50:53], v[78:81], v[206:209], v[50:53]
	v_mfma_f32_16x16x32_bf16 v[22:25], v[62:65], v[228:231], v[22:25]
	v_mfma_f32_16x16x32_bf16 v[18:21], v[78:81], v[228:231], v[18:21]
	v_mfma_f32_16x16x32_bf16 v[26:29], v[122:125], v[170:173], v[26:29]
	v_mfma_f32_16x16x32_bf16 v[78:81], v[142:145], v[174:177], v[26:29]
	v_mfma_f32_16x16x32_bf16 v[26:29], v[162:165], v[170:173], v[30:33]
	v_mfma_f32_16x16x32_bf16 v[74:77], v[166:169], v[174:177], v[26:29]
	v_mfma_f32_16x16x32_bf16 v[26:29], v[122:125], v[178:181], v[34:37]
	v_mfma_f32_16x16x32_bf16 v[62:65], v[142:145], v[198:201], v[26:29]
	v_mfma_f32_16x16x32_bf16 v[26:29], v[162:165], v[178:181], v[38:41]
	v_mfma_f32_16x16x32_bf16 v[58:61], v[166:169], v[198:201], v[26:29]
	v_mfma_f32_16x16x32_bf16 v[26:29], v[122:125], v[202:205], v[46:49]
	v_mfma_f32_16x16x32_bf16 v[46:49], v[142:145], v[206:209], v[26:29]
	v_mfma_f32_16x16x32_bf16 v[26:29], v[162:165], v[202:205], v[42:45]
	v_mfma_f32_16x16x32_bf16 v[12:15], v[122:125], v[220:223], v[14:17]
	v_mfma_f32_16x16x32_bf16 v[8:11], v[162:165], v[220:223], v[8:11]
	v_mfma_f32_16x16x32_bf16 v[42:45], v[166:169], v[206:209], v[26:29]
	v_mfma_f32_16x16x32_bf16 v[14:17], v[142:145], v[228:231], v[12:15]
	v_mfma_f32_16x16x32_bf16 v[10:13], v[166:169], v[228:231], v[8:11]
	s_setprio 0
	s_barrier
	s_add_u32 s6, s6, 0x100
	s_addc_u32 s7, s7, 0
	s_add_u32 s14, s14, 0x100
	s_addc_u32 s15, s15, 0
	s_cmp_ge_u32 s33, s12
	s_mov_b32 s31, s33
	s_cbranch_scc0 .LBB0_1038
	s_and_b64 vcc, exec, s[20:21]
	s_cbranch_vccz .LBB0_1041
	s_barrier

.LBB0_1523:
	ds_read_b128 v[2:5], v148
	ds_read_b128 v[6:9], v148 offset:1024
	ds_read_b128 v[10:13], v148 offset:2048
	ds_read_b128 v[14:17], v148 offset:3072
	ds_read_b128 v[18:21], v149
	ds_read_b128 v[22:25], v149 offset:1024
	ds_read_b128 v[26:29], v149 offset:2048
	ds_read_b128 v[30:33], v149 offset:3072
	s_ashr_i32 s47, s46, 31
	s_lshl_b64 s[50:51], s[46:47], 17
	s_add_u32 s50, s1, s50
	s_addc_u32 s51, s12, s51
	s_and_b64 s[6:7], s[6:7], exec
	s_cselect_b32 s7, s51, s59
	s_cselect_b32 s6, s50, s58
	s_add_u32 s64, s56, 0x10080
	s_addc_u32 s65, s57, 0
	s_add_i32 s62, s14, 0xc000
	v_lshl_add_u64 v[66:67], s[64:65], 0, v[130:131]
	s_mov_b32 m0, s62
	s_add_i32 s2, s14, 0xe000
	ds_read_b128 v[34:37], v150
	ds_read_b128 v[38:41], v150 offset:1024
	ds_read_b128 v[42:45], v150 offset:2048
	ds_read_b128 v[46:49], v150 offset:3072
	ds_read_b128 v[50:53], v150 offset:4096
	ds_read_b128 v[54:57], v150 offset:5120
	ds_read_b128 v[58:61], v150 offset:6144
	ds_read_b128 v[62:65], v150 offset:7168
	global_load_lds_dwordx4 v[66:67], off
	v_lshl_add_u64 v[66:67], s[64:65], 0, v[134:135]
	s_mov_b32 m0, s2
	s_nop 0
	global_load_lds_dwordx4 v[66:67], off
	s_waitcnt vmcnt(8)
	s_waitcnt lgkmcnt(0)
	s_barrier
	s_setprio 1
	s_waitcnt lgkmcnt(0)
	v_mfma_f32_16x16x32_bf16 v[66:69], v[2:5], v[34:37], 0
	v_mfma_f32_16x16x32_bf16 v[70:73], v[10:13], v[34:37], 0
	v_mfma_f32_16x16x32_bf16 v[74:77], v[2:5], v[42:45], 0
	v_mfma_f32_16x16x32_bf16 v[78:81], v[10:13], v[42:45], 0
	v_mfma_f32_16x16x32_bf16 v[82:85], v[2:5], v[50:53], 0
	v_mfma_f32_16x16x32_bf16 v[86:89], v[10:13], v[50:53], 0
	v_mfma_f32_16x16x32_bf16 v[90:93], v[2:5], v[58:61], 0
	v_mfma_f32_16x16x32_bf16 v[94:97], v[10:13], v[58:61], 0
	v_mfma_f32_16x16x32_bf16 v[66:69], v[6:9], v[38:41], v[66:69]
	v_mfma_f32_16x16x32_bf16 v[70:73], v[14:17], v[38:41], v[70:73]
	v_mfma_f32_16x16x32_bf16 v[74:77], v[6:9], v[46:49], v[74:77]
	v_mfma_f32_16x16x32_bf16 v[78:81], v[14:17], v[46:49], v[78:81]
	v_mfma_f32_16x16x32_bf16 v[82:85], v[6:9], v[54:57], v[82:85]
	v_mfma_f32_16x16x32_bf16 v[86:89], v[14:17], v[54:57], v[86:89]
	v_mfma_f32_16x16x32_bf16 v[90:93], v[6:9], v[62:65], v[90:93]
	v_mfma_f32_16x16x32_bf16 v[94:97], v[14:17], v[62:65], v[94:97]
	v_mfma_f32_16x16x32_bf16 v[98:101], v[18:21], v[34:37], 0
	v_mfma_f32_16x16x32_bf16 v[34:37], v[26:29], v[34:37], 0
	v_mfma_f32_16x16x32_bf16 v[98:101], v[22:25], v[38:41], v[98:101]
	v_mfma_f32_16x16x32_bf16 v[34:37], v[30:33], v[38:41], v[34:37]
	v_mfma_f32_16x16x32_bf16 v[38:41], v[18:21], v[42:45], 0
	v_mfma_f32_16x16x32_bf16 v[42:45], v[26:29], v[42:45], 0
	v_mfma_f32_16x16x32_bf16 v[38:41], v[22:25], v[46:49], v[38:41]
	v_mfma_f32_16x16x32_bf16 v[42:45], v[30:33], v[46:49], v[42:45]
	v_mfma_f32_16x16x32_bf16 v[46:49], v[18:21], v[50:53], 0
	v_mfma_f32_16x16x32_bf16 v[50:53], v[26:29], v[50:53], 0
	v_mfma_f32_16x16x32_bf16 v[46:49], v[22:25], v[54:57], v[46:49]
	v_mfma_f32_16x16x32_bf16 v[50:53], v[30:33], v[54:57], v[50:53]
	v_mfma_f32_16x16x32_bf16 v[54:57], v[18:21], v[58:61], 0
	v_mfma_f32_16x16x32_bf16 v[58:61], v[26:29], v[58:61], 0
	v_mfma_f32_16x16x32_bf16 v[54:57], v[22:25], v[62:65], v[54:57]
	v_mfma_f32_16x16x32_bf16 v[58:61], v[30:33], v[62:65], v[58:61]
	s_setprio 0
	s_barrier
	s_add_i32 s55, s45, s13
	v_lshl_add_u64 v[212:213], s[58:59], 0, v[132:133]
	s_add_i32 s31, s55, 0x2000
	v_lshl_add_u64 v[142:143], v[212:213], 0, s[26:27]
	s_mov_b32 m0, s55
	v_lshl_add_u64 v[214:215], s[58:59], 0, v[136:137]
	s_add_u32 s64, s58, 0x10100
	ds_read_b128 v[62:65], v150 offset:16384
	ds_read_b128 v[102:105], v150 offset:17408
	ds_read_b128 v[106:109], v150 offset:18432
	ds_read_b128 v[110:113], v150 offset:19456
	ds_read_b128 v[114:117], v150 offset:20480
	ds_read_b128 v[118:121], v150 offset:21504
	ds_read_b128 v[122:125], v150 offset:22528
	ds_read_b128 v[126:129], v150 offset:23552
	global_load_lds_dwordx4 v[142:143], off
	v_lshl_add_u64 v[142:143], v[214:215], 0, s[26:27]
	s_mov_b32 m0, s31
	s_addc_u32 s65, s59, 0
	s_add_i32 s47, s60, s13
	global_load_lds_dwordx4 v[142:143], off
	v_lshl_add_u64 v[142:143], s[64:65], 0, v[132:133]
	s_mov_b32 m0, s47
	s_add_i32 s53, s47, 0x2000
	global_load_lds_dwordx4 v[142:143], off
	v_lshl_add_u64 v[142:143], s[64:65], 0, v[136:137]
	s_mov_b32 m0, s53
	v_lshl_add_u64 v[216:217], s[56:57], 0, v[130:131]
	global_load_lds_dwordx4 v[142:143], off
	v_lshl_add_u64 v[142:143], v[216:217], 0, s[26:27]
	s_mov_b32 m0, s14
	v_lshl_add_u64 v[218:219], s[56:57], 0, v[134:135]
	global_load_lds_dwordx4 v[142:143], off
	v_lshl_add_u64 v[142:143], v[218:219], 0, s[26:27]
	s_mov_b32 m0, s15
	s_nop 0
	global_load_lds_dwordx4 v[142:143], off
	s_waitcnt vmcnt(8)
	s_waitcnt lgkmcnt(0)
	s_barrier
	s_setprio 1
	s_waitcnt lgkmcnt(0)
	v_mfma_f32_16x16x32_bf16 v[142:145], v[2:5], v[62:65], 0
	v_mfma_f32_16x16x32_bf16 v[156:159], v[2:5], v[106:109], 0
	v_mfma_f32_16x16x32_bf16 v[164:167], v[2:5], v[114:117], 0
	v_mfma_f32_16x16x32_bf16 v[2:5], v[2:5], v[122:125], 0
	v_mfma_f32_16x16x32_bf16 v[142:145], v[6:9], v[102:105], v[142:145]
	v_mfma_f32_16x16x32_bf16 v[156:159], v[6:9], v[110:113], v[156:159]
	v_mfma_f32_16x16x32_bf16 v[164:167], v[6:9], v[118:121], v[164:167]
	v_mfma_f32_16x16x32_bf16 v[2:5], v[6:9], v[126:129], v[2:5]
	v_mfma_f32_16x16x32_bf16 v[6:9], v[10:13], v[122:125], 0
	v_mfma_f32_16x16x32_bf16 v[152:155], v[10:13], v[62:65], 0
	v_mfma_f32_16x16x32_bf16 v[160:163], v[10:13], v[106:109], 0
	v_mfma_f32_16x16x32_bf16 v[168:171], v[10:13], v[114:117], 0
	v_mfma_f32_16x16x32_bf16 v[6:9], v[14:17], v[126:129], v[6:9]
	v_mfma_f32_16x16x32_bf16 v[152:155], v[14:17], v[102:105], v[152:155]
	v_mfma_f32_16x16x32_bf16 v[160:163], v[14:17], v[110:113], v[160:163]
	v_mfma_f32_16x16x32_bf16 v[168:171], v[14:17], v[118:121], v[168:171]
	v_mfma_f32_16x16x32_bf16 v[10:13], v[18:21], v[62:65], 0
	v_mfma_f32_16x16x32_bf16 v[14:17], v[26:29], v[62:65], 0
	v_mfma_f32_16x16x32_bf16 v[10:13], v[22:25], v[102:105], v[10:13]
	v_mfma_f32_16x16x32_bf16 v[14:17], v[30:33], v[102:105], v[14:17]
	v_mfma_f32_16x16x32_bf16 v[62:65], v[18:21], v[106:109], 0
	v_mfma_f32_16x16x32_bf16 v[102:105], v[26:29], v[106:109], 0
	v_mfma_f32_16x16x32_bf16 v[106:109], v[18:21], v[114:117], 0
	v_mfma_f32_16x16x32_bf16 v[18:21], v[18:21], v[122:125], 0
	v_mfma_f32_16x16x32_bf16 v[62:65], v[22:25], v[110:113], v[62:65]
	v_mfma_f32_16x16x32_bf16 v[102:105], v[30:33], v[110:113], v[102:105]
	v_mfma_f32_16x16x32_bf16 v[106:109], v[22:25], v[118:121], v[106:109]
	v_mfma_f32_16x16x32_bf16 v[110:113], v[26:29], v[114:117], 0
	v_mfma_f32_16x16x32_bf16 v[18:21], v[22:25], v[126:129], v[18:21]
	v_mfma_f32_16x16x32_bf16 v[22:25], v[26:29], v[122:125], 0
	v_mfma_f32_16x16x32_bf16 v[110:113], v[30:33], v[118:121], v[110:113]
	v_mfma_f32_16x16x32_bf16 v[22:25], v[30:33], v[126:129], v[22:25]
	s_setprio 0
	s_barrier
	s_add_i32 s63, 0, 0x18000
	s_add_i32 s66, 0, 0x1c000
	v_add_u32_e32 v151, s63, v147
	v_add_u32_e32 v222, s66, v147
	ds_read_b128 v[26:29], v151
	ds_read_b128 v[30:33], v151 offset:1024
	ds_read_b128 v[114:117], v151 offset:2048
	ds_read_b128 v[118:121], v151 offset:3072
	ds_read_b128 v[122:125], v222
	ds_read_b128 v[126:129], v222 offset:1024
	ds_read_b128 v[172:175], v222 offset:2048
	ds_read_b128 v[176:179], v222 offset:3072
	s_add_u32 s64, s56, 0x10100
	s_addc_u32 s65, s57, 0
	s_mov_b32 m0, s33
	v_lshl_add_u64 v[220:221], s[64:65], 0, v[130:131]
	ds_read_b128 v[180:183], v150 offset:32768
	ds_read_b128 v[184:187], v150 offset:33792
	ds_read_b128 v[188:191], v150 offset:34816
	ds_read_b128 v[192:195], v150 offset:35840
	ds_read_b128 v[196:199], v150 offset:36864
	ds_read_b128 v[200:203], v150 offset:37888
	ds_read_b128 v[204:207], v150 offset:38912
	ds_read_b128 v[208:211], v150 offset:39936
	global_load_lds_dwordx4 v[220:221], off
	v_lshl_add_u64 v[220:221], s[64:65], 0, v[134:135]
	s_mov_b32 m0, s40
	s_nop 0
	global_load_lds_dwordx4 v[220:221], off
	s_waitcnt vmcnt(8)
	s_waitcnt lgkmcnt(0)
	s_barrier
	s_setprio 1
	s_waitcnt lgkmcnt(0)
	v_mfma_f32_16x16x32_bf16 v[66:69], v[26:29], v[180:183], v[66:69]
	v_mfma_f32_16x16x32_bf16 v[70:73], v[114:117], v[180:183], v[70:73]
	v_mfma_f32_16x16x32_bf16 v[74:77], v[26:29], v[188:191], v[74:77]
	v_mfma_f32_16x16x32_bf16 v[78:81], v[114:117], v[188:191], v[78:81]
	v_mfma_f32_16x16x32_bf16 v[82:85], v[26:29], v[196:199], v[82:85]
	v_mfma_f32_16x16x32_bf16 v[86:89], v[114:117], v[196:199], v[86:89]
	v_mfma_f32_16x16x32_bf16 v[90:93], v[26:29], v[204:207], v[90:93]
	v_mfma_f32_16x16x32_bf16 v[94:97], v[114:117], v[204:207], v[94:97]
	v_mfma_f32_16x16x32_bf16 v[66:69], v[30:33], v[184:187], v[66:69]
	v_mfma_f32_16x16x32_bf16 v[70:73], v[118:121], v[184:187], v[70:73]
	v_mfma_f32_16x16x32_bf16 v[74:77], v[30:33], v[192:195], v[74:77]
	v_mfma_f32_16x16x32_bf16 v[78:81], v[118:121], v[192:195], v[78:81]
	v_mfma_f32_16x16x32_bf16 v[82:85], v[30:33], v[200:203], v[82:85]
	v_mfma_f32_16x16x32_bf16 v[86:89], v[118:121], v[200:203], v[86:89]
	v_mfma_f32_16x16x32_bf16 v[90:93], v[30:33], v[208:211], v[90:93]
	v_mfma_f32_16x16x32_bf16 v[94:97], v[118:121], v[208:211], v[94:97]
	v_mfma_f32_16x16x32_bf16 v[98:101], v[122:125], v[180:183], v[98:101]
	v_mfma_f32_16x16x32_bf16 v[34:37], v[172:175], v[180:183], v[34:37]
	v_mfma_f32_16x16x32_bf16 v[38:41], v[122:125], v[188:191], v[38:41]
	v_mfma_f32_16x16x32_bf16 v[42:45], v[172:175], v[188:191], v[42:45]
	v_mfma_f32_16x16x32_bf16 v[46:49], v[122:125], v[196:199], v[46:49]
	v_mfma_f32_16x16x32_bf16 v[50:53], v[172:175], v[196:199], v[50:53]
	v_mfma_f32_16x16x32_bf16 v[54:57], v[122:125], v[204:207], v[54:57]
	v_mfma_f32_16x16x32_bf16 v[58:61], v[172:175], v[204:207], v[58:61]
	v_mfma_f32_16x16x32_bf16 v[98:101], v[126:129], v[184:187], v[98:101]
	v_mfma_f32_16x16x32_bf16 v[34:37], v[176:179], v[184:187], v[34:37]
	v_mfma_f32_16x16x32_bf16 v[38:41], v[126:129], v[192:195], v[38:41]
	v_mfma_f32_16x16x32_bf16 v[42:45], v[176:179], v[192:195], v[42:45]
	v_mfma_f32_16x16x32_bf16 v[46:49], v[126:129], v[200:203], v[46:49]
	v_mfma_f32_16x16x32_bf16 v[50:53], v[176:179], v[200:203], v[50:53]
	v_mfma_f32_16x16x32_bf16 v[54:57], v[126:129], v[208:211], v[54:57]
	v_mfma_f32_16x16x32_bf16 v[58:61], v[176:179], v[208:211], v[58:61]
	s_setprio 0
	s_barrier
	s_add_i32 s63, s63, s13
	s_add_i32 s61, s63, 0x2000
	v_lshl_add_u64 v[212:213], v[212:213], 0, s[28:29]
	s_mov_b32 m0, s63
	s_add_u32 s64, s58, 0x10180
	ds_read_b128 v[180:183], v150 offset:49152
	ds_read_b128 v[184:187], v150 offset:50176
	ds_read_b128 v[188:191], v150 offset:51200
	ds_read_b128 v[192:195], v150 offset:52224
	ds_read_b128 v[196:199], v150 offset:53248
	ds_read_b128 v[200:203], v150 offset:54272
	ds_read_b128 v[204:207], v150 offset:55296
	ds_read_b128 v[208:211], v150 offset:56320
	global_load_lds_dwordx4 v[212:213], off
	v_lshl_add_u64 v[212:213], v[214:215], 0, s[28:29]
	s_mov_b32 m0, s61
	s_addc_u32 s65, s59, 0
	s_add_i32 s58, s66, s13
	global_load_lds_dwordx4 v[212:213], off
	v_lshl_add_u64 v[212:213], s[64:65], 0, v[132:133]
	s_mov_b32 m0, s58
	s_add_i32 s59, s58, 0x2000
	global_load_lds_dwordx4 v[212:213], off
	v_lshl_add_u64 v[212:213], s[64:65], 0, v[136:137]
	s_mov_b32 m0, s59
	s_nop 0
	global_load_lds_dwordx4 v[212:213], off
	v_lshl_add_u64 v[212:213], v[216:217], 0, s[28:29]
	s_mov_b32 m0, s43
	s_nop 0
	global_load_lds_dwordx4 v[212:213], off
	v_lshl_add_u64 v[212:213], v[218:219], 0, s[28:29]
	s_mov_b32 m0, s44
	s_nop 0
	global_load_lds_dwordx4 v[212:213], off
	s_waitcnt vmcnt(8)
	s_waitcnt lgkmcnt(0)
	s_barrier
	s_setprio 1
	s_waitcnt lgkmcnt(0)
	v_mfma_f32_16x16x32_bf16 v[2:5], v[26:29], v[204:207], v[2:5]
	v_mfma_f32_16x16x32_bf16 v[6:9], v[114:117], v[204:207], v[6:9]
	v_mfma_f32_16x16x32_bf16 v[142:145], v[26:29], v[180:183], v[142:145]
	v_mfma_f32_16x16x32_bf16 v[152:155], v[114:117], v[180:183], v[152:155]
	v_mfma_f32_16x16x32_bf16 v[156:159], v[26:29], v[188:191], v[156:159]
	v_mfma_f32_16x16x32_bf16 v[160:163], v[114:117], v[188:191], v[160:163]
	v_mfma_f32_16x16x32_bf16 v[164:167], v[26:29], v[196:199], v[164:167]
	v_mfma_f32_16x16x32_bf16 v[168:171], v[114:117], v[196:199], v[168:171]
	v_mfma_f32_16x16x32_bf16 v[2:5], v[30:33], v[208:211], v[2:5]
	v_mfma_f32_16x16x32_bf16 v[6:9], v[118:121], v[208:211], v[6:9]
	v_mfma_f32_16x16x32_bf16 v[142:145], v[30:33], v[184:187], v[142:145]
	v_mfma_f32_16x16x32_bf16 v[152:155], v[118:121], v[184:187], v[152:155]
	v_mfma_f32_16x16x32_bf16 v[156:159], v[30:33], v[192:195], v[156:159]
	v_mfma_f32_16x16x32_bf16 v[160:163], v[118:121], v[192:195], v[160:163]
	v_mfma_f32_16x16x32_bf16 v[164:167], v[30:33], v[200:203], v[164:167]
	v_mfma_f32_16x16x32_bf16 v[168:171], v[118:121], v[200:203], v[168:171]
	v_mfma_f32_16x16x32_bf16 v[10:13], v[122:125], v[180:183], v[10:13]
	v_mfma_f32_16x16x32_bf16 v[14:17], v[172:175], v[180:183], v[14:17]
	v_mfma_f32_16x16x32_bf16 v[26:29], v[122:125], v[188:191], v[62:65]
	v_mfma_f32_16x16x32_bf16 v[30:33], v[172:175], v[188:191], v[102:105]
	v_mfma_f32_16x16x32_bf16 v[62:65], v[122:125], v[196:199], v[106:109]
	v_mfma_f32_16x16x32_bf16 v[102:105], v[172:175], v[196:199], v[110:113]
	v_mfma_f32_16x16x32_bf16 v[18:21], v[122:125], v[204:207], v[18:21]
	v_mfma_f32_16x16x32_bf16 v[22:25], v[172:175], v[204:207], v[22:25]
	v_mfma_f32_16x16x32_bf16 v[10:13], v[126:129], v[184:187], v[10:13]
	v_mfma_f32_16x16x32_bf16 v[14:17], v[176:179], v[184:187], v[14:17]
	v_mfma_f32_16x16x32_bf16 v[26:29], v[126:129], v[192:195], v[26:29]
	v_mfma_f32_16x16x32_bf16 v[30:33], v[176:179], v[192:195], v[30:33]
	v_mfma_f32_16x16x32_bf16 v[62:65], v[126:129], v[200:203], v[62:65]
	v_mfma_f32_16x16x32_bf16 v[102:105], v[176:179], v[200:203], v[102:105]
	v_mfma_f32_16x16x32_bf16 v[18:21], v[126:129], v[208:211], v[18:21]
	v_mfma_f32_16x16x32_bf16 v[22:25], v[176:179], v[208:211], v[22:25]
	s_setprio 0
	s_barrier
	ds_read_b128 v[106:109], v148
	ds_read_b128 v[110:113], v148 offset:1024
	ds_read_b128 v[114:117], v148 offset:2048
	ds_read_b128 v[118:121], v148 offset:3072
	ds_read_b128 v[122:125], v149
	ds_read_b128 v[126:129], v149 offset:1024
	ds_read_b128 v[172:175], v149 offset:2048
	ds_read_b128 v[176:179], v149 offset:3072
	s_add_u32 s56, s56, 0x10180
	s_addc_u32 s57, s57, 0
	s_mov_b32 m0, s62
	v_lshl_add_u64 v[212:213], s[56:57], 0, v[130:131]
	ds_read_b128 v[180:183], v150
	ds_read_b128 v[184:187], v150 offset:1024
	ds_read_b128 v[188:191], v150 offset:2048
	ds_read_b128 v[192:195], v150 offset:3072
	ds_read_b128 v[196:199], v150 offset:4096
	ds_read_b128 v[200:203], v150 offset:5120
	ds_read_b128 v[204:207], v150 offset:6144
	ds_read_b128 v[208:211], v150 offset:7168
	global_load_lds_dwordx4 v[212:213], off
	v_lshl_add_u64 v[212:213], s[56:57], 0, v[134:135]
	s_mov_b32 m0, s2
	s_nop 0
	global_load_lds_dwordx4 v[212:213], off
	s_waitcnt vmcnt(8)
	s_waitcnt lgkmcnt(0)
	s_barrier
	s_setprio 1
	s_waitcnt lgkmcnt(0)
	v_mfma_f32_16x16x32_bf16 v[90:93], v[106:109], v[204:207], v[90:93]
	v_mfma_f32_16x16x32_bf16 v[66:69], v[106:109], v[180:183], v[66:69]
	v_mfma_f32_16x16x32_bf16 v[70:73], v[114:117], v[180:183], v[70:73]
	v_mfma_f32_16x16x32_bf16 v[74:77], v[106:109], v[188:191], v[74:77]
	v_mfma_f32_16x16x32_bf16 v[78:81], v[114:117], v[188:191], v[78:81]
	v_mfma_f32_16x16x32_bf16 v[82:85], v[106:109], v[196:199], v[82:85]
	v_mfma_f32_16x16x32_bf16 v[86:89], v[114:117], v[196:199], v[86:89]
	v_mfma_f32_16x16x32_bf16 v[212:215], v[110:113], v[208:211], v[90:93]
	v_mfma_f32_16x16x32_bf16 v[90:93], v[114:117], v[204:207], v[94:97]
	v_mfma_f32_16x16x32_bf16 v[66:69], v[110:113], v[184:187], v[66:69]
	v_mfma_f32_16x16x32_bf16 v[70:73], v[118:121], v[184:187], v[70:73]
	v_mfma_f32_16x16x32_bf16 v[74:77], v[110:113], v[192:195], v[74:77]
	v_mfma_f32_16x16x32_bf16 v[78:81], v[118:121], v[192:195], v[78:81]
	v_mfma_f32_16x16x32_bf16 v[82:85], v[110:113], v[200:203], v[82:85]
	v_mfma_f32_16x16x32_bf16 v[86:89], v[118:121], v[200:203], v[86:89]
	v_mfma_f32_16x16x32_bf16 v[94:97], v[118:121], v[208:211], v[90:93]
	v_mfma_f32_16x16x32_bf16 v[34:37], v[172:175], v[180:183], v[34:37]
	v_mfma_f32_16x16x32_bf16 v[38:41], v[122:125], v[188:191], v[38:41]
	v_mfma_f32_16x16x32_bf16 v[42:45], v[172:175], v[188:191], v[42:45]
	v_mfma_f32_16x16x32_bf16 v[46:49], v[122:125], v[196:199], v[46:49]
	v_mfma_f32_16x16x32_bf16 v[50:53], v[172:175], v[196:199], v[50:53]
	v_mfma_f32_16x16x32_bf16 v[54:57], v[122:125], v[204:207], v[54:57]
	v_mfma_f32_16x16x32_bf16 v[58:61], v[172:175], v[204:207], v[58:61]
	v_mfma_f32_16x16x32_bf16 v[90:93], v[122:125], v[180:183], v[98:101]
	v_mfma_f32_16x16x32_bf16 v[34:37], v[176:179], v[184:187], v[34:37]
	v_mfma_f32_16x16x32_bf16 v[38:41], v[126:129], v[192:195], v[38:41]
	v_mfma_f32_16x16x32_bf16 v[42:45], v[176:179], v[192:195], v[42:45]
	v_mfma_f32_16x16x32_bf16 v[46:49], v[126:129], v[200:203], v[46:49]
	v_mfma_f32_16x16x32_bf16 v[50:53], v[176:179], v[200:203], v[50:53]
	v_mfma_f32_16x16x32_bf16 v[54:57], v[126:129], v[208:211], v[54:57]
	v_mfma_f32_16x16x32_bf16 v[58:61], v[176:179], v[208:211], v[58:61]
	v_mfma_f32_16x16x32_bf16 v[216:219], v[126:129], v[184:187], v[90:93]
	s_setprio 0
	s_barrier
	s_mov_b32 m0, s55
	v_lshl_add_u64 v[224:225], s[6:7], 0, v[132:133]
	s_add_u32 s56, s6, 0x10000
	ds_read_b128 v[90:93], v150 offset:16384
	ds_read_b128 v[98:101], v150 offset:17408
	ds_read_b128 v[180:183], v150 offset:18432
	ds_read_b128 v[184:187], v150 offset:19456
	ds_read_b128 v[188:191], v150 offset:20480
	ds_read_b128 v[192:195], v150 offset:21504
	ds_read_b128 v[196:199], v150 offset:22528
	ds_read_b128 v[200:203], v150 offset:23552
	global_load_lds_dwordx4 v[224:225], off
	v_lshl_add_u64 v[226:227], s[6:7], 0, v[136:137]
	s_mov_b32 m0, s31
	s_addc_u32 s57, s7, 0
	global_load_lds_dwordx4 v[226:227], off
	v_lshl_add_u64 v[204:205], s[56:57], 0, v[132:133]
	s_mov_b32 m0, s47
	v_lshl_add_u64 v[248:249], s[48:49], 0, v[130:131]
	global_load_lds_dwordx4 v[204:205], off
	v_lshl_add_u64 v[204:205], s[56:57], 0, v[136:137]
	s_mov_b32 m0, s53
	v_lshl_add_u64 v[250:251], s[48:49], 0, v[134:135]
	global_load_lds_dwordx4 v[204:205], off
	s_mov_b32 m0, s14
	s_nop 0
	global_load_lds_dwordx4 v[248:249], off
	s_mov_b32 m0, s15
	s_nop 0
	global_load_lds_dwordx4 v[250:251], off
	s_waitcnt vmcnt(8)
	s_waitcnt lgkmcnt(0)
	s_barrier
	s_setprio 1
	s_waitcnt lgkmcnt(0)
	v_mfma_f32_16x16x32_bf16 v[2:5], v[106:109], v[196:199], v[2:5]
	v_mfma_f32_16x16x32_bf16 v[6:9], v[114:117], v[196:199], v[6:9]
	v_mfma_f32_16x16x32_bf16 v[142:145], v[106:109], v[90:93], v[142:145]
	v_mfma_f32_16x16x32_bf16 v[152:155], v[114:117], v[90:93], v[152:155]
	v_mfma_f32_16x16x32_bf16 v[156:159], v[106:109], v[180:183], v[156:159]
	v_mfma_f32_16x16x32_bf16 v[160:163], v[114:117], v[180:183], v[160:163]
	v_mfma_f32_16x16x32_bf16 v[164:167], v[106:109], v[188:191], v[164:167]
	v_mfma_f32_16x16x32_bf16 v[168:171], v[114:117], v[188:191], v[168:171]
	v_mfma_f32_16x16x32_bf16 v[2:5], v[110:113], v[200:203], v[2:5]
	v_mfma_f32_16x16x32_bf16 v[6:9], v[118:121], v[200:203], v[6:9]
	v_mfma_f32_16x16x32_bf16 v[142:145], v[110:113], v[98:101], v[142:145]
	v_mfma_f32_16x16x32_bf16 v[152:155], v[118:121], v[98:101], v[152:155]
	v_mfma_f32_16x16x32_bf16 v[156:159], v[110:113], v[184:187], v[156:159]
	v_mfma_f32_16x16x32_bf16 v[160:163], v[118:121], v[184:187], v[160:163]
	v_mfma_f32_16x16x32_bf16 v[164:167], v[110:113], v[192:195], v[164:167]
	v_mfma_f32_16x16x32_bf16 v[168:171], v[118:121], v[192:195], v[168:171]
	v_mfma_f32_16x16x32_bf16 v[10:13], v[122:125], v[90:93], v[10:13]
	v_mfma_f32_16x16x32_bf16 v[204:207], v[126:129], v[98:101], v[10:13]
	v_mfma_f32_16x16x32_bf16 v[10:13], v[172:175], v[90:93], v[14:17]
	v_mfma_f32_16x16x32_bf16 v[14:17], v[176:179], v[98:101], v[10:13]
	v_mfma_f32_16x16x32_bf16 v[10:13], v[122:125], v[180:183], v[26:29]
	v_mfma_f32_16x16x32_bf16 v[208:211], v[126:129], v[184:187], v[10:13]
	v_mfma_f32_16x16x32_bf16 v[10:13], v[172:175], v[180:183], v[30:33]
	v_mfma_f32_16x16x32_bf16 v[30:33], v[176:179], v[184:187], v[10:13]
	v_mfma_f32_16x16x32_bf16 v[10:13], v[122:125], v[188:191], v[62:65]
	v_mfma_f32_16x16x32_bf16 v[180:183], v[126:129], v[192:195], v[10:13]
	v_mfma_f32_16x16x32_bf16 v[10:13], v[172:175], v[188:191], v[102:105]
	v_mfma_f32_16x16x32_bf16 v[184:187], v[176:179], v[192:195], v[10:13]
	v_mfma_f32_16x16x32_bf16 v[10:13], v[122:125], v[196:199], v[18:21]
	v_mfma_f32_16x16x32_bf16 v[188:191], v[126:129], v[200:203], v[10:13]
	v_mfma_f32_16x16x32_bf16 v[10:13], v[172:175], v[196:199], v[22:25]
	v_mfma_f32_16x16x32_bf16 v[172:175], v[176:179], v[200:203], v[10:13]
	s_setprio 0
	s_barrier
	s_nop 4
	ds_read_b128 v[10:13], v151
	ds_read_b128 v[22:25], v151 offset:1024
	ds_read_b128 v[62:65], v151 offset:2048
	ds_read_b128 v[176:179], v151 offset:3072
	ds_read_b128 v[192:195], v222
	ds_read_b128 v[196:199], v222 offset:1024
	ds_read_b128 v[200:203], v222 offset:2048
	ds_read_b128 v[220:223], v222 offset:3072
	s_add_u32 s56, s48, 0x10000
	s_addc_u32 s57, s49, 0
	s_mov_b32 m0, s33
	v_lshl_add_u64 v[90:91], s[56:57], 0, v[130:131]
	ds_read_b128 v[18:21], v150 offset:32768
	ds_read_b128 v[26:29], v150 offset:33792
	ds_read_b128 v[102:105], v150 offset:34816
	ds_read_b128 v[228:231], v150 offset:35840
	ds_read_b128 v[232:235], v150 offset:36864
	ds_read_b128 v[236:239], v150 offset:37888
	ds_read_b128 v[240:243], v150 offset:38912
	ds_read_b128 v[244:247], v150 offset:39936
	global_load_lds_dwordx4 v[90:91], off
	v_lshl_add_u64 v[90:91], s[56:57], 0, v[134:135]
	s_mov_b32 m0, s40
	s_nop 0
	global_load_lds_dwordx4 v[90:91], off
	s_waitcnt vmcnt(8)
	s_waitcnt lgkmcnt(0)
	s_barrier
	s_setprio 1
	s_waitcnt lgkmcnt(0)
	v_mfma_f32_16x16x32_bf16 v[66:69], v[10:13], v[18:21], v[66:69]
	v_mfma_f32_16x16x32_bf16 v[122:125], v[22:25], v[26:29], v[66:69]
	v_mfma_f32_16x16x32_bf16 v[66:69], v[62:65], v[18:21], v[70:73]
	v_mfma_f32_16x16x32_bf16 v[114:117], v[176:179], v[26:29], v[66:69]
	v_mfma_f32_16x16x32_bf16 v[66:69], v[10:13], v[102:105], v[74:77]
	v_mfma_f32_16x16x32_bf16 v[106:109], v[22:25], v[228:231], v[66:69]
	v_mfma_f32_16x16x32_bf16 v[66:69], v[62:65], v[102:105], v[78:81]
	v_mfma_f32_16x16x32_bf16 v[98:101], v[176:179], v[228:231], v[66:69]
	v_mfma_f32_16x16x32_bf16 v[66:69], v[10:13], v[232:235], v[82:85]
	v_mfma_f32_16x16x32_bf16 v[90:93], v[22:25], v[236:239], v[66:69]
	v_mfma_f32_16x16x32_bf16 v[66:69], v[62:65], v[232:235], v[86:89]
	v_mfma_f32_16x16x32_bf16 v[82:85], v[176:179], v[236:239], v[66:69]
	v_mfma_f32_16x16x32_bf16 v[66:69], v[10:13], v[240:243], v[212:215]
	v_mfma_f32_16x16x32_bf16 v[74:77], v[22:25], v[244:247], v[66:69]
	v_mfma_f32_16x16x32_bf16 v[66:69], v[62:65], v[240:243], v[94:97]
	v_mfma_f32_16x16x32_bf16 v[66:69], v[176:179], v[244:247], v[66:69]
	v_mfma_f32_16x16x32_bf16 v[70:73], v[192:195], v[18:21], v[216:219]
	v_mfma_f32_16x16x32_bf16 v[18:21], v[200:203], v[18:21], v[34:37]
	v_mfma_f32_16x16x32_bf16 v[118:121], v[220:223], v[26:29], v[18:21]
	v_mfma_f32_16x16x32_bf16 v[18:21], v[192:195], v[102:105], v[38:41]
	v_mfma_f32_16x16x32_bf16 v[110:113], v[196:199], v[228:231], v[18:21]
	v_mfma_f32_16x16x32_bf16 v[18:21], v[200:203], v[102:105], v[42:45]
	v_mfma_f32_16x16x32_bf16 v[102:105], v[220:223], v[228:231], v[18:21]
	v_mfma_f32_16x16x32_bf16 v[18:21], v[192:195], v[232:235], v[46:49]
	v_mfma_f32_16x16x32_bf16 v[94:97], v[196:199], v[236:239], v[18:21]
	v_mfma_f32_16x16x32_bf16 v[18:21], v[200:203], v[232:235], v[50:53]
	v_mfma_f32_16x16x32_bf16 v[86:89], v[220:223], v[236:239], v[18:21]
	v_mfma_f32_16x16x32_bf16 v[18:21], v[192:195], v[240:243], v[54:57]
	v_mfma_f32_16x16x32_bf16 v[78:81], v[196:199], v[244:247], v[18:21]
	v_mfma_f32_16x16x32_bf16 v[18:21], v[200:203], v[240:243], v[58:61]
	v_mfma_f32_16x16x32_bf16 v[126:129], v[196:199], v[26:29], v[70:73]
	v_mfma_f32_16x16x32_bf16 v[70:73], v[220:223], v[244:247], v[18:21]
	s_setprio 0
	s_barrier
	s_mov_b32 m0, s63
	s_nop 2
	v_lshl_add_u64 v[18:19], v[224:225], 0, s[20:21]
	s_add_u32 s6, s6, 0x10080
	ds_read_b128 v[38:41], v150 offset:49152
	ds_read_b128 v[46:49], v150 offset:50176
	ds_read_b128 v[212:215], v150 offset:51200
	ds_read_b128 v[216:219], v150 offset:52224
	ds_read_b128 v[228:231], v150 offset:53248
	ds_read_b128 v[232:235], v150 offset:54272
	ds_read_b128 v[236:239], v150 offset:55296
	ds_read_b128 v[240:243], v150 offset:56320
	global_load_lds_dwordx4 v[18:19], off
	v_lshl_add_u64 v[18:19], v[226:227], 0, s[20:21]
	s_mov_b32 m0, s61
	s_addc_u32 s7, s7, 0
	global_load_lds_dwordx4 v[18:19], off
	v_lshl_add_u64 v[18:19], s[6:7], 0, v[132:133]
	s_mov_b32 m0, s58
	s_nop 0
	global_load_lds_dwordx4 v[18:19], off
	v_lshl_add_u64 v[18:19], s[6:7], 0, v[136:137]
	s_mov_b32 m0, s59
	s_nop 0
	global_load_lds_dwordx4 v[18:19], off
	v_lshl_add_u64 v[18:19], v[248:249], 0, s[20:21]
	s_mov_b32 m0, s43
	s_nop 0
	global_load_lds_dwordx4 v[18:19], off
	v_lshl_add_u64 v[18:19], v[250:251], 0, s[20:21]
	s_mov_b32 m0, s44
	s_nop 0
	global_load_lds_dwordx4 v[18:19], off
	s_waitcnt vmcnt(8)
	s_waitcnt lgkmcnt(0)
	s_barrier
	s_setprio 1
	s_waitcnt lgkmcnt(0)
	v_mfma_f32_16x16x32_bf16 v[18:21], v[10:13], v[38:41], v[142:145]
	v_mfma_f32_16x16x32_bf16 v[58:61], v[22:25], v[46:49], v[18:21]
	v_mfma_f32_16x16x32_bf16 v[18:21], v[62:65], v[38:41], v[152:155]
	v_mfma_f32_16x16x32_bf16 v[50:53], v[176:179], v[46:49], v[18:21]
	v_mfma_f32_16x16x32_bf16 v[18:21], v[10:13], v[212:215], v[156:159]
	v_mfma_f32_16x16x32_bf16 v[42:45], v[22:25], v[216:219], v[18:21]
	v_mfma_f32_16x16x32_bf16 v[18:21], v[62:65], v[212:215], v[160:163]
	v_mfma_f32_16x16x32_bf16 v[34:37], v[176:179], v[216:219], v[18:21]
	v_mfma_f32_16x16x32_bf16 v[18:21], v[10:13], v[228:231], v[164:167]
	v_mfma_f32_16x16x32_bf16 v[2:5], v[10:13], v[236:239], v[2:5]
	v_mfma_f32_16x16x32_bf16 v[26:29], v[22:25], v[232:235], v[18:21]
	v_mfma_f32_16x16x32_bf16 v[18:21], v[62:65], v[228:231], v[168:171]
	v_mfma_f32_16x16x32_bf16 v[10:13], v[22:25], v[240:243], v[2:5]
	v_mfma_f32_16x16x32_bf16 v[2:5], v[62:65], v[236:239], v[6:9]
	v_mfma_f32_16x16x32_bf16 v[18:21], v[176:179], v[232:235], v[18:21]
	v_mfma_f32_16x16x32_bf16 v[2:5], v[176:179], v[240:243], v[2:5]
	v_mfma_f32_16x16x32_bf16 v[6:9], v[192:195], v[38:41], v[204:207]
	v_mfma_f32_16x16x32_bf16 v[62:65], v[196:199], v[46:49], v[6:9]
	v_mfma_f32_16x16x32_bf16 v[6:9], v[200:203], v[38:41], v[14:17]
	v_mfma_f32_16x16x32_bf16 v[54:57], v[220:223], v[46:49], v[6:9]
	v_mfma_f32_16x16x32_bf16 v[6:9], v[192:195], v[212:215], v[208:211]
	v_mfma_f32_16x16x32_bf16 v[46:49], v[196:199], v[216:219], v[6:9]
	v_mfma_f32_16x16x32_bf16 v[6:9], v[200:203], v[212:215], v[30:33]
	v_mfma_f32_16x16x32_bf16 v[38:41], v[220:223], v[216:219], v[6:9]
	v_mfma_f32_16x16x32_bf16 v[6:9], v[192:195], v[228:231], v[180:183]
	v_mfma_f32_16x16x32_bf16 v[30:33], v[196:199], v[232:235], v[6:9]
	v_mfma_f32_16x16x32_bf16 v[6:9], v[200:203], v[228:231], v[184:187]
	v_mfma_f32_16x16x32_bf16 v[22:25], v[220:223], v[232:235], v[6:9]
	v_mfma_f32_16x16x32_bf16 v[6:9], v[192:195], v[236:239], v[188:191]
	v_mfma_f32_16x16x32_bf16 v[14:17], v[196:199], v[240:243], v[6:9]
	v_mfma_f32_16x16x32_bf16 v[6:9], v[200:203], v[236:239], v[172:175]
	v_mfma_f32_16x16x32_bf16 v[6:9], v[220:223], v[240:243], v[6:9]
	s_setprio 0
	s_barrier
	s_andn2_b64 vcc, exec, s[22:23]
	s_cbranch_vccnz .LBB0_1525
	s_barrier

.LBB0_1631:
	v_add_u32_e32 v153, s44, v151
	ds_read_b128 v[154:157], v153
	ds_read_b128 v[158:161], v153 offset:1024
	ds_read_b128 v[162:165], v153 offset:2048
	ds_read_b128 v[166:169], v153 offset:3072
	v_add_u32_e32 v153, s45, v151
	s_add_u32 s46, s18, s30
	ds_read_b128 v[170:173], v153
	ds_read_b128 v[174:177], v153 offset:1024
	ds_read_b128 v[178:181], v153 offset:2048
	ds_read_b128 v[182:185], v153 offset:3072
	s_addc_u32 s47, s19, s31
	s_add_u32 s46, s46, 0x100
	s_addc_u32 s47, s47, 0
	s_add_u32 s55, s50, s30
	s_addc_u32 s56, s51, s31
	s_cmpk_eq_i32 s30, 0x700
	s_cselect_b32 s49, s25, s47
	s_cselect_b32 s48, s52, s46
	s_cselect_b32 s47, s23, s56
	s_cselect_b32 s46, s53, s55
	v_lshl_add_u64 v[218:219], v[146:147], 0, s[30:31]
	s_add_i32 m0, s33, 0xc000
	ds_read_b128 v[186:189], v152
	ds_read_b128 v[190:193], v152 offset:1024
	ds_read_b128 v[194:197], v152 offset:2048
	ds_read_b128 v[198:201], v152 offset:3072
	ds_read_b128 v[202:205], v152 offset:4096
	ds_read_b128 v[206:209], v152 offset:5120
	ds_read_b128 v[210:213], v152 offset:6144
	ds_read_b128 v[214:217], v152 offset:7168
	global_load_lds_dwordx4 v[218:219], off
	v_lshl_add_u64 v[218:219], v[148:149], 0, s[30:31]
	s_add_i32 m0, s33, 0xe000
	s_nop 0
	global_load_lds_dwordx4 v[218:219], off
	s_waitcnt vmcnt(8)
	s_waitcnt lgkmcnt(0)
	s_barrier
	s_setprio 1
	s_waitcnt lgkmcnt(0)
	v_mfma_f32_16x16x32_bf16 v[126:129], v[154:157], v[186:189], v[126:129]
	v_mfma_f32_16x16x32_bf16 v[122:125], v[162:165], v[186:189], v[122:125]
	v_mfma_f32_16x16x32_bf16 v[110:113], v[154:157], v[194:197], v[110:113]
	v_mfma_f32_16x16x32_bf16 v[106:109], v[162:165], v[194:197], v[106:109]
	v_mfma_f32_16x16x32_bf16 v[94:97], v[154:157], v[202:205], v[94:97]
	v_mfma_f32_16x16x32_bf16 v[90:93], v[162:165], v[202:205], v[90:93]
	v_mfma_f32_16x16x32_bf16 v[78:81], v[154:157], v[210:213], v[78:81]
	v_mfma_f32_16x16x32_bf16 v[74:77], v[162:165], v[210:213], v[74:77]
	v_mfma_f32_16x16x32_bf16 v[126:129], v[158:161], v[190:193], v[126:129]
	v_mfma_f32_16x16x32_bf16 v[122:125], v[166:169], v[190:193], v[122:125]
	v_mfma_f32_16x16x32_bf16 v[110:113], v[158:161], v[198:201], v[110:113]
	v_mfma_f32_16x16x32_bf16 v[106:109], v[166:169], v[198:201], v[106:109]
	v_mfma_f32_16x16x32_bf16 v[94:97], v[158:161], v[206:209], v[94:97]
	v_mfma_f32_16x16x32_bf16 v[90:93], v[166:169], v[206:209], v[90:93]
	v_mfma_f32_16x16x32_bf16 v[78:81], v[158:161], v[214:217], v[78:81]
	v_mfma_f32_16x16x32_bf16 v[74:77], v[166:169], v[214:217], v[74:77]
	v_mfma_f32_16x16x32_bf16 v[118:121], v[170:173], v[186:189], v[118:121]
	v_mfma_f32_16x16x32_bf16 v[114:117], v[178:181], v[186:189], v[114:117]
	v_mfma_f32_16x16x32_bf16 v[102:105], v[170:173], v[194:197], v[102:105]
	v_mfma_f32_16x16x32_bf16 v[98:101], v[178:181], v[194:197], v[98:101]
	v_mfma_f32_16x16x32_bf16 v[86:89], v[170:173], v[202:205], v[86:89]
	v_mfma_f32_16x16x32_bf16 v[82:85], v[178:181], v[202:205], v[82:85]
	v_mfma_f32_16x16x32_bf16 v[70:73], v[170:173], v[210:213], v[70:73]
	v_mfma_f32_16x16x32_bf16 v[66:69], v[178:181], v[210:213], v[66:69]
	v_mfma_f32_16x16x32_bf16 v[118:121], v[174:177], v[190:193], v[118:121]
	v_mfma_f32_16x16x32_bf16 v[114:117], v[182:185], v[190:193], v[114:117]
	v_mfma_f32_16x16x32_bf16 v[102:105], v[174:177], v[198:201], v[102:105]
	v_mfma_f32_16x16x32_bf16 v[98:101], v[182:185], v[198:201], v[98:101]
	v_mfma_f32_16x16x32_bf16 v[86:89], v[174:177], v[206:209], v[86:89]
	v_mfma_f32_16x16x32_bf16 v[82:85], v[182:185], v[206:209], v[82:85]
	v_mfma_f32_16x16x32_bf16 v[70:73], v[174:177], v[214:217], v[70:73]
	v_mfma_f32_16x16x32_bf16 v[66:69], v[182:185], v[214:217], v[66:69]
	s_setprio 0
	s_barrier
	s_add_i32 s55, s44, s13
	s_add_u32 s98, s46, s20
	s_addc_u32 s99, s47, s21
	s_mov_b32 m0, s55
	ds_read_b128 v[186:189], v152 offset:16384
	ds_read_b128 v[190:193], v152 offset:17408
	ds_read_b128 v[194:197], v152 offset:18432
	ds_read_b128 v[198:201], v152 offset:19456
	ds_read_b128 v[202:205], v152 offset:20480
	ds_read_b128 v[206:209], v152 offset:21504
	ds_read_b128 v[210:213], v152 offset:22528
	ds_read_b128 v[214:217], v152 offset:23552
	global_load_lds_dwordx4 v132, s[46:47]
	s_add_i32 m0, s55, 0x2000
	s_add_u32 s56, s46, 0x40000
	s_addc_u32 s57, s47, 0
	s_add_i32 s55, s45, s13
	global_load_lds_dwordx4 v136, s[46:47]
	s_mov_b32 m0, s55
	s_nop 0
	global_load_lds_dwordx4 v132, s[56:57]
	s_add_i32 m0, s55, 0x2000
	s_nop 0
	global_load_lds_dwordx4 v136, s[56:57]
	s_add_u32 s100, s48, s20
	s_addc_u32 s101, s49, s21
	s_mov_b32 m0, s33
	s_nop 0
	global_load_lds_dwordx4 v130, s[48:49]
	s_mov_b32 m0, s14
	s_nop 0
	global_load_lds_dwordx4 v134, s[48:49]
	s_waitcnt vmcnt(8)
	s_waitcnt lgkmcnt(0)
	s_barrier
	s_setprio 1
	s_waitcnt lgkmcnt(0)
	v_mfma_f32_16x16x32_bf16 v[62:65], v[154:157], v[186:189], v[62:65]
	v_mfma_f32_16x16x32_bf16 v[58:61], v[162:165], v[186:189], v[58:61]
	v_mfma_f32_16x16x32_bf16 v[46:49], v[154:157], v[194:197], v[46:49]
	v_mfma_f32_16x16x32_bf16 v[42:45], v[162:165], v[194:197], v[42:45]
	v_mfma_f32_16x16x32_bf16 v[30:33], v[154:157], v[202:205], v[30:33]
	v_mfma_f32_16x16x32_bf16 v[26:29], v[162:165], v[202:205], v[26:29]
	v_mfma_f32_16x16x32_bf16 v[14:17], v[154:157], v[210:213], v[14:17]
	v_mfma_f32_16x16x32_bf16 v[10:13], v[162:165], v[210:213], v[10:13]
	v_mfma_f32_16x16x32_bf16 v[62:65], v[158:161], v[190:193], v[62:65]
	v_mfma_f32_16x16x32_bf16 v[58:61], v[166:169], v[190:193], v[58:61]
	v_mfma_f32_16x16x32_bf16 v[46:49], v[158:161], v[198:201], v[46:49]
	v_mfma_f32_16x16x32_bf16 v[42:45], v[166:169], v[198:201], v[42:45]
	v_mfma_f32_16x16x32_bf16 v[30:33], v[158:161], v[206:209], v[30:33]
	v_mfma_f32_16x16x32_bf16 v[26:29], v[166:169], v[206:209], v[26:29]
	v_mfma_f32_16x16x32_bf16 v[14:17], v[158:161], v[214:217], v[14:17]
	v_mfma_f32_16x16x32_bf16 v[10:13], v[166:169], v[214:217], v[10:13]
	v_mfma_f32_16x16x32_bf16 v[54:57], v[170:173], v[186:189], v[54:57]
	v_mfma_f32_16x16x32_bf16 v[50:53], v[178:181], v[186:189], v[50:53]
	v_mfma_f32_16x16x32_bf16 v[38:41], v[170:173], v[194:197], v[38:41]
	v_mfma_f32_16x16x32_bf16 v[34:37], v[178:181], v[194:197], v[34:37]
	v_mfma_f32_16x16x32_bf16 v[22:25], v[170:173], v[202:205], v[22:25]
	v_mfma_f32_16x16x32_bf16 v[18:21], v[178:181], v[202:205], v[18:21]
	v_mfma_f32_16x16x32_bf16 v[6:9], v[170:173], v[210:213], v[6:9]
	v_mfma_f32_16x16x32_bf16 v[2:5], v[178:181], v[210:213], v[2:5]
	v_mfma_f32_16x16x32_bf16 v[54:57], v[174:177], v[190:193], v[54:57]
	v_mfma_f32_16x16x32_bf16 v[50:53], v[182:185], v[190:193], v[50:53]
	v_mfma_f32_16x16x32_bf16 v[38:41], v[174:177], v[198:201], v[38:41]
	v_mfma_f32_16x16x32_bf16 v[34:37], v[182:185], v[198:201], v[34:37]
	v_mfma_f32_16x16x32_bf16 v[22:25], v[174:177], v[206:209], v[22:25]
	v_mfma_f32_16x16x32_bf16 v[18:21], v[182:185], v[206:209], v[18:21]
	v_mfma_f32_16x16x32_bf16 v[6:9], v[174:177], v[214:217], v[6:9]
	v_mfma_f32_16x16x32_bf16 v[2:5], v[182:185], v[214:217], v[2:5]
	s_setprio 0
	s_barrier
	s_add_i32 s55, 0, 0x18000
	v_add_u32_e32 v153, s55, v151
	s_add_i32 s56, 0, 0x1c000
	ds_read_b128 v[154:157], v153
	ds_read_b128 v[158:161], v153 offset:1024
	ds_read_b128 v[162:165], v153 offset:2048
	ds_read_b128 v[166:169], v153 offset:3072
	v_add_u32_e32 v153, s56, v151
	ds_read_b128 v[170:173], v153
	ds_read_b128 v[174:177], v153 offset:1024
	ds_read_b128 v[178:181], v153 offset:2048
	ds_read_b128 v[182:185], v153 offset:3072
	s_add_u32 s48, s48, 0x40000
	s_addc_u32 s49, s49, 0
	s_mov_b32 m0, s15
	ds_read_b128 v[186:189], v152 offset:32768
	ds_read_b128 v[190:193], v152 offset:33792
	ds_read_b128 v[194:197], v152 offset:34816
	ds_read_b128 v[198:201], v152 offset:35840
	ds_read_b128 v[202:205], v152 offset:36864
	ds_read_b128 v[206:209], v152 offset:37888
	ds_read_b128 v[210:213], v152 offset:38912
	ds_read_b128 v[214:217], v152 offset:39936
	global_load_lds_dwordx4 v130, s[48:49]
	s_mov_b32 m0, s40
	s_nop 0
	global_load_lds_dwordx4 v134, s[48:49]
	s_waitcnt vmcnt(8)
	s_waitcnt lgkmcnt(0)
	s_barrier
	s_setprio 1
	s_waitcnt lgkmcnt(0)
	v_mfma_f32_16x16x32_bf16 v[126:129], v[154:157], v[186:189], v[126:129]
	v_mfma_f32_16x16x32_bf16 v[122:125], v[162:165], v[186:189], v[122:125]
	v_mfma_f32_16x16x32_bf16 v[110:113], v[154:157], v[194:197], v[110:113]
	v_mfma_f32_16x16x32_bf16 v[106:109], v[162:165], v[194:197], v[106:109]
	v_mfma_f32_16x16x32_bf16 v[94:97], v[154:157], v[202:205], v[94:97]
	v_mfma_f32_16x16x32_bf16 v[90:93], v[162:165], v[202:205], v[90:93]
	v_mfma_f32_16x16x32_bf16 v[78:81], v[154:157], v[210:213], v[78:81]
	v_mfma_f32_16x16x32_bf16 v[74:77], v[162:165], v[210:213], v[74:77]
	v_mfma_f32_16x16x32_bf16 v[126:129], v[158:161], v[190:193], v[126:129]
	v_mfma_f32_16x16x32_bf16 v[122:125], v[166:169], v[190:193], v[122:125]
	v_mfma_f32_16x16x32_bf16 v[110:113], v[158:161], v[198:201], v[110:113]
	v_mfma_f32_16x16x32_bf16 v[106:109], v[166:169], v[198:201], v[106:109]
	v_mfma_f32_16x16x32_bf16 v[94:97], v[158:161], v[206:209], v[94:97]
	v_mfma_f32_16x16x32_bf16 v[90:93], v[166:169], v[206:209], v[90:93]
	v_mfma_f32_16x16x32_bf16 v[78:81], v[158:161], v[214:217], v[78:81]
	v_mfma_f32_16x16x32_bf16 v[74:77], v[166:169], v[214:217], v[74:77]
	v_mfma_f32_16x16x32_bf16 v[118:121], v[170:173], v[186:189], v[118:121]
	v_mfma_f32_16x16x32_bf16 v[114:117], v[178:181], v[186:189], v[114:117]
	v_mfma_f32_16x16x32_bf16 v[102:105], v[170:173], v[194:197], v[102:105]
	v_mfma_f32_16x16x32_bf16 v[98:101], v[178:181], v[194:197], v[98:101]
	v_mfma_f32_16x16x32_bf16 v[86:89], v[170:173], v[202:205], v[86:89]
	v_mfma_f32_16x16x32_bf16 v[82:85], v[178:181], v[202:205], v[82:85]
	v_mfma_f32_16x16x32_bf16 v[70:73], v[170:173], v[210:213], v[70:73]
	v_mfma_f32_16x16x32_bf16 v[66:69], v[178:181], v[210:213], v[66:69]
	v_mfma_f32_16x16x32_bf16 v[118:121], v[174:177], v[190:193], v[118:121]
	v_mfma_f32_16x16x32_bf16 v[114:117], v[182:185], v[190:193], v[114:117]
	v_mfma_f32_16x16x32_bf16 v[102:105], v[174:177], v[198:201], v[102:105]
	v_mfma_f32_16x16x32_bf16 v[98:101], v[182:185], v[198:201], v[98:101]
	v_mfma_f32_16x16x32_bf16 v[86:89], v[174:177], v[206:209], v[86:89]
	v_mfma_f32_16x16x32_bf16 v[82:85], v[182:185], v[206:209], v[82:85]
	v_mfma_f32_16x16x32_bf16 v[70:73], v[174:177], v[214:217], v[70:73]
	v_mfma_f32_16x16x32_bf16 v[66:69], v[182:185], v[214:217], v[66:69]
	s_setprio 0
	s_barrier
	s_add_i32 s48, s55, s13
	s_mov_b32 m0, s48
	ds_read_b128 v[186:189], v152 offset:49152
	ds_read_b128 v[190:193], v152 offset:50176
	ds_read_b128 v[194:197], v152 offset:51200
	ds_read_b128 v[198:201], v152 offset:52224
	ds_read_b128 v[202:205], v152 offset:53248
	ds_read_b128 v[206:209], v152 offset:54272
	ds_read_b128 v[210:213], v152 offset:55296
	ds_read_b128 v[214:217], v152 offset:56320
	global_load_lds_dwordx4 v132, s[98:99]
	s_add_i32 m0, s48, 0x2000
	s_add_u32 s46, s46, 0x40080
	s_addc_u32 s47, s47, 0
	s_add_i32 s48, s56, s13
	global_load_lds_dwordx4 v136, s[98:99]
	s_mov_b32 m0, s48
	s_nop 0
	global_load_lds_dwordx4 v132, s[46:47]
	s_add_i32 m0, s48, 0x2000
	s_nop 0
	global_load_lds_dwordx4 v136, s[46:47]
	s_mov_b32 m0, s42
	s_nop 0
	global_load_lds_dwordx4 v130, s[100:101]
	s_mov_b32 m0, s43
	s_nop 0
	global_load_lds_dwordx4 v134, s[100:101]
	s_waitcnt vmcnt(8)
	s_waitcnt lgkmcnt(0)
	s_barrier
	s_setprio 1
	s_waitcnt lgkmcnt(0)
	v_mfma_f32_16x16x32_bf16 v[62:65], v[154:157], v[186:189], v[62:65]
	v_mfma_f32_16x16x32_bf16 v[58:61], v[162:165], v[186:189], v[58:61]
	v_mfma_f32_16x16x32_bf16 v[46:49], v[154:157], v[194:197], v[46:49]
	v_mfma_f32_16x16x32_bf16 v[42:45], v[162:165], v[194:197], v[42:45]
	v_mfma_f32_16x16x32_bf16 v[30:33], v[154:157], v[202:205], v[30:33]
	v_mfma_f32_16x16x32_bf16 v[26:29], v[162:165], v[202:205], v[26:29]
	v_mfma_f32_16x16x32_bf16 v[14:17], v[154:157], v[210:213], v[14:17]
	v_mfma_f32_16x16x32_bf16 v[10:13], v[162:165], v[210:213], v[10:13]
	v_mfma_f32_16x16x32_bf16 v[62:65], v[158:161], v[190:193], v[62:65]
	v_mfma_f32_16x16x32_bf16 v[58:61], v[166:169], v[190:193], v[58:61]
	v_mfma_f32_16x16x32_bf16 v[46:49], v[158:161], v[198:201], v[46:49]
	v_mfma_f32_16x16x32_bf16 v[42:45], v[166:169], v[198:201], v[42:45]
	v_mfma_f32_16x16x32_bf16 v[30:33], v[158:161], v[206:209], v[30:33]
	v_mfma_f32_16x16x32_bf16 v[26:29], v[166:169], v[206:209], v[26:29]
	v_mfma_f32_16x16x32_bf16 v[14:17], v[158:161], v[214:217], v[14:17]
	v_mfma_f32_16x16x32_bf16 v[10:13], v[166:169], v[214:217], v[10:13]
	v_mfma_f32_16x16x32_bf16 v[54:57], v[170:173], v[186:189], v[54:57]
	v_mfma_f32_16x16x32_bf16 v[50:53], v[178:181], v[186:189], v[50:53]
	v_mfma_f32_16x16x32_bf16 v[38:41], v[170:173], v[194:197], v[38:41]
	v_mfma_f32_16x16x32_bf16 v[34:37], v[178:181], v[194:197], v[34:37]
	v_mfma_f32_16x16x32_bf16 v[22:25], v[170:173], v[202:205], v[22:25]
	v_mfma_f32_16x16x32_bf16 v[18:21], v[178:181], v[202:205], v[18:21]
	v_mfma_f32_16x16x32_bf16 v[6:9], v[170:173], v[210:213], v[6:9]
	v_mfma_f32_16x16x32_bf16 v[2:5], v[178:181], v[210:213], v[2:5]
	v_mfma_f32_16x16x32_bf16 v[54:57], v[174:177], v[190:193], v[54:57]
	v_mfma_f32_16x16x32_bf16 v[50:53], v[182:185], v[190:193], v[50:53]
	v_mfma_f32_16x16x32_bf16 v[38:41], v[174:177], v[198:201], v[38:41]
	v_mfma_f32_16x16x32_bf16 v[34:37], v[182:185], v[198:201], v[34:37]
	v_mfma_f32_16x16x32_bf16 v[22:25], v[174:177], v[206:209], v[22:25]
	v_mfma_f32_16x16x32_bf16 v[18:21], v[182:185], v[206:209], v[18:21]
	v_mfma_f32_16x16x32_bf16 v[6:9], v[174:177], v[214:217], v[6:9]
	v_mfma_f32_16x16x32_bf16 v[2:5], v[182:185], v[214:217], v[2:5]
	s_setprio 0
	s_barrier
	s_add_i32 s54, s54, 2
	s_add_u32 s30, s30, 0x100
	s_addc_u32 s31, s31, 0
	s_cmp_gt_u32 s54, 13
	s_cbranch_scc0 .LBB0_1631
	s_add_u32 s30, s50, 0xffffff00
	s_addc_u32 s31, s51, -1
	s_andn2_b64 vcc, exec, s[6:7]
	s_cbranch_vccnz .LBB0_1634
	v_mov_b32_e32 v2, 0
	s_mov_b32 s10, s22
	s_mov_b32 s16, s24
	s_mov_b64 s[18:19], s[28:29]
	s_mov_b32 s41, s2
	v_mov_b32_e32 v3, v2
	v_mov_b32_e32 v4, v2
	v_mov_b32_e32 v5, v2
	v_mov_b32_e32 v6, v2
	v_mov_b32_e32 v7, v2
	v_mov_b32_e32 v8, v2
	v_mov_b32_e32 v9, v2
	v_mov_b32_e32 v18, v2
	v_mov_b32_e32 v19, v2
	v_mov_b32_e32 v20, v2
	v_mov_b32_e32 v21, v2
	v_mov_b32_e32 v22, v2
	v_mov_b32_e32 v23, v2
	v_mov_b32_e32 v24, v2
	v_mov_b32_e32 v25, v2
	v_mov_b32_e32 v34, v2
	v_mov_b32_e32 v35, v2
	v_mov_b32_e32 v36, v2
	v_mov_b32_e32 v37, v2
	v_mov_b32_e32 v38, v2
	v_mov_b32_e32 v39, v2
	v_mov_b32_e32 v40, v2
	v_mov_b32_e32 v41, v2
	v_mov_b32_e32 v50, v2
	v_mov_b32_e32 v51, v2
	v_mov_b32_e32 v52, v2
	v_mov_b32_e32 v53, v2
	v_mov_b32_e32 v54, v2
	v_mov_b32_e32 v55, v2
	v_mov_b32_e32 v56, v2
	v_mov_b32_e32 v57, v2
	v_mov_b32_e32 v10, v2
	v_mov_b32_e32 v11, v2
	v_mov_b32_e32 v12, v2
	v_mov_b32_e32 v13, v2
	v_mov_b32_e32 v14, v2
	v_mov_b32_e32 v15, v2
	v_mov_b32_e32 v16, v2
	v_mov_b32_e32 v17, v2
	v_mov_b32_e32 v26, v2
	v_mov_b32_e32 v27, v2
	v_mov_b32_e32 v28, v2
	v_mov_b32_e32 v29, v2
	v_mov_b32_e32 v30, v2
	v_mov_b32_e32 v31, v2
	v_mov_b32_e32 v32, v2
	v_mov_b32_e32 v33, v2
	v_mov_b32_e32 v42, v2
	v_mov_b32_e32 v43, v2
	v_mov_b32_e32 v44, v2
	v_mov_b32_e32 v45, v2
	v_mov_b32_e32 v46, v2
	v_mov_b32_e32 v47, v2
	v_mov_b32_e32 v48, v2
	v_mov_b32_e32 v49, v2
	v_mov_b32_e32 v58, v2
	v_mov_b32_e32 v59, v2
	v_mov_b32_e32 v60, v2
	v_mov_b32_e32 v61, v2
	v_mov_b32_e32 v62, v2
	v_mov_b32_e32 v63, v2
	v_mov_b32_e32 v64, v2
	v_mov_b32_e32 v65, v2
	v_mov_b32_e32 v66, v2
	v_mov_b32_e32 v67, v2
	v_mov_b32_e32 v68, v2
	v_mov_b32_e32 v69, v2
	v_mov_b32_e32 v70, v2
	v_mov_b32_e32 v71, v2
	v_mov_b32_e32 v72, v2
	v_mov_b32_e32 v73, v2
	v_mov_b32_e32 v82, v2
	v_mov_b32_e32 v83, v2
	v_mov_b32_e32 v84, v2
	v_mov_b32_e32 v85, v2
	v_mov_b32_e32 v86, v2
	v_mov_b32_e32 v87, v2
	v_mov_b32_e32 v88, v2
	v_mov_b32_e32 v89, v2
	v_mov_b32_e32 v98, v2
	v_mov_b32_e32 v99, v2
	v_mov_b32_e32 v100, v2
	v_mov_b32_e32 v101, v2
	v_mov_b32_e32 v102, v2
	v_mov_b32_e32 v103, v2
	v_mov_b32_e32 v104, v2
	v_mov_b32_e32 v105, v2
	v_mov_b32_e32 v114, v2
	v_mov_b32_e32 v115, v2
	v_mov_b32_e32 v116, v2
	v_mov_b32_e32 v117, v2
	v_mov_b32_e32 v118, v2
	v_mov_b32_e32 v119, v2
	v_mov_b32_e32 v120, v2
	v_mov_b32_e32 v121, v2
	v_mov_b32_e32 v74, v2
	v_mov_b32_e32 v75, v2
	v_mov_b32_e32 v76, v2
	v_mov_b32_e32 v77, v2
	v_mov_b32_e32 v78, v2
	v_mov_b32_e32 v79, v2
	v_mov_b32_e32 v80, v2
	v_mov_b32_e32 v81, v2
	v_mov_b32_e32 v90, v2
	v_mov_b32_e32 v91, v2
	v_mov_b32_e32 v92, v2
	v_mov_b32_e32 v93, v2
	v_mov_b32_e32 v94, v2
	v_mov_b32_e32 v95, v2
	v_mov_b32_e32 v96, v2
	v_mov_b32_e32 v97, v2
	v_mov_b32_e32 v106, v2
	v_mov_b32_e32 v107, v2
	v_mov_b32_e32 v108, v2
	v_mov_b32_e32 v109, v2
	v_mov_b32_e32 v110, v2
	v_mov_b32_e32 v111, v2
	v_mov_b32_e32 v112, v2
	v_mov_b32_e32 v113, v2
	v_mov_b32_e32 v122, v2
	v_mov_b32_e32 v123, v2
	v_mov_b32_e32 v124, v2
	v_mov_b32_e32 v125, v2
	v_mov_b32_e32 v126, v2
	v_mov_b32_e32 v127, v2
	v_mov_b32_e32 v128, v2
	v_mov_b32_e32 v129, v2
	s_andn2_b64 vcc, exec, s[4:5]
	s_cbranch_vccnz .LBB0_1635
	s_branch .LBB0_1636

.LBB0_1765:
	s_waitcnt lgkmcnt(0)
	s_barrier
	s_setprio 1
	s_waitcnt lgkmcnt(0)
	v_mfma_f32_16x16x32_bf16 v[66:69], v[150:153], v[190:193], v[66:69]
	v_mfma_f32_16x16x32_bf16 v[58:61], v[158:161], v[190:193], v[58:61]
	v_mfma_f32_16x16x32_bf16 v[50:53], v[150:153], v[182:185], v[50:53]
	v_mfma_f32_16x16x32_bf16 v[42:45], v[158:161], v[182:185], v[42:45]
	v_mfma_f32_16x16x32_bf16 v[34:37], v[150:153], v[174:177], v[34:37]
	v_mfma_f32_16x16x32_bf16 v[26:29], v[158:161], v[174:177], v[26:29]
	v_mfma_f32_16x16x32_bf16 v[18:21], v[150:153], v[166:169], v[18:21]
	v_mfma_f32_16x16x32_bf16 v[10:13], v[158:161], v[166:169], v[10:13]
	v_mfma_f32_16x16x32_bf16 v[66:69], v[154:157], v[194:197], v[66:69]
	v_mfma_f32_16x16x32_bf16 v[58:61], v[162:165], v[194:197], v[58:61]
	v_mfma_f32_16x16x32_bf16 v[50:53], v[154:157], v[186:189], v[50:53]
	v_mfma_f32_16x16x32_bf16 v[42:45], v[162:165], v[186:189], v[42:45]
	v_mfma_f32_16x16x32_bf16 v[34:37], v[154:157], v[178:181], v[34:37]
	v_mfma_f32_16x16x32_bf16 v[26:29], v[162:165], v[178:181], v[26:29]
	v_mfma_f32_16x16x32_bf16 v[18:21], v[154:157], v[170:173], v[18:21]
	v_mfma_f32_16x16x32_bf16 v[10:13], v[162:165], v[170:173], v[10:13]
	v_mfma_f32_16x16x32_bf16 v[62:65], v[134:137], v[190:193], v[62:65]
	v_mfma_f32_16x16x32_bf16 v[54:57], v[142:145], v[190:193], v[54:57]
	v_mfma_f32_16x16x32_bf16 v[46:49], v[134:137], v[182:185], v[46:49]
	v_mfma_f32_16x16x32_bf16 v[38:41], v[142:145], v[182:185], v[38:41]
	v_mfma_f32_16x16x32_bf16 v[30:33], v[134:137], v[174:177], v[30:33]
	v_mfma_f32_16x16x32_bf16 v[22:25], v[142:145], v[174:177], v[22:25]
	v_mfma_f32_16x16x32_bf16 v[14:17], v[134:137], v[166:169], v[14:17]
	v_mfma_f32_16x16x32_bf16 v[6:9], v[142:145], v[166:169], v[6:9]
	v_mfma_f32_16x16x32_bf16 v[62:65], v[138:141], v[194:197], v[62:65]
	v_mfma_f32_16x16x32_bf16 v[54:57], v[146:149], v[194:197], v[54:57]
	v_mfma_f32_16x16x32_bf16 v[46:49], v[138:141], v[186:189], v[46:49]
	v_mfma_f32_16x16x32_bf16 v[38:41], v[146:149], v[186:189], v[38:41]
	v_mfma_f32_16x16x32_bf16 v[30:33], v[138:141], v[178:181], v[30:33]
	v_mfma_f32_16x16x32_bf16 v[22:25], v[146:149], v[178:181], v[22:25]
	v_mfma_f32_16x16x32_bf16 v[14:17], v[138:141], v[170:173], v[14:17]
	v_mfma_f32_16x16x32_bf16 v[6:9], v[146:149], v[170:173], v[6:9]
	s_setprio 0
	s_barrier
	s_add_i32 s61, s61, 2
	s_add_u32 s28, s28, 0x100
	s_addc_u32 s29, s29, 0
	s_add_u32 s59, s59, 0x100
	s_addc_u32 s60, s60, 0
	s_cmp_gt_u32 s61, 13
	s_cbranch_scc1 .LBB0_1771

.LBB0_1768:
	v_add_u32_e32 v146, s53, v217
	v_add_u32_e32 v162, s54, v217
	ds_read_b128 v[134:137], v146
	ds_read_b128 v[138:141], v146 offset:1024
	ds_read_b128 v[142:145], v146 offset:2048
	ds_read_b128 v[146:149], v146 offset:3072
	ds_read_b128 v[150:153], v162
	ds_read_b128 v[154:157], v162 offset:1024
	ds_read_b128 v[158:161], v162 offset:2048
	ds_read_b128 v[162:165], v162 offset:3072
	s_add_u32 s48, s28, 0xfffc0080
	s_addc_u32 s49, s29, -1
	s_and_b64 s[46:47], s[30:31], exec
	s_cselect_b32 s49, s23, s49
	s_cselect_b32 s48, s56, s48
	s_cselect_b32 s47, s57, s60
	s_cselect_b32 s46, s58, s59
	s_add_i32 m0, s40, 0xc000
	ds_read_b128 v[166:169], v220
	ds_read_b128 v[170:173], v220 offset:1024
	ds_read_b128 v[174:177], v220 offset:2048
	ds_read_b128 v[178:181], v220 offset:3072
	ds_read_b128 v[182:185], v220 offset:4096
	ds_read_b128 v[186:189], v220 offset:5120
	ds_read_b128 v[190:193], v220 offset:6144
	ds_read_b128 v[194:197], v220 offset:7168
	global_load_lds_dwordx4 v206, s[28:29]
	s_add_i32 m0, s40, 0xe000
	s_nop 0
	global_load_lds_dwordx4 v208, s[28:29]
	s_waitcnt vmcnt(8)
	s_waitcnt lgkmcnt(0)
	s_barrier
	s_setprio 1
	s_waitcnt lgkmcnt(0)
	v_mfma_f32_16x16x32_bf16 v[130:133], v[134:137], v[166:169], v[130:133]
	v_mfma_f32_16x16x32_bf16 v[122:125], v[142:145], v[166:169], v[122:125]
	v_mfma_f32_16x16x32_bf16 v[114:117], v[134:137], v[174:177], v[114:117]
	v_mfma_f32_16x16x32_bf16 v[106:109], v[142:145], v[174:177], v[106:109]
	v_mfma_f32_16x16x32_bf16 v[98:101], v[134:137], v[182:185], v[98:101]
	v_mfma_f32_16x16x32_bf16 v[90:93], v[142:145], v[182:185], v[90:93]
	v_mfma_f32_16x16x32_bf16 v[82:85], v[134:137], v[190:193], v[82:85]
	v_mfma_f32_16x16x32_bf16 v[74:77], v[142:145], v[190:193], v[74:77]
	v_mfma_f32_16x16x32_bf16 v[130:133], v[138:141], v[170:173], v[130:133]
	v_mfma_f32_16x16x32_bf16 v[122:125], v[146:149], v[170:173], v[122:125]
	v_mfma_f32_16x16x32_bf16 v[114:117], v[138:141], v[178:181], v[114:117]
	v_mfma_f32_16x16x32_bf16 v[106:109], v[146:149], v[178:181], v[106:109]
	v_mfma_f32_16x16x32_bf16 v[98:101], v[138:141], v[186:189], v[98:101]
	v_mfma_f32_16x16x32_bf16 v[90:93], v[146:149], v[186:189], v[90:93]
	v_mfma_f32_16x16x32_bf16 v[82:85], v[138:141], v[194:197], v[82:85]
	v_mfma_f32_16x16x32_bf16 v[74:77], v[146:149], v[194:197], v[74:77]
	v_mfma_f32_16x16x32_bf16 v[126:129], v[150:153], v[166:169], v[126:129]
	v_mfma_f32_16x16x32_bf16 v[118:121], v[158:161], v[166:169], v[118:121]
	v_mfma_f32_16x16x32_bf16 v[110:113], v[150:153], v[174:177], v[110:113]
	v_mfma_f32_16x16x32_bf16 v[102:105], v[158:161], v[174:177], v[102:105]
	v_mfma_f32_16x16x32_bf16 v[94:97], v[150:153], v[182:185], v[94:97]
	v_mfma_f32_16x16x32_bf16 v[86:89], v[158:161], v[182:185], v[86:89]
	v_mfma_f32_16x16x32_bf16 v[78:81], v[150:153], v[190:193], v[78:81]
	v_mfma_f32_16x16x32_bf16 v[70:73], v[158:161], v[190:193], v[70:73]
	v_mfma_f32_16x16x32_bf16 v[126:129], v[154:157], v[170:173], v[126:129]
	v_mfma_f32_16x16x32_bf16 v[118:121], v[162:165], v[170:173], v[118:121]
	v_mfma_f32_16x16x32_bf16 v[110:113], v[154:157], v[178:181], v[110:113]
	v_mfma_f32_16x16x32_bf16 v[102:105], v[162:165], v[178:181], v[102:105]
	v_mfma_f32_16x16x32_bf16 v[94:97], v[154:157], v[186:189], v[94:97]
	v_mfma_f32_16x16x32_bf16 v[86:89], v[162:165], v[186:189], v[86:89]
	v_mfma_f32_16x16x32_bf16 v[78:81], v[154:157], v[194:197], v[78:81]
	v_mfma_f32_16x16x32_bf16 v[70:73], v[162:165], v[194:197], v[70:73]
	s_setprio 0
	s_barrier
	s_add_i32 s62, s53, s12
	s_add_u32 s98, s46, s16
	s_addc_u32 s99, s47, s17
	s_mov_b32 m0, s62
	ds_read_b128 v[166:169], v220 offset:16384
	ds_read_b128 v[170:173], v220 offset:17408
	ds_read_b128 v[174:177], v220 offset:18432
	ds_read_b128 v[178:181], v220 offset:19456
	ds_read_b128 v[182:185], v220 offset:20480
	ds_read_b128 v[186:189], v220 offset:21504
	ds_read_b128 v[190:193], v220 offset:22528
	ds_read_b128 v[194:197], v220 offset:23552
	global_load_lds_dwordx4 v202, s[46:47]
	s_add_i32 m0, s62, 0x2000
	s_add_u32 s62, s46, 0x40000
	s_addc_u32 s63, s47, 0
	s_add_i32 s64, s54, s12
	global_load_lds_dwordx4 v198, s[46:47]
	s_mov_b32 m0, s64
	s_nop 0
	global_load_lds_dwordx4 v202, s[62:63]
	s_add_i32 m0, s64, 0x2000
	s_nop 0
	global_load_lds_dwordx4 v198, s[62:63]
	s_add_u32 s100, s48, s16
	s_addc_u32 s101, s49, s17
	s_mov_b32 m0, s40
	s_nop 0
	global_load_lds_dwordx4 v204, s[48:49]
	s_mov_b32 m0, s41
	s_nop 0
	global_load_lds_dwordx4 v200, s[48:49]
	s_waitcnt vmcnt(8)
	s_waitcnt lgkmcnt(0)
	s_barrier
	s_setprio 1
	s_waitcnt lgkmcnt(0)
	v_mfma_f32_16x16x32_bf16 v[66:69], v[134:137], v[166:169], v[66:69]
	v_mfma_f32_16x16x32_bf16 v[58:61], v[142:145], v[166:169], v[58:61]
	v_mfma_f32_16x16x32_bf16 v[50:53], v[134:137], v[174:177], v[50:53]
	v_mfma_f32_16x16x32_bf16 v[42:45], v[142:145], v[174:177], v[42:45]
	v_mfma_f32_16x16x32_bf16 v[34:37], v[134:137], v[182:185], v[34:37]
	v_mfma_f32_16x16x32_bf16 v[26:29], v[142:145], v[182:185], v[26:29]
	v_mfma_f32_16x16x32_bf16 v[18:21], v[134:137], v[190:193], v[18:21]
	v_mfma_f32_16x16x32_bf16 v[10:13], v[142:145], v[190:193], v[10:13]
	v_mfma_f32_16x16x32_bf16 v[66:69], v[138:141], v[170:173], v[66:69]
	v_mfma_f32_16x16x32_bf16 v[58:61], v[146:149], v[170:173], v[58:61]
	v_mfma_f32_16x16x32_bf16 v[50:53], v[138:141], v[178:181], v[50:53]
	v_mfma_f32_16x16x32_bf16 v[42:45], v[146:149], v[178:181], v[42:45]
	v_mfma_f32_16x16x32_bf16 v[34:37], v[138:141], v[186:189], v[34:37]
	v_mfma_f32_16x16x32_bf16 v[26:29], v[146:149], v[186:189], v[26:29]
	v_mfma_f32_16x16x32_bf16 v[18:21], v[138:141], v[194:197], v[18:21]
	v_mfma_f32_16x16x32_bf16 v[10:13], v[146:149], v[194:197], v[10:13]
	v_mfma_f32_16x16x32_bf16 v[62:65], v[150:153], v[166:169], v[62:65]
	v_mfma_f32_16x16x32_bf16 v[54:57], v[158:161], v[166:169], v[54:57]
	v_mfma_f32_16x16x32_bf16 v[46:49], v[150:153], v[174:177], v[46:49]
	v_mfma_f32_16x16x32_bf16 v[38:41], v[158:161], v[174:177], v[38:41]
	v_mfma_f32_16x16x32_bf16 v[30:33], v[150:153], v[182:185], v[30:33]
	v_mfma_f32_16x16x32_bf16 v[22:25], v[158:161], v[182:185], v[22:25]
	v_mfma_f32_16x16x32_bf16 v[14:17], v[150:153], v[190:193], v[14:17]
	v_mfma_f32_16x16x32_bf16 v[6:9], v[158:161], v[190:193], v[6:9]
	v_mfma_f32_16x16x32_bf16 v[62:65], v[154:157], v[170:173], v[62:65]
	v_mfma_f32_16x16x32_bf16 v[54:57], v[162:165], v[170:173], v[54:57]
	v_mfma_f32_16x16x32_bf16 v[46:49], v[154:157], v[178:181], v[46:49]
	v_mfma_f32_16x16x32_bf16 v[38:41], v[162:165], v[178:181], v[38:41]
	v_mfma_f32_16x16x32_bf16 v[30:33], v[154:157], v[186:189], v[30:33]
	v_mfma_f32_16x16x32_bf16 v[22:25], v[162:165], v[186:189], v[22:25]
	v_mfma_f32_16x16x32_bf16 v[14:17], v[154:157], v[194:197], v[14:17]
	v_mfma_f32_16x16x32_bf16 v[6:9], v[162:165], v[194:197], v[6:9]
	s_setprio 0
	s_barrier
	s_add_i32 s62, 0, 0x18000
	s_add_i32 s63, 0, 0x1c000
	v_add_u32_e32 v134, s62, v217
	v_add_u32_e32 v146, s63, v217
	ds_read_b128 v[150:153], v134
	ds_read_b128 v[154:157], v134 offset:1024
	ds_read_b128 v[158:161], v134 offset:2048
	ds_read_b128 v[162:165], v134 offset:3072
	ds_read_b128 v[134:137], v146
	ds_read_b128 v[138:141], v146 offset:1024
	ds_read_b128 v[142:145], v146 offset:2048
	ds_read_b128 v[146:149], v146 offset:3072
	s_add_u32 s48, s48, 0x40000
	s_addc_u32 s49, s49, 0
	s_mov_b32 m0, s42
	ds_read_b128 v[166:169], v220 offset:32768
	ds_read_b128 v[170:173], v220 offset:33792
	ds_read_b128 v[174:177], v220 offset:34816
	ds_read_b128 v[178:181], v220 offset:35840
	ds_read_b128 v[182:185], v220 offset:36864
	ds_read_b128 v[186:189], v220 offset:37888
	ds_read_b128 v[190:193], v220 offset:38912
	ds_read_b128 v[194:197], v220 offset:39936
	global_load_lds_dwordx4 v204, s[48:49]
	s_mov_b32 m0, s43
	s_nop 0
	global_load_lds_dwordx4 v200, s[48:49]
	s_waitcnt vmcnt(8)
	s_waitcnt lgkmcnt(0)
	s_barrier
	s_setprio 1
	s_waitcnt lgkmcnt(0)
	v_mfma_f32_16x16x32_bf16 v[130:133], v[150:153], v[166:169], v[130:133]
	v_mfma_f32_16x16x32_bf16 v[122:125], v[158:161], v[166:169], v[122:125]
	v_mfma_f32_16x16x32_bf16 v[114:117], v[150:153], v[174:177], v[114:117]
	v_mfma_f32_16x16x32_bf16 v[106:109], v[158:161], v[174:177], v[106:109]
	v_mfma_f32_16x16x32_bf16 v[98:101], v[150:153], v[182:185], v[98:101]
	v_mfma_f32_16x16x32_bf16 v[90:93], v[158:161], v[182:185], v[90:93]
	v_mfma_f32_16x16x32_bf16 v[82:85], v[150:153], v[190:193], v[82:85]
	v_mfma_f32_16x16x32_bf16 v[74:77], v[158:161], v[190:193], v[74:77]
	v_mfma_f32_16x16x32_bf16 v[130:133], v[154:157], v[170:173], v[130:133]
	v_mfma_f32_16x16x32_bf16 v[122:125], v[162:165], v[170:173], v[122:125]
	v_mfma_f32_16x16x32_bf16 v[114:117], v[154:157], v[178:181], v[114:117]
	v_mfma_f32_16x16x32_bf16 v[106:109], v[162:165], v[178:181], v[106:109]
	v_mfma_f32_16x16x32_bf16 v[98:101], v[154:157], v[186:189], v[98:101]
	v_mfma_f32_16x16x32_bf16 v[90:93], v[162:165], v[186:189], v[90:93]
	v_mfma_f32_16x16x32_bf16 v[82:85], v[154:157], v[194:197], v[82:85]
	v_mfma_f32_16x16x32_bf16 v[74:77], v[162:165], v[194:197], v[74:77]
	v_mfma_f32_16x16x32_bf16 v[126:129], v[134:137], v[166:169], v[126:129]
	v_mfma_f32_16x16x32_bf16 v[118:121], v[142:145], v[166:169], v[118:121]
	v_mfma_f32_16x16x32_bf16 v[110:113], v[134:137], v[174:177], v[110:113]
	v_mfma_f32_16x16x32_bf16 v[102:105], v[142:145], v[174:177], v[102:105]
	v_mfma_f32_16x16x32_bf16 v[94:97], v[134:137], v[182:185], v[94:97]
	v_mfma_f32_16x16x32_bf16 v[86:89], v[142:145], v[182:185], v[86:89]
	v_mfma_f32_16x16x32_bf16 v[78:81], v[134:137], v[190:193], v[78:81]
	v_mfma_f32_16x16x32_bf16 v[70:73], v[142:145], v[190:193], v[70:73]
	v_mfma_f32_16x16x32_bf16 v[126:129], v[138:141], v[170:173], v[126:129]
	v_mfma_f32_16x16x32_bf16 v[118:121], v[146:149], v[170:173], v[118:121]
	v_mfma_f32_16x16x32_bf16 v[110:113], v[138:141], v[178:181], v[110:113]
	v_mfma_f32_16x16x32_bf16 v[102:105], v[146:149], v[178:181], v[102:105]
	v_mfma_f32_16x16x32_bf16 v[94:97], v[138:141], v[186:189], v[94:97]
	v_mfma_f32_16x16x32_bf16 v[86:89], v[146:149], v[186:189], v[86:89]
	v_mfma_f32_16x16x32_bf16 v[78:81], v[138:141], v[194:197], v[78:81]
	v_mfma_f32_16x16x32_bf16 v[70:73], v[146:149], v[194:197], v[70:73]
	s_setprio 0
	s_barrier
	s_add_i32 s48, s62, s12
	s_mov_b32 m0, s48
	ds_read_b128 v[190:193], v220 offset:49152
	ds_read_b128 v[194:197], v220 offset:50176
	ds_read_b128 v[182:185], v220 offset:51200
	ds_read_b128 v[186:189], v220 offset:52224
	ds_read_b128 v[174:177], v220 offset:53248
	ds_read_b128 v[178:181], v220 offset:54272
	ds_read_b128 v[166:169], v220 offset:55296
	ds_read_b128 v[170:173], v220 offset:56320
	global_load_lds_dwordx4 v202, s[98:99]
	s_add_i32 m0, s48, 0x2000
	s_add_u32 s46, s46, 0x40080
	s_addc_u32 s47, s47, 0
	s_add_i32 s48, s63, s12
	global_load_lds_dwordx4 v198, s[98:99]
	s_mov_b32 m0, s48
	s_andn2_b64 vcc, exec, s[30:31]
	global_load_lds_dwordx4 v202, s[46:47]
	s_add_i32 m0, s48, 0x2000
	s_nop 0
	global_load_lds_dwordx4 v198, s[46:47]
	s_mov_b32 m0, s51
	s_nop 0
	global_load_lds_dwordx4 v204, s[100:101]
	s_mov_b32 m0, s52
	s_nop 0
	global_load_lds_dwordx4 v200, s[100:101]
	s_waitcnt vmcnt(8)
	s_cbranch_vccnz .LBB0_1765
	s_and_saveexec_b64 s[30:31], s[4:5]
	s_cbranch_execz .LBB0_1764
	v_mov_b32_e32 v222, v3
	v_mov_b32_e32 v223, v4
	v_mov_b32_e32 v224, v2
	v_mov_b32_e32 v225, v5
	v_pk_add_f32 v[222:223], v[222:223], v[224:225]
	s_nop 0
	v_add_f32_e32 v222, v222, v223
	v_fmamk_f32 v222, v222, 0x3a800000, v221
	ds_write_b32 v219, v222
	s_branch .LBB0_1764

.LBB0_1894:
	v_add_u32_e32 v153, s44, v151
	ds_read_b128 v[154:157], v153
	ds_read_b128 v[158:161], v153 offset:1024
	ds_read_b128 v[162:165], v153 offset:2048
	ds_read_b128 v[166:169], v153 offset:3072
	v_add_u32_e32 v153, s45, v151
	s_add_u32 s26, s18, s24
	ds_read_b128 v[170:173], v153
	ds_read_b128 v[174:177], v153 offset:1024
	ds_read_b128 v[178:181], v153 offset:2048
	ds_read_b128 v[182:185], v153 offset:3072
	s_addc_u32 s27, s19, s25
	s_add_u32 s26, s26, 0x100
	s_addc_u32 s27, s27, 0
	s_add_u32 s51, s48, s24
	s_addc_u32 s52, s49, s25
	s_cmpk_eq_i32 s24, 0x1500
	s_cselect_b32 s29, s23, s27
	s_cselect_b32 s28, s22, s26
	s_cselect_b32 s27, s9, s52
	s_cselect_b32 s26, s8, s51
	v_lshl_add_u64 v[218:219], v[146:147], 0, s[24:25]
	s_add_i32 m0, s33, 0xc000
	ds_read_b128 v[186:189], v152
	ds_read_b128 v[190:193], v152 offset:1024
	ds_read_b128 v[194:197], v152 offset:2048
	ds_read_b128 v[198:201], v152 offset:3072
	ds_read_b128 v[202:205], v152 offset:4096
	ds_read_b128 v[206:209], v152 offset:5120
	ds_read_b128 v[210:213], v152 offset:6144
	ds_read_b128 v[214:217], v152 offset:7168
	global_load_lds_dwordx4 v[218:219], off
	v_lshl_add_u64 v[218:219], v[148:149], 0, s[24:25]
	s_add_i32 m0, s33, 0xe000
	s_nop 0
	global_load_lds_dwordx4 v[218:219], off
	s_waitcnt vmcnt(8)
	s_waitcnt lgkmcnt(0)
	s_barrier
	s_setprio 1
	s_waitcnt lgkmcnt(0)
	v_mfma_f32_16x16x32_bf16 v[126:129], v[154:157], v[186:189], v[126:129]
	v_mfma_f32_16x16x32_bf16 v[122:125], v[162:165], v[186:189], v[122:125]
	v_mfma_f32_16x16x32_bf16 v[110:113], v[154:157], v[194:197], v[110:113]
	v_mfma_f32_16x16x32_bf16 v[106:109], v[162:165], v[194:197], v[106:109]
	v_mfma_f32_16x16x32_bf16 v[94:97], v[154:157], v[202:205], v[94:97]
	v_mfma_f32_16x16x32_bf16 v[90:93], v[162:165], v[202:205], v[90:93]
	v_mfma_f32_16x16x32_bf16 v[78:81], v[154:157], v[210:213], v[78:81]
	v_mfma_f32_16x16x32_bf16 v[74:77], v[162:165], v[210:213], v[74:77]
	v_mfma_f32_16x16x32_bf16 v[126:129], v[158:161], v[190:193], v[126:129]
	v_mfma_f32_16x16x32_bf16 v[122:125], v[166:169], v[190:193], v[122:125]
	v_mfma_f32_16x16x32_bf16 v[110:113], v[158:161], v[198:201], v[110:113]
	v_mfma_f32_16x16x32_bf16 v[106:109], v[166:169], v[198:201], v[106:109]
	v_mfma_f32_16x16x32_bf16 v[94:97], v[158:161], v[206:209], v[94:97]
	v_mfma_f32_16x16x32_bf16 v[90:93], v[166:169], v[206:209], v[90:93]
	v_mfma_f32_16x16x32_bf16 v[78:81], v[158:161], v[214:217], v[78:81]
	v_mfma_f32_16x16x32_bf16 v[74:77], v[166:169], v[214:217], v[74:77]
	v_mfma_f32_16x16x32_bf16 v[118:121], v[170:173], v[186:189], v[118:121]
	v_mfma_f32_16x16x32_bf16 v[114:117], v[178:181], v[186:189], v[114:117]
	v_mfma_f32_16x16x32_bf16 v[102:105], v[170:173], v[194:197], v[102:105]
	v_mfma_f32_16x16x32_bf16 v[98:101], v[178:181], v[194:197], v[98:101]
	v_mfma_f32_16x16x32_bf16 v[86:89], v[170:173], v[202:205], v[86:89]
	v_mfma_f32_16x16x32_bf16 v[82:85], v[178:181], v[202:205], v[82:85]
	v_mfma_f32_16x16x32_bf16 v[70:73], v[170:173], v[210:213], v[70:73]
	v_mfma_f32_16x16x32_bf16 v[66:69], v[178:181], v[210:213], v[66:69]
	v_mfma_f32_16x16x32_bf16 v[118:121], v[174:177], v[190:193], v[118:121]
	v_mfma_f32_16x16x32_bf16 v[114:117], v[182:185], v[190:193], v[114:117]
	v_mfma_f32_16x16x32_bf16 v[102:105], v[174:177], v[198:201], v[102:105]
	v_mfma_f32_16x16x32_bf16 v[98:101], v[182:185], v[198:201], v[98:101]
	v_mfma_f32_16x16x32_bf16 v[86:89], v[174:177], v[206:209], v[86:89]
	v_mfma_f32_16x16x32_bf16 v[82:85], v[182:185], v[206:209], v[82:85]
	v_mfma_f32_16x16x32_bf16 v[70:73], v[174:177], v[214:217], v[70:73]
	v_mfma_f32_16x16x32_bf16 v[66:69], v[182:185], v[214:217], v[66:69]
	s_setprio 0
	s_barrier
	s_add_i32 s51, s44, s13
	s_add_u32 s98, s26, s20
	s_addc_u32 s99, s27, s21
	s_mov_b32 m0, s51
	ds_read_b128 v[186:189], v152 offset:16384
	ds_read_b128 v[190:193], v152 offset:17408
	ds_read_b128 v[194:197], v152 offset:18432
	ds_read_b128 v[198:201], v152 offset:19456
	ds_read_b128 v[202:205], v152 offset:20480
	ds_read_b128 v[206:209], v152 offset:21504
	ds_read_b128 v[210:213], v152 offset:22528
	ds_read_b128 v[214:217], v152 offset:23552
	global_load_lds_dwordx4 v132, s[26:27]
	s_add_i32 m0, s51, 0x2000
	s_add_u32 s52, s26, 0xb0000
	s_addc_u32 s53, s27, 0
	s_add_i32 s51, s45, s13
	global_load_lds_dwordx4 v136, s[26:27]
	s_mov_b32 m0, s51
	s_nop 0
	global_load_lds_dwordx4 v132, s[52:53]
	s_add_i32 m0, s51, 0x2000
	s_nop 0
	global_load_lds_dwordx4 v136, s[52:53]
	s_add_u32 s100, s28, s20
	s_addc_u32 s101, s29, s21
	s_mov_b32 m0, s33
	s_nop 0
	global_load_lds_dwordx4 v130, s[28:29]
	s_mov_b32 m0, s14
	s_nop 0
	global_load_lds_dwordx4 v134, s[28:29]
	s_waitcnt vmcnt(8)
	s_waitcnt lgkmcnt(0)
	s_barrier
	s_setprio 1
	s_waitcnt lgkmcnt(0)
	v_mfma_f32_16x16x32_bf16 v[62:65], v[154:157], v[186:189], v[62:65]
	v_mfma_f32_16x16x32_bf16 v[58:61], v[162:165], v[186:189], v[58:61]
	v_mfma_f32_16x16x32_bf16 v[46:49], v[154:157], v[194:197], v[46:49]
	v_mfma_f32_16x16x32_bf16 v[42:45], v[162:165], v[194:197], v[42:45]
	v_mfma_f32_16x16x32_bf16 v[30:33], v[154:157], v[202:205], v[30:33]
	v_mfma_f32_16x16x32_bf16 v[26:29], v[162:165], v[202:205], v[26:29]
	v_mfma_f32_16x16x32_bf16 v[14:17], v[154:157], v[210:213], v[14:17]
	v_mfma_f32_16x16x32_bf16 v[10:13], v[162:165], v[210:213], v[10:13]
	v_mfma_f32_16x16x32_bf16 v[62:65], v[158:161], v[190:193], v[62:65]
	v_mfma_f32_16x16x32_bf16 v[58:61], v[166:169], v[190:193], v[58:61]
	v_mfma_f32_16x16x32_bf16 v[46:49], v[158:161], v[198:201], v[46:49]
	v_mfma_f32_16x16x32_bf16 v[42:45], v[166:169], v[198:201], v[42:45]
	v_mfma_f32_16x16x32_bf16 v[30:33], v[158:161], v[206:209], v[30:33]
	v_mfma_f32_16x16x32_bf16 v[26:29], v[166:169], v[206:209], v[26:29]
	v_mfma_f32_16x16x32_bf16 v[14:17], v[158:161], v[214:217], v[14:17]
	v_mfma_f32_16x16x32_bf16 v[10:13], v[166:169], v[214:217], v[10:13]
	v_mfma_f32_16x16x32_bf16 v[54:57], v[170:173], v[186:189], v[54:57]
	v_mfma_f32_16x16x32_bf16 v[50:53], v[178:181], v[186:189], v[50:53]
	v_mfma_f32_16x16x32_bf16 v[38:41], v[170:173], v[194:197], v[38:41]
	v_mfma_f32_16x16x32_bf16 v[34:37], v[178:181], v[194:197], v[34:37]
	v_mfma_f32_16x16x32_bf16 v[22:25], v[170:173], v[202:205], v[22:25]
	v_mfma_f32_16x16x32_bf16 v[18:21], v[178:181], v[202:205], v[18:21]
	v_mfma_f32_16x16x32_bf16 v[6:9], v[170:173], v[210:213], v[6:9]
	v_mfma_f32_16x16x32_bf16 v[2:5], v[178:181], v[210:213], v[2:5]
	v_mfma_f32_16x16x32_bf16 v[54:57], v[174:177], v[190:193], v[54:57]
	v_mfma_f32_16x16x32_bf16 v[50:53], v[182:185], v[190:193], v[50:53]
	v_mfma_f32_16x16x32_bf16 v[38:41], v[174:177], v[198:201], v[38:41]
	v_mfma_f32_16x16x32_bf16 v[34:37], v[182:185], v[198:201], v[34:37]
	v_mfma_f32_16x16x32_bf16 v[22:25], v[174:177], v[206:209], v[22:25]
	v_mfma_f32_16x16x32_bf16 v[18:21], v[182:185], v[206:209], v[18:21]
	v_mfma_f32_16x16x32_bf16 v[6:9], v[174:177], v[214:217], v[6:9]
	v_mfma_f32_16x16x32_bf16 v[2:5], v[182:185], v[214:217], v[2:5]
	s_setprio 0
	s_barrier
	s_add_i32 s51, 0, 0x18000
	v_add_u32_e32 v153, s51, v151
	s_add_i32 s52, 0, 0x1c000
	ds_read_b128 v[154:157], v153
	ds_read_b128 v[158:161], v153 offset:1024
	ds_read_b128 v[162:165], v153 offset:2048
	ds_read_b128 v[166:169], v153 offset:3072
	v_add_u32_e32 v153, s52, v151
	ds_read_b128 v[170:173], v153
	ds_read_b128 v[174:177], v153 offset:1024
	ds_read_b128 v[178:181], v153 offset:2048
	ds_read_b128 v[182:185], v153 offset:3072
	s_add_u32 s28, s28, 0xb0000
	s_addc_u32 s29, s29, 0
	s_mov_b32 m0, s15
	ds_read_b128 v[186:189], v152 offset:32768
	ds_read_b128 v[190:193], v152 offset:33792
	ds_read_b128 v[194:197], v152 offset:34816
	ds_read_b128 v[198:201], v152 offset:35840
	ds_read_b128 v[202:205], v152 offset:36864
	ds_read_b128 v[206:209], v152 offset:37888
	ds_read_b128 v[210:213], v152 offset:38912
	ds_read_b128 v[214:217], v152 offset:39936
	global_load_lds_dwordx4 v130, s[28:29]
	s_mov_b32 m0, s40
	s_nop 0
	global_load_lds_dwordx4 v134, s[28:29]
	s_waitcnt vmcnt(8)
	s_waitcnt lgkmcnt(0)
	s_barrier
	s_setprio 1
	s_waitcnt lgkmcnt(0)
	v_mfma_f32_16x16x32_bf16 v[126:129], v[154:157], v[186:189], v[126:129]
	v_mfma_f32_16x16x32_bf16 v[122:125], v[162:165], v[186:189], v[122:125]
	v_mfma_f32_16x16x32_bf16 v[110:113], v[154:157], v[194:197], v[110:113]
	v_mfma_f32_16x16x32_bf16 v[106:109], v[162:165], v[194:197], v[106:109]
	v_mfma_f32_16x16x32_bf16 v[94:97], v[154:157], v[202:205], v[94:97]
	v_mfma_f32_16x16x32_bf16 v[90:93], v[162:165], v[202:205], v[90:93]
	v_mfma_f32_16x16x32_bf16 v[78:81], v[154:157], v[210:213], v[78:81]
	v_mfma_f32_16x16x32_bf16 v[74:77], v[162:165], v[210:213], v[74:77]
	v_mfma_f32_16x16x32_bf16 v[126:129], v[158:161], v[190:193], v[126:129]
	v_mfma_f32_16x16x32_bf16 v[122:125], v[166:169], v[190:193], v[122:125]
	v_mfma_f32_16x16x32_bf16 v[110:113], v[158:161], v[198:201], v[110:113]
	v_mfma_f32_16x16x32_bf16 v[106:109], v[166:169], v[198:201], v[106:109]
	v_mfma_f32_16x16x32_bf16 v[94:97], v[158:161], v[206:209], v[94:97]
	v_mfma_f32_16x16x32_bf16 v[90:93], v[166:169], v[206:209], v[90:93]
	v_mfma_f32_16x16x32_bf16 v[78:81], v[158:161], v[214:217], v[78:81]
	v_mfma_f32_16x16x32_bf16 v[74:77], v[166:169], v[214:217], v[74:77]
	v_mfma_f32_16x16x32_bf16 v[118:121], v[170:173], v[186:189], v[118:121]
	v_mfma_f32_16x16x32_bf16 v[114:117], v[178:181], v[186:189], v[114:117]
	v_mfma_f32_16x16x32_bf16 v[102:105], v[170:173], v[194:197], v[102:105]
	v_mfma_f32_16x16x32_bf16 v[98:101], v[178:181], v[194:197], v[98:101]
	v_mfma_f32_16x16x32_bf16 v[86:89], v[170:173], v[202:205], v[86:89]
	v_mfma_f32_16x16x32_bf16 v[82:85], v[178:181], v[202:205], v[82:85]
	v_mfma_f32_16x16x32_bf16 v[70:73], v[170:173], v[210:213], v[70:73]
	v_mfma_f32_16x16x32_bf16 v[66:69], v[178:181], v[210:213], v[66:69]
	v_mfma_f32_16x16x32_bf16 v[118:121], v[174:177], v[190:193], v[118:121]
	v_mfma_f32_16x16x32_bf16 v[114:117], v[182:185], v[190:193], v[114:117]
	v_mfma_f32_16x16x32_bf16 v[102:105], v[174:177], v[198:201], v[102:105]
	v_mfma_f32_16x16x32_bf16 v[98:101], v[182:185], v[198:201], v[98:101]
	v_mfma_f32_16x16x32_bf16 v[86:89], v[174:177], v[206:209], v[86:89]
	v_mfma_f32_16x16x32_bf16 v[82:85], v[182:185], v[206:209], v[82:85]
	v_mfma_f32_16x16x32_bf16 v[70:73], v[174:177], v[214:217], v[70:73]
	v_mfma_f32_16x16x32_bf16 v[66:69], v[182:185], v[214:217], v[66:69]
	s_setprio 0
	s_barrier
	s_add_i32 s28, s51, s13
	s_mov_b32 m0, s28
	ds_read_b128 v[186:189], v152 offset:49152
	ds_read_b128 v[190:193], v152 offset:50176
	ds_read_b128 v[194:197], v152 offset:51200
	ds_read_b128 v[198:201], v152 offset:52224
	ds_read_b128 v[202:205], v152 offset:53248
	ds_read_b128 v[206:209], v152 offset:54272
	ds_read_b128 v[210:213], v152 offset:55296
	ds_read_b128 v[214:217], v152 offset:56320
	global_load_lds_dwordx4 v132, s[98:99]
	s_add_i32 m0, s28, 0x2000
	s_add_u32 s26, s26, 0xb0080
	s_addc_u32 s27, s27, 0
	s_add_i32 s28, s52, s13
	global_load_lds_dwordx4 v136, s[98:99]
	s_mov_b32 m0, s28
	s_nop 0
	global_load_lds_dwordx4 v132, s[26:27]
	s_add_i32 m0, s28, 0x2000
	s_nop 0
	global_load_lds_dwordx4 v136, s[26:27]
	s_mov_b32 m0, s42
	s_nop 0
	global_load_lds_dwordx4 v130, s[100:101]
	s_mov_b32 m0, s43
	s_nop 0
	global_load_lds_dwordx4 v134, s[100:101]
	s_waitcnt vmcnt(8)
	s_waitcnt lgkmcnt(0)
	s_barrier
	s_setprio 1
	s_waitcnt lgkmcnt(0)
	v_mfma_f32_16x16x32_bf16 v[62:65], v[154:157], v[186:189], v[62:65]
	v_mfma_f32_16x16x32_bf16 v[58:61], v[162:165], v[186:189], v[58:61]
	v_mfma_f32_16x16x32_bf16 v[46:49], v[154:157], v[194:197], v[46:49]
	v_mfma_f32_16x16x32_bf16 v[42:45], v[162:165], v[194:197], v[42:45]
	v_mfma_f32_16x16x32_bf16 v[30:33], v[154:157], v[202:205], v[30:33]
	v_mfma_f32_16x16x32_bf16 v[26:29], v[162:165], v[202:205], v[26:29]
	v_mfma_f32_16x16x32_bf16 v[14:17], v[154:157], v[210:213], v[14:17]
	v_mfma_f32_16x16x32_bf16 v[10:13], v[162:165], v[210:213], v[10:13]
	v_mfma_f32_16x16x32_bf16 v[62:65], v[158:161], v[190:193], v[62:65]
	v_mfma_f32_16x16x32_bf16 v[58:61], v[166:169], v[190:193], v[58:61]
	v_mfma_f32_16x16x32_bf16 v[46:49], v[158:161], v[198:201], v[46:49]
	v_mfma_f32_16x16x32_bf16 v[42:45], v[166:169], v[198:201], v[42:45]
	v_mfma_f32_16x16x32_bf16 v[30:33], v[158:161], v[206:209], v[30:33]
	v_mfma_f32_16x16x32_bf16 v[26:29], v[166:169], v[206:209], v[26:29]
	v_mfma_f32_16x16x32_bf16 v[14:17], v[158:161], v[214:217], v[14:17]
	v_mfma_f32_16x16x32_bf16 v[10:13], v[166:169], v[214:217], v[10:13]
	v_mfma_f32_16x16x32_bf16 v[54:57], v[170:173], v[186:189], v[54:57]
	v_mfma_f32_16x16x32_bf16 v[50:53], v[178:181], v[186:189], v[50:53]
	v_mfma_f32_16x16x32_bf16 v[38:41], v[170:173], v[194:197], v[38:41]
	v_mfma_f32_16x16x32_bf16 v[34:37], v[178:181], v[194:197], v[34:37]
	v_mfma_f32_16x16x32_bf16 v[22:25], v[170:173], v[202:205], v[22:25]
	v_mfma_f32_16x16x32_bf16 v[18:21], v[178:181], v[202:205], v[18:21]
	v_mfma_f32_16x16x32_bf16 v[6:9], v[170:173], v[210:213], v[6:9]
	v_mfma_f32_16x16x32_bf16 v[2:5], v[178:181], v[210:213], v[2:5]
	v_mfma_f32_16x16x32_bf16 v[54:57], v[174:177], v[190:193], v[54:57]
	v_mfma_f32_16x16x32_bf16 v[50:53], v[182:185], v[190:193], v[50:53]
	v_mfma_f32_16x16x32_bf16 v[38:41], v[174:177], v[198:201], v[38:41]
	v_mfma_f32_16x16x32_bf16 v[34:37], v[182:185], v[198:201], v[34:37]
	v_mfma_f32_16x16x32_bf16 v[22:25], v[174:177], v[206:209], v[22:25]
	v_mfma_f32_16x16x32_bf16 v[18:21], v[182:185], v[206:209], v[18:21]
	v_mfma_f32_16x16x32_bf16 v[6:9], v[174:177], v[214:217], v[6:9]
	v_mfma_f32_16x16x32_bf16 v[2:5], v[182:185], v[214:217], v[2:5]
	s_setprio 0
	s_barrier
	s_add_i32 s50, s50, 2
	s_add_u32 s24, s24, 0x100
	s_addc_u32 s25, s25, 0
	s_cmp_gt_u32 s50, 41
	s_cbranch_scc0 .LBB0_1894
	s_add_u32 s24, s48, 0xffffff00
	s_addc_u32 s25, s49, -1
	s_and_b64 vcc, exec, s[6:7]
	s_cbranch_vccnz .LBB0_1897
	v_mov_b32_e32 v2, 0
	s_mov_b32 s16, s46
	s_mov_b32 s31, s47
	s_mov_b64 s[18:19], s[22:23]
	s_mov_b32 s41, s2
	v_mov_b32_e32 v3, v2
	v_mov_b32_e32 v4, v2
	v_mov_b32_e32 v5, v2
	v_mov_b32_e32 v6, v2
	v_mov_b32_e32 v7, v2
	v_mov_b32_e32 v8, v2
	v_mov_b32_e32 v9, v2
	v_mov_b32_e32 v18, v2
	v_mov_b32_e32 v19, v2
	v_mov_b32_e32 v20, v2
	v_mov_b32_e32 v21, v2
	v_mov_b32_e32 v22, v2
	v_mov_b32_e32 v23, v2
	v_mov_b32_e32 v24, v2
	v_mov_b32_e32 v25, v2
	v_mov_b32_e32 v34, v2
	v_mov_b32_e32 v35, v2
	v_mov_b32_e32 v36, v2
	v_mov_b32_e32 v37, v2
	v_mov_b32_e32 v38, v2
	v_mov_b32_e32 v39, v2
	v_mov_b32_e32 v40, v2
	v_mov_b32_e32 v41, v2
	v_mov_b32_e32 v50, v2
	v_mov_b32_e32 v51, v2
	v_mov_b32_e32 v52, v2
	v_mov_b32_e32 v53, v2
	v_mov_b32_e32 v54, v2
	v_mov_b32_e32 v55, v2
	v_mov_b32_e32 v56, v2
	v_mov_b32_e32 v57, v2
	v_mov_b32_e32 v10, v2
	v_mov_b32_e32 v11, v2
	v_mov_b32_e32 v12, v2
	v_mov_b32_e32 v13, v2
	v_mov_b32_e32 v14, v2
	v_mov_b32_e32 v15, v2
	v_mov_b32_e32 v16, v2
	v_mov_b32_e32 v17, v2
	v_mov_b32_e32 v26, v2
	v_mov_b32_e32 v27, v2
	v_mov_b32_e32 v28, v2
	v_mov_b32_e32 v29, v2
	v_mov_b32_e32 v30, v2
	v_mov_b32_e32 v31, v2
	v_mov_b32_e32 v32, v2
	v_mov_b32_e32 v33, v2
	v_mov_b32_e32 v42, v2
	v_mov_b32_e32 v43, v2
	v_mov_b32_e32 v44, v2
	v_mov_b32_e32 v45, v2
	v_mov_b32_e32 v46, v2
	v_mov_b32_e32 v47, v2
	v_mov_b32_e32 v48, v2
	v_mov_b32_e32 v49, v2
	v_mov_b32_e32 v58, v2
	v_mov_b32_e32 v59, v2
	v_mov_b32_e32 v60, v2
	v_mov_b32_e32 v61, v2
	v_mov_b32_e32 v62, v2
	v_mov_b32_e32 v63, v2
	v_mov_b32_e32 v64, v2
	v_mov_b32_e32 v65, v2
	v_mov_b32_e32 v66, v2
	v_mov_b32_e32 v67, v2
	v_mov_b32_e32 v68, v2
	v_mov_b32_e32 v69, v2
	v_mov_b32_e32 v70, v2
	v_mov_b32_e32 v71, v2
	v_mov_b32_e32 v72, v2
	v_mov_b32_e32 v73, v2
	v_mov_b32_e32 v82, v2
	v_mov_b32_e32 v83, v2
	v_mov_b32_e32 v84, v2
	v_mov_b32_e32 v85, v2
	v_mov_b32_e32 v86, v2
	v_mov_b32_e32 v87, v2
	v_mov_b32_e32 v88, v2
	v_mov_b32_e32 v89, v2
	v_mov_b32_e32 v98, v2
	v_mov_b32_e32 v99, v2
	v_mov_b32_e32 v100, v2
	v_mov_b32_e32 v101, v2
	v_mov_b32_e32 v102, v2
	v_mov_b32_e32 v103, v2
	v_mov_b32_e32 v104, v2
	v_mov_b32_e32 v105, v2
	v_mov_b32_e32 v114, v2
	v_mov_b32_e32 v115, v2
	v_mov_b32_e32 v116, v2
	v_mov_b32_e32 v117, v2
	v_mov_b32_e32 v118, v2
	v_mov_b32_e32 v119, v2
	v_mov_b32_e32 v120, v2
	v_mov_b32_e32 v121, v2
	v_mov_b32_e32 v74, v2
	v_mov_b32_e32 v75, v2
	v_mov_b32_e32 v76, v2
	v_mov_b32_e32 v77, v2
	v_mov_b32_e32 v78, v2
	v_mov_b32_e32 v79, v2
	v_mov_b32_e32 v80, v2
	v_mov_b32_e32 v81, v2
	v_mov_b32_e32 v90, v2
	v_mov_b32_e32 v91, v2
	v_mov_b32_e32 v92, v2
	v_mov_b32_e32 v93, v2
	v_mov_b32_e32 v94, v2
	v_mov_b32_e32 v95, v2
	v_mov_b32_e32 v96, v2
	v_mov_b32_e32 v97, v2
	v_mov_b32_e32 v106, v2
	v_mov_b32_e32 v107, v2
	v_mov_b32_e32 v108, v2
	v_mov_b32_e32 v109, v2
	v_mov_b32_e32 v110, v2
	v_mov_b32_e32 v111, v2
	v_mov_b32_e32 v112, v2
	v_mov_b32_e32 v113, v2
	v_mov_b32_e32 v122, v2
	v_mov_b32_e32 v123, v2
	v_mov_b32_e32 v124, v2
	v_mov_b32_e32 v125, v2
	v_mov_b32_e32 v126, v2
	v_mov_b32_e32 v127, v2
	v_mov_b32_e32 v128, v2
	v_mov_b32_e32 v129, v2
	s_andn2_b64 vcc, exec, s[4:5]
	s_cbranch_vccnz .LBB0_1898
	s_branch .LBB0_1899

.LBB0_2031:
	ds_read_b128 v[36:39], v203
	ds_read_b128 v[44:47], v203 offset:1024
	ds_read_b128 v[48:51], v203 offset:2048
	ds_read_b128 v[56:59], v203 offset:3072
	ds_read_b128 v[144:147], v207
	ds_read_b128 v[148:151], v207 offset:1024
	ds_read_b128 v[152:155], v207 offset:2048
	ds_read_b128 v[156:159], v207 offset:3072
	s_add_u32 s34, s30, 0xfffc0080
	s_addc_u32 s35, s31, -1
	s_cmp_eq_u32 s63, 12
	s_cselect_b32 s39, s14, s35
	s_cselect_b32 s38, s15, s34
	s_cselect_b32 s35, s21, s62
	s_cselect_b32 s34, s23, s61
	s_add_i32 m0, s29, 0xc000
	ds_read_b128 v[172:175], v209
	ds_read_b128 v[176:179], v209 offset:1024
	ds_read_b128 v[180:183], v209 offset:2048
	ds_read_b128 v[184:187], v209 offset:3072
	ds_read_b128 v[188:191], v209 offset:4096
	ds_read_b128 v[192:195], v209 offset:5120
	ds_read_b128 v[196:199], v209 offset:6144
	ds_read_b128 v[214:217], v209 offset:7168
	global_load_lds_dwordx4 v168, s[30:31]
	s_add_i32 m0, s29, 0xe000
	s_nop 0
	global_load_lds_dwordx4 v170, s[30:31]
	s_waitcnt vmcnt(8)
	s_waitcnt lgkmcnt(0)
	s_barrier
	s_setprio 1
	s_waitcnt lgkmcnt(0)
	v_mfma_f32_16x16x32_bf16 v[140:143], v[36:39], v[172:175], v[140:143]
	v_mfma_f32_16x16x32_bf16 v[136:139], v[48:51], v[172:175], v[136:139]
	v_mfma_f32_16x16x32_bf16 v[124:127], v[36:39], v[180:183], v[124:127]
	v_mfma_f32_16x16x32_bf16 v[120:123], v[48:51], v[180:183], v[120:123]
	v_mfma_f32_16x16x32_bf16 v[108:111], v[36:39], v[188:191], v[108:111]
	v_mfma_f32_16x16x32_bf16 v[104:107], v[48:51], v[188:191], v[104:107]
	v_mfma_f32_16x16x32_bf16 v[92:95], v[36:39], v[196:199], v[92:95]
	v_mfma_f32_16x16x32_bf16 v[88:91], v[48:51], v[196:199], v[88:91]
	v_mfma_f32_16x16x32_bf16 v[140:143], v[44:47], v[176:179], v[140:143]
	v_mfma_f32_16x16x32_bf16 v[136:139], v[56:59], v[176:179], v[136:139]
	v_mfma_f32_16x16x32_bf16 v[124:127], v[44:47], v[184:187], v[124:127]
	v_mfma_f32_16x16x32_bf16 v[120:123], v[56:59], v[184:187], v[120:123]
	v_mfma_f32_16x16x32_bf16 v[108:111], v[44:47], v[192:195], v[108:111]
	v_mfma_f32_16x16x32_bf16 v[104:107], v[56:59], v[192:195], v[104:107]
	v_mfma_f32_16x16x32_bf16 v[92:95], v[44:47], v[214:217], v[92:95]
	v_mfma_f32_16x16x32_bf16 v[88:91], v[56:59], v[214:217], v[88:91]
	v_mfma_f32_16x16x32_bf16 v[132:135], v[144:147], v[172:175], v[132:135]
	v_mfma_f32_16x16x32_bf16 v[128:131], v[152:155], v[172:175], v[128:131]
	v_mfma_f32_16x16x32_bf16 v[116:119], v[144:147], v[180:183], v[116:119]
	v_mfma_f32_16x16x32_bf16 v[112:115], v[152:155], v[180:183], v[112:115]
	v_mfma_f32_16x16x32_bf16 v[100:103], v[144:147], v[188:191], v[100:103]
	v_mfma_f32_16x16x32_bf16 v[96:99], v[152:155], v[188:191], v[96:99]
	v_mfma_f32_16x16x32_bf16 v[84:87], v[144:147], v[196:199], v[84:87]
	v_mfma_f32_16x16x32_bf16 v[80:83], v[152:155], v[196:199], v[80:83]
	v_mfma_f32_16x16x32_bf16 v[132:135], v[148:151], v[176:179], v[132:135]
	v_mfma_f32_16x16x32_bf16 v[128:131], v[156:159], v[176:179], v[128:131]
	v_mfma_f32_16x16x32_bf16 v[116:119], v[148:151], v[184:187], v[116:119]
	v_mfma_f32_16x16x32_bf16 v[112:115], v[156:159], v[184:187], v[112:115]
	v_mfma_f32_16x16x32_bf16 v[100:103], v[148:151], v[192:195], v[100:103]
	v_mfma_f32_16x16x32_bf16 v[96:99], v[156:159], v[192:195], v[96:99]
	v_mfma_f32_16x16x32_bf16 v[84:87], v[148:151], v[214:217], v[84:87]
	v_mfma_f32_16x16x32_bf16 v[80:83], v[156:159], v[214:217], v[80:83]
	s_setprio 0
	s_barrier
	s_add_i32 s64, s55, s42
	s_add_u32 s98, s34, s16
	s_addc_u32 s99, s35, s17
	s_mov_b32 m0, s64
	ds_read_b128 v[172:175], v209 offset:16384
	ds_read_b128 v[176:179], v209 offset:17408
	ds_read_b128 v[180:183], v209 offset:18432
	ds_read_b128 v[184:187], v209 offset:19456
	ds_read_b128 v[188:191], v209 offset:20480
	ds_read_b128 v[192:195], v209 offset:21504
	ds_read_b128 v[196:199], v209 offset:22528
	ds_read_b128 v[214:217], v209 offset:23552
	global_load_lds_dwordx4 v162, s[34:35]
	s_add_i32 m0, s64, 0x2000
	s_add_u32 s64, s34, 0x40000
	s_addc_u32 s65, s35, 0
	s_add_i32 s66, s56, s42
	global_load_lds_dwordx4 v166, s[34:35]
	s_mov_b32 m0, s66
	s_nop 0
	global_load_lds_dwordx4 v162, s[64:65]
	s_add_i32 m0, s66, 0x2000
	s_nop 0
	global_load_lds_dwordx4 v166, s[64:65]
	s_add_u32 s100, s38, s16
	s_addc_u32 s101, s39, s17
	s_mov_b32 m0, s29
	s_nop 0
	global_load_lds_dwordx4 v160, s[38:39]
	s_mov_b32 m0, s43
	s_nop 0
	global_load_lds_dwordx4 v164, s[38:39]
	s_waitcnt vmcnt(8)
	s_waitcnt lgkmcnt(0)
	s_barrier
	s_setprio 1
	s_waitcnt lgkmcnt(0)
	v_mfma_f32_16x16x32_bf16 v[76:79], v[36:39], v[172:175], v[76:79]
	v_mfma_f32_16x16x32_bf16 v[72:75], v[48:51], v[172:175], v[72:75]
	v_mfma_f32_16x16x32_bf16 v[60:63], v[36:39], v[180:183], v[60:63]
	v_mfma_f32_16x16x32_bf16 v[52:55], v[48:51], v[180:183], v[52:55]
	v_mfma_f32_16x16x32_bf16 v[28:31], v[36:39], v[188:191], v[28:31]
	v_mfma_f32_16x16x32_bf16 v[24:27], v[48:51], v[188:191], v[24:27]
	v_mfma_f32_16x16x32_bf16 v[12:15], v[36:39], v[196:199], v[12:15]
	v_mfma_f32_16x16x32_bf16 v[8:11], v[48:51], v[196:199], v[8:11]
	v_mfma_f32_16x16x32_bf16 v[76:79], v[44:47], v[176:179], v[76:79]
	v_mfma_f32_16x16x32_bf16 v[72:75], v[56:59], v[176:179], v[72:75]
	v_mfma_f32_16x16x32_bf16 v[60:63], v[44:47], v[184:187], v[60:63]
	v_mfma_f32_16x16x32_bf16 v[52:55], v[56:59], v[184:187], v[52:55]
	v_mfma_f32_16x16x32_bf16 v[28:31], v[44:47], v[192:195], v[28:31]
	v_mfma_f32_16x16x32_bf16 v[24:27], v[56:59], v[192:195], v[24:27]
	v_mfma_f32_16x16x32_bf16 v[12:15], v[44:47], v[214:217], v[12:15]
	v_mfma_f32_16x16x32_bf16 v[8:11], v[56:59], v[214:217], v[8:11]
	v_mfma_f32_16x16x32_bf16 v[40:43], v[144:147], v[180:183], v[40:43]
	v_mfma_f32_16x16x32_bf16 v[32:35], v[152:155], v[180:183], v[32:35]
	v_mfma_f32_16x16x32_bf16 v[20:23], v[144:147], v[188:191], v[20:23]
	v_mfma_f32_16x16x32_bf16 v[16:19], v[152:155], v[188:191], v[16:19]
	v_mfma_f32_16x16x32_bf16 v[4:7], v[144:147], v[196:199], v[4:7]
	v_mfma_f32_16x16x32_bf16 v[0:3], v[152:155], v[196:199], v[0:3]
	v_mfma_f32_16x16x32_bf16 v[36:39], v[144:147], v[172:175], v[68:71]
	v_mfma_f32_16x16x32_bf16 v[44:47], v[152:155], v[172:175], v[64:67]
	v_mfma_f32_16x16x32_bf16 v[40:43], v[148:151], v[184:187], v[40:43]
	v_mfma_f32_16x16x32_bf16 v[32:35], v[156:159], v[184:187], v[32:35]
	v_mfma_f32_16x16x32_bf16 v[20:23], v[148:151], v[192:195], v[20:23]
	v_mfma_f32_16x16x32_bf16 v[16:19], v[156:159], v[192:195], v[16:19]
	v_mfma_f32_16x16x32_bf16 v[4:7], v[148:151], v[214:217], v[4:7]
	v_mfma_f32_16x16x32_bf16 v[0:3], v[156:159], v[214:217], v[0:3]
	v_mfma_f32_16x16x32_bf16 v[36:39], v[148:151], v[176:179], v[36:39]
	v_mfma_f32_16x16x32_bf16 v[44:47], v[156:159], v[176:179], v[44:47]
	s_setprio 0
	s_barrier
	s_add_i32 s64, 0, 0x18000
	s_add_i32 s65, 0, 0x1c000
	v_add_u32_e32 v68, s64, v201
	v_add_u32_e32 v156, s65, v201
	ds_read_b128 v[48:51], v68
	ds_read_b128 v[56:59], v68 offset:1024
	ds_read_b128 v[64:67], v68 offset:2048
	ds_read_b128 v[68:71], v68 offset:3072
	ds_read_b128 v[144:147], v156
	ds_read_b128 v[148:151], v156 offset:1024
	ds_read_b128 v[152:155], v156 offset:2048
	ds_read_b128 v[156:159], v156 offset:3072
	s_add_u32 s38, s38, 0x40000
	s_addc_u32 s39, s39, 0
	s_mov_b32 m0, s44
	ds_read_b128 v[172:175], v209 offset:32768
	ds_read_b128 v[176:179], v209 offset:33792
	ds_read_b128 v[180:183], v209 offset:34816
	ds_read_b128 v[184:187], v209 offset:35840
	ds_read_b128 v[188:191], v209 offset:36864
	ds_read_b128 v[192:195], v209 offset:37888
	ds_read_b128 v[196:199], v209 offset:38912
	ds_read_b128 v[214:217], v209 offset:39936
	global_load_lds_dwordx4 v160, s[38:39]
	s_mov_b32 m0, s45
	s_nop 0
	global_load_lds_dwordx4 v164, s[38:39]
	s_waitcnt vmcnt(8)
	s_waitcnt lgkmcnt(0)
	s_barrier
	s_setprio 1
	s_waitcnt lgkmcnt(0)
	v_mfma_f32_16x16x32_bf16 v[140:143], v[48:51], v[172:175], v[140:143]
	v_mfma_f32_16x16x32_bf16 v[136:139], v[64:67], v[172:175], v[136:139]
	v_mfma_f32_16x16x32_bf16 v[124:127], v[48:51], v[180:183], v[124:127]
	v_mfma_f32_16x16x32_bf16 v[120:123], v[64:67], v[180:183], v[120:123]
	v_mfma_f32_16x16x32_bf16 v[108:111], v[48:51], v[188:191], v[108:111]
	v_mfma_f32_16x16x32_bf16 v[104:107], v[64:67], v[188:191], v[104:107]
	v_mfma_f32_16x16x32_bf16 v[92:95], v[48:51], v[196:199], v[92:95]
	v_mfma_f32_16x16x32_bf16 v[88:91], v[64:67], v[196:199], v[88:91]
	v_mfma_f32_16x16x32_bf16 v[140:143], v[56:59], v[176:179], v[140:143]
	v_mfma_f32_16x16x32_bf16 v[136:139], v[68:71], v[176:179], v[136:139]
	v_mfma_f32_16x16x32_bf16 v[124:127], v[56:59], v[184:187], v[124:127]
	v_mfma_f32_16x16x32_bf16 v[120:123], v[68:71], v[184:187], v[120:123]
	v_mfma_f32_16x16x32_bf16 v[108:111], v[56:59], v[192:195], v[108:111]
	v_mfma_f32_16x16x32_bf16 v[104:107], v[68:71], v[192:195], v[104:107]
	v_mfma_f32_16x16x32_bf16 v[92:95], v[56:59], v[214:217], v[92:95]
	v_mfma_f32_16x16x32_bf16 v[88:91], v[68:71], v[214:217], v[88:91]
	v_mfma_f32_16x16x32_bf16 v[132:135], v[144:147], v[172:175], v[132:135]
	v_mfma_f32_16x16x32_bf16 v[128:131], v[152:155], v[172:175], v[128:131]
	v_mfma_f32_16x16x32_bf16 v[116:119], v[144:147], v[180:183], v[116:119]
	v_mfma_f32_16x16x32_bf16 v[112:115], v[152:155], v[180:183], v[112:115]
	v_mfma_f32_16x16x32_bf16 v[100:103], v[144:147], v[188:191], v[100:103]
	v_mfma_f32_16x16x32_bf16 v[96:99], v[152:155], v[188:191], v[96:99]
	v_mfma_f32_16x16x32_bf16 v[84:87], v[144:147], v[196:199], v[84:87]
	v_mfma_f32_16x16x32_bf16 v[80:83], v[152:155], v[196:199], v[80:83]
	v_mfma_f32_16x16x32_bf16 v[132:135], v[148:151], v[176:179], v[132:135]
	v_mfma_f32_16x16x32_bf16 v[128:131], v[156:159], v[176:179], v[128:131]
	v_mfma_f32_16x16x32_bf16 v[116:119], v[148:151], v[184:187], v[116:119]
	v_mfma_f32_16x16x32_bf16 v[112:115], v[156:159], v[184:187], v[112:115]
	v_mfma_f32_16x16x32_bf16 v[100:103], v[148:151], v[192:195], v[100:103]
	v_mfma_f32_16x16x32_bf16 v[96:99], v[156:159], v[192:195], v[96:99]
	v_mfma_f32_16x16x32_bf16 v[84:87], v[148:151], v[214:217], v[84:87]
	v_mfma_f32_16x16x32_bf16 v[80:83], v[156:159], v[214:217], v[80:83]
	s_setprio 0
	s_barrier
	s_add_i32 s38, s64, s42
	s_mov_b32 m0, s38
	ds_read_b128 v[172:175], v209 offset:49152
	ds_read_b128 v[176:179], v209 offset:50176
	ds_read_b128 v[180:183], v209 offset:51200
	ds_read_b128 v[184:187], v209 offset:52224
	ds_read_b128 v[188:191], v209 offset:53248
	ds_read_b128 v[192:195], v209 offset:54272
	ds_read_b128 v[196:199], v209 offset:55296
	ds_read_b128 v[214:217], v209 offset:56320
	global_load_lds_dwordx4 v162, s[98:99]
	s_add_i32 m0, s38, 0x2000
	s_add_u32 s34, s34, 0x40080
	s_addc_u32 s35, s35, 0
	s_add_i32 s38, s65, s42
	global_load_lds_dwordx4 v166, s[98:99]
	s_mov_b32 m0, s38
	s_nop 0
	global_load_lds_dwordx4 v162, s[34:35]
	s_add_i32 m0, s38, 0x2000
	s_nop 0
	global_load_lds_dwordx4 v166, s[34:35]
	s_mov_b32 m0, s50
	s_nop 0
	global_load_lds_dwordx4 v160, s[100:101]
	s_mov_b32 m0, s51
	s_nop 0
	global_load_lds_dwordx4 v164, s[100:101]
	s_waitcnt vmcnt(8)
	s_waitcnt lgkmcnt(0)
	s_barrier
	s_setprio 1
	s_waitcnt lgkmcnt(0)
	v_mfma_f32_16x16x32_bf16 v[76:79], v[48:51], v[172:175], v[76:79]
	v_mfma_f32_16x16x32_bf16 v[72:75], v[64:67], v[172:175], v[72:75]
	v_mfma_f32_16x16x32_bf16 v[60:63], v[48:51], v[180:183], v[60:63]
	v_mfma_f32_16x16x32_bf16 v[52:55], v[64:67], v[180:183], v[52:55]
	v_mfma_f32_16x16x32_bf16 v[28:31], v[48:51], v[188:191], v[28:31]
	v_mfma_f32_16x16x32_bf16 v[24:27], v[64:67], v[188:191], v[24:27]
	v_mfma_f32_16x16x32_bf16 v[12:15], v[48:51], v[196:199], v[12:15]
	v_mfma_f32_16x16x32_bf16 v[8:11], v[64:67], v[196:199], v[8:11]
	v_mfma_f32_16x16x32_bf16 v[76:79], v[56:59], v[176:179], v[76:79]
	v_mfma_f32_16x16x32_bf16 v[72:75], v[68:71], v[176:179], v[72:75]
	v_mfma_f32_16x16x32_bf16 v[60:63], v[56:59], v[184:187], v[60:63]
	v_mfma_f32_16x16x32_bf16 v[52:55], v[68:71], v[184:187], v[52:55]
	v_mfma_f32_16x16x32_bf16 v[28:31], v[56:59], v[192:195], v[28:31]
	v_mfma_f32_16x16x32_bf16 v[24:27], v[68:71], v[192:195], v[24:27]
	v_mfma_f32_16x16x32_bf16 v[12:15], v[56:59], v[214:217], v[12:15]
	v_mfma_f32_16x16x32_bf16 v[8:11], v[68:71], v[214:217], v[8:11]
	v_mfma_f32_16x16x32_bf16 v[36:39], v[144:147], v[172:175], v[36:39]
	v_mfma_f32_16x16x32_bf16 v[68:71], v[148:151], v[176:179], v[36:39]
	v_mfma_f32_16x16x32_bf16 v[36:39], v[152:155], v[172:175], v[44:47]
	v_mfma_f32_16x16x32_bf16 v[64:67], v[156:159], v[176:179], v[36:39]
	v_mfma_f32_16x16x32_bf16 v[36:39], v[144:147], v[180:183], v[40:43]
	v_mfma_f32_16x16x32_bf16 v[32:35], v[152:155], v[180:183], v[32:35]
	v_mfma_f32_16x16x32_bf16 v[20:23], v[144:147], v[188:191], v[20:23]
	v_mfma_f32_16x16x32_bf16 v[16:19], v[152:155], v[188:191], v[16:19]
	v_mfma_f32_16x16x32_bf16 v[4:7], v[144:147], v[196:199], v[4:7]
	v_mfma_f32_16x16x32_bf16 v[0:3], v[152:155], v[196:199], v[0:3]
	v_mfma_f32_16x16x32_bf16 v[40:43], v[148:151], v[184:187], v[36:39]
	v_mfma_f32_16x16x32_bf16 v[32:35], v[156:159], v[184:187], v[32:35]
	v_mfma_f32_16x16x32_bf16 v[20:23], v[148:151], v[192:195], v[20:23]
	v_mfma_f32_16x16x32_bf16 v[16:19], v[156:159], v[192:195], v[16:19]
	v_mfma_f32_16x16x32_bf16 v[4:7], v[148:151], v[214:217], v[4:7]
	v_mfma_f32_16x16x32_bf16 v[0:3], v[156:159], v[214:217], v[0:3]
	s_setprio 0
	s_barrier
	s_add_i32 s63, s63, 2
	s_add_u32 s30, s30, 0x100
	s_addc_u32 s31, s31, 0
	s_add_u32 s61, s61, 0x100
	s_addc_u32 s62, s62, 0
	s_cmp_gt_u32 s63, 13
	s_cbranch_scc0 .LBB0_2031
	s_lshl_b32 s2, s2, 8
	v_mov_b32_e32 v154, v229
	v_mov_b32_e32 v155, v231
	s_or_b32 s2, s2, s49
	s_mov_b64 s[34:35], s[26:27]
	v_lshl_add_u32 v144, v155, 3, s2
	v_ashrrev_i32_e32 v145, 31, v144
	v_lshlrev_b64 v[188:189], 2, v[144:145]
	v_lshl_add_u64 v[150:151], s[4:5], 0, v[188:189]
	global_load_dwordx4 v[36:39], v[150:151], off offset:16
	global_load_dwordx4 v[44:47], v[150:151], off
	v_lshl_add_u64 v[152:153], s[6:7], 0, v[188:189]
	global_load_dwordx4 v[48:51], v[152:153], off offset:16
	global_load_dwordx4 v[56:59], v[152:153], off
	s_lshl_b32 s2, s28, 8
	s_add_i32 s2, s2, s48
	s_mov_b32 s28, s22
	s_mov_b64 s[30:31], s[24:25]
	s_waitcnt vmcnt(0)
	v_pk_mul_f32 v[184:185], v[38:39], s[18:19] op_sel_hi:[1,0]
	v_pk_mul_f32 v[186:187], v[36:37], s[18:19] op_sel_hi:[1,0]
	global_load_dwordx4 v[146:149], v[150:151], off offset:528
	global_load_dwordx4 v[36:39], v[150:151], off offset:512
	v_pk_mul_f32 v[190:191], v[46:47], s[18:19] op_sel_hi:[1,0]
	v_pk_mul_f32 v[192:193], v[44:45], s[18:19] op_sel_hi:[1,0]
	s_waitcnt vmcnt(1)
	v_pk_mul_f32 v[176:177], v[148:149], s[18:19] op_sel_hi:[1,0]
	v_pk_mul_f32 v[178:179], v[146:147], s[18:19] op_sel_hi:[1,0]
	v_add_u32_e32 v146, s2, v154
	v_lshlrev_b32_e32 v148, 2, v155
	v_ashrrev_i32_e32 v149, 31, v148
	v_ashrrev_i32_e32 v147, 31, v146
	v_lshl_add_u64 v[194:195], v[148:149], 2, s[12:13]
	v_lshl_add_u64 v[148:149], v[146:147], 4, s[10:11]
	s_waitcnt vmcnt(0)
	v_pk_mul_f32 v[180:181], v[38:39], s[18:19] op_sel_hi:[1,0]
	v_pk_mul_f32 v[182:183], v[36:37], s[18:19] op_sel_hi:[1,0]
	global_load_dwordx4 v[36:39], v[152:153], off offset:528
	global_load_dwordx4 v[44:47], v[152:153], off offset:512
	v_lshlrev_b64 v[152:153], 6, v[146:147]
	global_load_dwordx4 v[148:151], v[148:149], off
	v_lshl_add_u64 v[152:153], v[194:195], 0, v[152:153]
	global_load_dwordx4 v[152:155], v[152:153], off
	v_add_u32_e32 v238, 16, v146
	v_ashrrev_i32_e32 v239, 31, v238
	v_lshl_add_u64 v[156:157], v[238:239], 4, s[10:11]
	global_load_dwordx4 v[156:159], v[156:157], off
	v_lshlrev_b64 v[172:173], 6, v[238:239]
	v_lshl_add_u64 v[172:173], v[194:195], 0, v[172:173]
	global_load_dwordx4 v[214:217], v[172:173], off
	v_add_u32_e32 v232, 32, v146
	v_ashrrev_i32_e32 v233, 31, v232
	v_lshl_add_u64 v[172:173], v[232:233], 4, s[10:11]
	global_load_dwordx4 v[218:221], v[172:173], off
	v_lshlrev_b64 v[172:173], 6, v[232:233]
	v_lshl_add_u64 v[172:173], v[194:195], 0, v[172:173]
	global_load_dwordx4 v[222:225], v[172:173], off
	v_add_u32_e32 v226, 48, v146
	v_ashrrev_i32_e32 v227, 31, v226
	v_lshl_add_u64 v[172:173], v[226:227], 4, s[10:11]
	global_load_dwordx4 v[244:247], v[172:173], off
	v_lshlrev_b64 v[172:173], 6, v[226:227]
	v_lshl_add_u64 v[172:173], v[194:195], 0, v[172:173]
	global_load_dwordx4 v[248:251], v[172:173], off
	v_add_u32_e32 v210, 0x90, v146
	v_ashrrev_i32_e32 v211, 31, v210
	v_add_u32_e32 v204, 0xa0, v146
	v_ashrrev_i32_e32 v205, 31, v204
	v_add_u32_e32 v198, 0xb0, v146
	v_ashrrev_i32_e32 v199, 31, v198
	v_lshlrev_b64 v[196:197], 6, v[198:199]
	s_mov_b32 s2, s20
	s_waitcnt vmcnt(7)
	v_mov_b32_e32 v172, v149
	v_mov_b32_e32 v173, v150
	v_mov_b32_e32 v149, v151
	v_pk_add_f32 v[148:149], v[172:173], v[148:149]
	v_lshlrev_b64 v[172:173], 6, v[210:211]
	v_add_f32_e32 v148, v148, v149
	v_fmamk_f32 v148, v148, 0x3a800000, v213
	v_rsq_f32_e32 v148, v148
	s_waitcnt vmcnt(6)
	v_add_f32_e32 v149, v154, v155
	v_lshl_add_u64 v[172:173], v[194:195], 0, v[172:173]
	v_mul_f32_e32 v242, 0xbfb8aa3b, v148
	v_add_f32_e32 v148, v152, v153
	v_add_f32_e32 v148, v148, v149
	v_mov_b32_e32 v149, v148
	s_nop 1
	v_permlane16_swap_b32_e32 v148, v149
	v_add_f32_e32 v148, v148, v149
	v_mov_b32_e32 v149, v148
	s_nop 1
	v_permlane32_swap_b32_e32 v148, v149
	v_add_f32_e32 v148, v148, v149
	v_fmamk_f32 v148, v148, 0x3a800000, v213
	v_rsq_f32_e32 v240, v148
	s_waitcnt vmcnt(5)
	v_mov_b32_e32 v148, v157
	v_mov_b32_e32 v149, v158
	v_mov_b32_e32 v157, v159
	v_pk_add_f32 v[148:149], v[148:149], v[156:157]
	v_lshl_add_u64 v[156:157], v[210:211], 4, s[10:11]
	v_add_f32_e32 v148, v148, v149
	v_fmamk_f32 v148, v148, 0x3a800000, v213
	v_rsq_f32_e32 v148, v148
	s_waitcnt vmcnt(4)
	v_add_f32_e32 v149, v216, v217
	global_load_dwordx4 v[156:159], v[156:157], off
	v_pk_fma_f32 v[142:143], v[142:143], v[242:243], v[190:191] op_sel_hi:[1,0,1]
	v_mul_f32_e32 v236, 0xbfb8aa3b, v148
	v_add_f32_e32 v148, v214, v215
	v_add_f32_e32 v148, v148, v149
	v_mov_b32_e32 v149, v148
	s_nop 1
	v_permlane16_swap_b32_e32 v148, v149
	v_add_f32_e32 v148, v148, v149
	v_mov_b32_e32 v149, v148
	s_nop 1
	v_permlane32_swap_b32_e32 v148, v149
	v_add_f32_e32 v148, v148, v149
	v_fmamk_f32 v148, v148, 0x3a800000, v213
	v_rsq_f32_e32 v234, v148
	s_waitcnt vmcnt(4)
	v_mov_b32_e32 v148, v219
	v_mov_b32_e32 v149, v220
	v_mov_b32_e32 v219, v221
	v_pk_add_f32 v[148:149], v[148:149], v[218:219]
	v_add_u32_e32 v220, 0x80, v146
	v_add_f32_e32 v148, v148, v149
	v_fmamk_f32 v148, v148, 0x3a800000, v213
	v_rsq_f32_e32 v148, v148
	s_waitcnt vmcnt(3)
	v_add_f32_e32 v149, v224, v225
	v_ashrrev_i32_e32 v221, 31, v220
	v_lshlrev_b64 v[152:153], 6, v[220:221]
	v_mul_f32_e32 v230, 0xbfb8aa3b, v148
	v_add_f32_e32 v148, v222, v223
	v_add_f32_e32 v148, v148, v149
	v_mov_b32_e32 v149, v148
	s_nop 1
	v_permlane16_swap_b32_e32 v148, v149
	v_add_f32_e32 v148, v148, v149
	v_mov_b32_e32 v149, v148
	s_nop 1
	v_permlane32_swap_b32_e32 v148, v149
	v_add_f32_e32 v148, v148, v149
	v_fmamk_f32 v148, v148, 0x3a800000, v213
	v_rsq_f32_e32 v228, v148
	s_waitcnt vmcnt(2)
	v_mov_b32_e32 v148, v245
	v_mov_b32_e32 v149, v246
	v_mov_b32_e32 v245, v247
	v_pk_add_f32 v[148:149], v[148:149], v[244:245]
	v_lshl_add_u64 v[152:153], v[194:195], 0, v[152:153]
	v_add_f32_e32 v148, v148, v149
	v_fmamk_f32 v148, v148, 0x3a800000, v213
	v_rsq_f32_e32 v148, v148
	s_waitcnt vmcnt(1)
	v_add_f32_e32 v149, v250, v251
	global_load_dwordx4 v[152:155], v[152:153], off
	v_pk_fma_f32 v[140:141], v[140:141], v[242:243], v[192:193] op_sel_hi:[1,0,1]
	v_mul_f32_e32 v224, 0xbfb8aa3b, v148
	v_add_f32_e32 v148, v248, v249
	v_add_f32_e32 v148, v148, v149
	v_mov_b32_e32 v149, v148
	s_nop 1
	v_permlane16_swap_b32_e32 v148, v149
	v_add_f32_e32 v148, v148, v149
	v_mov_b32_e32 v149, v148
	s_nop 1
	v_permlane32_swap_b32_e32 v148, v149
	v_add_f32_e32 v148, v148, v149
	v_fmamk_f32 v148, v148, 0x3a800000, v213
	v_rsq_f32_e32 v222, v148
	v_lshl_add_u64 v[148:149], v[220:221], 4, s[10:11]
	global_load_dwordx4 v[148:151], v[148:149], off
	v_exp_f32_e32 v142, v142
	global_load_dwordx4 v[216:219], v[172:173], off
	v_lshl_add_u64 v[172:173], v[204:205], 4, s[10:11]
	global_load_dwordx4 v[244:247], v[172:173], off
	v_lshlrev_b64 v[172:173], 6, v[204:205]
	v_lshl_add_u64 v[172:173], v[194:195], 0, v[172:173]
	global_load_dwordx4 v[248:251], v[172:173], off
	v_lshl_add_u64 v[194:195], v[194:195], 0, v[196:197]
	global_load_dwordx4 v[194:197], v[194:195], off
	v_lshl_add_u64 v[172:173], v[198:199], 4, s[10:11]
	global_load_dwordx4 v[172:175], v[172:173], off
	v_exp_f32_e32 v143, v143
	v_exp_f32_e32 v140, v140
	v_exp_f32_e32 v141, v141
	v_pk_fma_f32 v[138:139], v[138:139], v[242:243], v[184:185] op_sel_hi:[1,0,1]
	v_pk_add_f32 v[142:143], v[142:143], 1.0 op_sel_hi:[1,0]
	v_exp_f32_e32 v138, v138
	v_exp_f32_e32 v139, v139
	v_pk_fma_f32 v[136:137], v[136:137], v[242:243], v[186:187] op_sel_hi:[1,0,1]
	v_pk_add_f32 v[140:141], v[140:141], 1.0 op_sel_hi:[1,0]
	v_rcp_f32_e32 v142, v142
	v_rcp_f32_e32 v143, v143
	v_exp_f32_e32 v136, v136
	v_exp_f32_e32 v137, v137
	v_rcp_f32_e32 v140, v140
	v_rcp_f32_e32 v141, v141
	v_pk_add_f32 v[138:139], v[138:139], 1.0 op_sel_hi:[1,0]
	v_pk_add_f32 v[136:137], v[136:137], 1.0 op_sel_hi:[1,0]
	v_rcp_f32_e32 v138, v138
	v_rcp_f32_e32 v139, v139
	v_rcp_f32_e32 v136, v136
	v_rcp_f32_e32 v137, v137
	v_pk_fma_f32 v[132:133], v[132:133], v[242:243], v[182:183] op_sel_hi:[1,0,1]
	v_pk_fma_f32 v[134:135], v[134:135], v[242:243], v[180:181] op_sel_hi:[1,0,1]
	v_exp_f32_e32 v132, v132
	v_exp_f32_e32 v133, v133
	v_exp_f32_e32 v134, v134
	v_exp_f32_e32 v135, v135
	v_pk_fma_f32 v[128:129], v[128:129], v[242:243], v[178:179] op_sel_hi:[1,0,1]
	v_pk_fma_f32 v[130:131], v[130:131], v[242:243], v[176:177] op_sel_hi:[1,0,1]
	v_pk_add_f32 v[132:133], v[132:133], 1.0 op_sel_hi:[1,0]
	v_pk_add_f32 v[134:135], v[134:135], 1.0 op_sel_hi:[1,0]
	v_exp_f32_e32 v128, v128
	v_exp_f32_e32 v129, v129
	v_exp_f32_e32 v130, v130
	v_exp_f32_e32 v131, v131
	v_rcp_f32_e32 v132, v132
	v_rcp_f32_e32 v133, v133
	v_rcp_f32_e32 v134, v134
	v_rcp_f32_e32 v135, v135
	v_pk_add_f32 v[128:129], v[128:129], 1.0 op_sel_hi:[1,0]
	v_pk_add_f32 v[130:131], v[130:131], 1.0 op_sel_hi:[1,0]
	v_rcp_f32_e32 v128, v128
	v_rcp_f32_e32 v129, v129
	v_rcp_f32_e32 v130, v130
	v_rcp_f32_e32 v131, v131
	v_pk_fma_f32 v[126:127], v[126:127], v[236:237], v[190:191] op_sel_hi:[1,0,1]
	v_pk_fma_f32 v[124:125], v[124:125], v[236:237], v[192:193] op_sel_hi:[1,0,1]
	v_exp_f32_e32 v126, v126
	v_exp_f32_e32 v127, v127
	v_exp_f32_e32 v124, v124
	v_exp_f32_e32 v125, v125
	v_pk_fma_f32 v[122:123], v[122:123], v[236:237], v[184:185] op_sel_hi:[1,0,1]
	v_pk_add_f32 v[126:127], v[126:127], 1.0 op_sel_hi:[1,0]
	v_exp_f32_e32 v122, v122
	v_exp_f32_e32 v123, v123
	v_pk_fma_f32 v[120:121], v[120:121], v[236:237], v[186:187] op_sel_hi:[1,0,1]
	v_pk_add_f32 v[124:125], v[124:125], 1.0 op_sel_hi:[1,0]
	v_rcp_f32_e32 v126, v126
	v_rcp_f32_e32 v127, v127
	v_exp_f32_e32 v120, v120
	v_exp_f32_e32 v121, v121
	v_rcp_f32_e32 v124, v124
	v_rcp_f32_e32 v125, v125
	v_pk_add_f32 v[122:123], v[122:123], 1.0 op_sel_hi:[1,0]
	v_pk_add_f32 v[120:121], v[120:121], 1.0 op_sel_hi:[1,0]
	v_rcp_f32_e32 v122, v122
	v_rcp_f32_e32 v123, v123
	v_rcp_f32_e32 v120, v120
	s_waitcnt vmcnt(5)
	v_mov_b32_e32 v214, v149
	v_mov_b32_e32 v215, v150
	v_mov_b32_e32 v149, v151
	v_pk_add_f32 v[148:149], v[214:215], v[148:149]
	v_rcp_f32_e32 v121, v121
	v_add_f32_e32 v148, v148, v149
	v_fmamk_f32 v148, v148, 0x3a800000, v213
	v_rsq_f32_e32 v148, v148
	v_add_f32_e32 v149, v154, v155
	v_pk_fma_f32 v[116:117], v[116:117], v[236:237], v[182:183] op_sel_hi:[1,0,1]
	v_pk_fma_f32 v[118:119], v[118:119], v[236:237], v[180:181] op_sel_hi:[1,0,1]
	v_mul_f32_e32 v214, 0xbfb8aa3b, v148
	v_add_f32_e32 v148, v152, v153
	v_add_f32_e32 v148, v148, v149
	v_mov_b32_e32 v149, v148
	s_nop 1
	v_permlane16_swap_b32_e32 v148, v149
	v_add_f32_e32 v148, v148, v149
	v_mov_b32_e32 v149, v148
	s_nop 1
	v_permlane32_swap_b32_e32 v148, v149
	v_add_f32_e32 v148, v148, v149
	v_fmamk_f32 v148, v148, 0x3a800000, v213
	v_rsq_f32_e32 v212, v148
	v_mov_b32_e32 v148, v157
	v_mov_b32_e32 v149, v158
	v_mov_b32_e32 v157, v159
	v_pk_add_f32 v[148:149], v[148:149], v[156:157]
	v_exp_f32_e32 v116, v116
	v_add_f32_e32 v148, v148, v149
	v_fmamk_f32 v148, v148, 0x3a800000, v213
	v_rsq_f32_e32 v148, v148
	s_waitcnt vmcnt(4)
	v_add_f32_e32 v149, v218, v219
	v_exp_f32_e32 v117, v117
	v_exp_f32_e32 v118, v118
	v_mul_f32_e32 v208, 0xbfb8aa3b, v148
	v_add_f32_e32 v148, v216, v217
	v_add_f32_e32 v148, v148, v149
	v_mov_b32_e32 v149, v148
	s_nop 1
	v_permlane16_swap_b32_e32 v148, v149
	v_add_f32_e32 v148, v148, v149
	v_mov_b32_e32 v149, v148
	s_nop 1
	v_permlane32_swap_b32_e32 v148, v149
	v_add_f32_e32 v148, v148, v149
	v_fmamk_f32 v148, v148, 0x3a800000, v213
	v_rsq_f32_e32 v206, v148
	s_waitcnt vmcnt(3)
	v_mov_b32_e32 v148, v245
	v_mov_b32_e32 v149, v246
	v_mov_b32_e32 v245, v247
	v_pk_add_f32 v[148:149], v[148:149], v[244:245]
	v_lshlrev_b64 v[244:245], 12, v[146:147]
	v_add_f32_e32 v148, v148, v149
	v_fmamk_f32 v148, v148, 0x3a800000, v213
	v_rsq_f32_e32 v148, v148
	s_waitcnt vmcnt(2)
	v_add_f32_e32 v149, v250, v251
	v_exp_f32_e32 v119, v119
	v_pk_fma_f32 v[112:113], v[112:113], v[236:237], v[178:179] op_sel_hi:[1,0,1]
	v_mul_f32_e32 v202, 0xbfb8aa3b, v148
	v_add_f32_e32 v148, v248, v249
	v_add_f32_e32 v148, v148, v149
	v_mov_b32_e32 v149, v148
	s_nop 1
	v_permlane16_swap_b32_e32 v148, v149
	v_add_f32_e32 v148, v148, v149
	v_mov_b32_e32 v149, v148
	s_nop 1
	v_permlane32_swap_b32_e32 v148, v149
	v_add_f32_e32 v148, v148, v149
	v_fmamk_f32 v148, v148, 0x3a800000, v213
	v_rsq_f32_e32 v200, v148
	s_waitcnt vmcnt(0)
	v_mov_b32_e32 v148, v173
	v_mov_b32_e32 v149, v174
	v_mov_b32_e32 v173, v175
	v_pk_add_f32 v[148:149], v[148:149], v[172:173]
	v_pk_fma_f32 v[114:115], v[114:115], v[236:237], v[176:177] op_sel_hi:[1,0,1]
	v_add_f32_e32 v148, v148, v149
	v_fmamk_f32 v148, v148, 0x3a800000, v213
	v_rsq_f32_e32 v148, v148
	v_add_f32_e32 v149, v196, v197
	v_pk_add_f32 v[116:117], v[116:117], 1.0 op_sel_hi:[1,0]
	v_pk_add_f32 v[118:119], v[118:119], 1.0 op_sel_hi:[1,0]
	v_mul_f32_e32 v172, 0xbfb8aa3b, v148
	v_add_f32_e32 v148, v194, v195
	v_add_f32_e32 v148, v148, v149
	v_mov_b32_e32 v149, v148
	s_nop 1
	v_permlane16_swap_b32_e32 v148, v149
	v_add_f32_e32 v148, v148, v149
	v_mov_b32_e32 v149, v148
	s_nop 1
	v_permlane32_swap_b32_e32 v148, v149
	v_add_f32_e32 v148, v148, v149
	v_fmamk_f32 v148, v148, 0x3a800000, v213
	v_rsq_f32_e32 v194, v148
	v_lshlrev_b64 v[148:149], 10, v[146:147]
	v_lshl_add_u64 v[144:145], v[148:149], 0, v[144:145]
	v_lshlrev_b64 v[144:145], 1, v[144:145]
	v_lshl_add_u64 v[216:217], s[68:69], 0, v[144:145]
	v_lshl_add_u64 v[218:219], s[8:9], 0, v[144:145]
	global_load_dwordx4 v[152:155], v[216:217], off
	global_load_dwordx4 v[156:159], v[218:219], off
	global_load_dwordx4 v[148:151], v[216:217], off offset:256
	global_load_dwordx4 v[144:147], v[218:219], off offset:256
	v_exp_f32_e32 v112, v112
	v_exp_f32_e32 v113, v113
	v_exp_f32_e32 v114, v114
	v_exp_f32_e32 v115, v115
	v_rcp_f32_e32 v116, v116
	v_rcp_f32_e32 v117, v117
	v_rcp_f32_e32 v118, v118
	v_rcp_f32_e32 v119, v119
	v_pk_add_f32 v[112:113], v[112:113], 1.0 op_sel_hi:[1,0]
	v_pk_add_f32 v[114:115], v[114:115], 1.0 op_sel_hi:[1,0]
	v_rcp_f32_e32 v112, v112
	v_rcp_f32_e32 v113, v113
	v_rcp_f32_e32 v114, v114
	v_rcp_f32_e32 v115, v115
	v_pk_fma_f32 v[110:111], v[110:111], v[230:231], v[190:191] op_sel_hi:[1,0,1]
	v_pk_fma_f32 v[108:109], v[108:109], v[230:231], v[192:193] op_sel_hi:[1,0,1]
	v_exp_f32_e32 v110, v110
	v_exp_f32_e32 v111, v111
	v_exp_f32_e32 v108, v108
	v_exp_f32_e32 v109, v109
	v_pk_fma_f32 v[106:107], v[106:107], v[230:231], v[184:185] op_sel_hi:[1,0,1]
	v_pk_add_f32 v[110:111], v[110:111], 1.0 op_sel_hi:[1,0]
	v_exp_f32_e32 v106, v106
	v_exp_f32_e32 v107, v107
	v_pk_fma_f32 v[104:105], v[104:105], v[230:231], v[186:187] op_sel_hi:[1,0,1]
	v_pk_add_f32 v[108:109], v[108:109], 1.0 op_sel_hi:[1,0]
	v_rcp_f32_e32 v110, v110
	v_rcp_f32_e32 v111, v111
	v_exp_f32_e32 v104, v104
	v_exp_f32_e32 v105, v105
	v_rcp_f32_e32 v108, v108
	v_rcp_f32_e32 v109, v109
	v_pk_add_f32 v[106:107], v[106:107], 1.0 op_sel_hi:[1,0]
	v_pk_add_f32 v[104:105], v[104:105], 1.0 op_sel_hi:[1,0]
	v_rcp_f32_e32 v106, v106
	v_rcp_f32_e32 v107, v107
	v_rcp_f32_e32 v104, v104
	v_rcp_f32_e32 v105, v105
	v_pk_fma_f32 v[100:101], v[100:101], v[230:231], v[182:183] op_sel_hi:[1,0,1]
	v_pk_fma_f32 v[102:103], v[102:103], v[230:231], v[180:181] op_sel_hi:[1,0,1]
	v_exp_f32_e32 v100, v100
	v_exp_f32_e32 v101, v101
	v_exp_f32_e32 v102, v102
	v_exp_f32_e32 v103, v103
	v_pk_fma_f32 v[96:97], v[96:97], v[230:231], v[178:179] op_sel_hi:[1,0,1]
	v_pk_fma_f32 v[98:99], v[98:99], v[230:231], v[176:177] op_sel_hi:[1,0,1]
	v_pk_add_f32 v[100:101], v[100:101], 1.0 op_sel_hi:[1,0]
	v_pk_add_f32 v[102:103], v[102:103], 1.0 op_sel_hi:[1,0]
	v_exp_f32_e32 v96, v96
	v_exp_f32_e32 v97, v97
	v_exp_f32_e32 v98, v98
	v_exp_f32_e32 v99, v99
	v_rcp_f32_e32 v100, v100
	v_rcp_f32_e32 v101, v101
	v_rcp_f32_e32 v102, v102
	v_rcp_f32_e32 v103, v103
	v_pk_add_f32 v[96:97], v[96:97], 1.0 op_sel_hi:[1,0]
	v_pk_add_f32 v[98:99], v[98:99], 1.0 op_sel_hi:[1,0]
	v_rcp_f32_e32 v96, v96
	v_rcp_f32_e32 v97, v97
	v_rcp_f32_e32 v98, v98
	v_rcp_f32_e32 v99, v99
	v_pk_fma_f32 v[94:95], v[94:95], v[224:225], v[190:191] op_sel_hi:[1,0,1]
	v_pk_fma_f32 v[92:93], v[92:93], v[224:225], v[192:193] op_sel_hi:[1,0,1]
	v_exp_f32_e32 v94, v94
	v_exp_f32_e32 v95, v95
	v_exp_f32_e32 v92, v92
	v_exp_f32_e32 v93, v93
	v_pk_fma_f32 v[90:91], v[90:91], v[224:225], v[184:185] op_sel_hi:[1,0,1]
	v_pk_add_f32 v[94:95], v[94:95], 1.0 op_sel_hi:[1,0]
	v_exp_f32_e32 v90, v90
	v_exp_f32_e32 v91, v91
	v_pk_fma_f32 v[88:89], v[88:89], v[224:225], v[186:187] op_sel_hi:[1,0,1]
	v_pk_add_f32 v[92:93], v[92:93], 1.0 op_sel_hi:[1,0]
	v_rcp_f32_e32 v94, v94
	v_rcp_f32_e32 v95, v95
	s_waitcnt vmcnt(3)
	v_lshlrev_b32_e32 v246, 16, v152
	s_waitcnt vmcnt(2)
	v_lshlrev_b32_e32 v174, 16, v156
	v_and_b32_e32 v175, 0xffff0000, v156
	v_lshlrev_b32_e32 v156, 16, v157
	v_and_b32_e32 v157, 0xffff0000, v157
	v_pk_mul_f32 v[156:157], v[240:241], v[156:157] op_sel_hi:[0,1]
	v_and_b32_e32 v247, 0xffff0000, v152
	v_lshlrev_b32_e32 v152, 16, v153
	v_and_b32_e32 v153, 0xffff0000, v153
	v_pk_mul_f32 v[174:175], v[240:241], v[174:175] op_sel_hi:[0,1]
	v_pk_mul_f32 v[156:157], v[58:59], v[156:157]
	v_pk_mul_f32 v[174:175], v[56:57], v[174:175]
	v_pk_fma_f32 v[142:143], v[142:143], v[156:157], v[152:153]
	v_lshl_add_u64 v[152:153], s[36:37], 0, v[244:245]
	v_lshlrev_b32_e32 v156, 16, v159
	v_and_b32_e32 v157, 0xffff0000, v159
	v_pk_fma_f32 v[140:141], v[140:141], v[174:175], v[246:247]
	v_lshl_add_u64 v[152:153], v[152:153], 0, v[188:189]
	v_pk_mul_f32 v[156:157], v[240:241], v[156:157] op_sel_hi:[0,1]
	global_store_dwordx4 v[152:153], v[140:143], off nt
	v_pk_mul_f32 v[156:157], v[50:51], v[156:157]
	s_waitcnt vmcnt(1)
	v_lshlrev_b32_e32 v174, 16, v144
	v_lshlrev_b32_e32 v140, 16, v154
	v_and_b32_e32 v141, 0xffff0000, v154
	v_lshlrev_b32_e32 v142, 16, v158
	v_and_b32_e32 v143, 0xffff0000, v158
	v_lshlrev_b32_e32 v154, 16, v155
	v_and_b32_e32 v155, 0xffff0000, v155
	v_pk_mul_f32 v[142:143], v[240:241], v[142:143] op_sel_hi:[0,1]
	v_pk_fma_f32 v[138:139], v[138:139], v[156:157], v[154:155]
	v_add_co_u32_e32 v154, vcc, s53, v216
	v_pk_mul_f32 v[142:143], v[48:49], v[142:143]
	s_nop 0
	v_addc_co_u32_e32 v155, vcc, 0, v217, vcc
	v_pk_fma_f32 v[136:137], v[136:137], v[142:143], v[140:141]
	v_add_co_u32_e32 v156, vcc, s53, v218
	global_store_dwordx4 v[152:153], v[136:139], off offset:16 nt
	s_nop 0
	v_addc_co_u32_e32 v157, vcc, 0, v219, vcc
	global_load_dwordx4 v[136:139], v[154:155], off
	global_load_dwordx4 v[140:143], v[156:157], off
	v_and_b32_e32 v175, 0xffff0000, v144
	v_lshlrev_b32_e32 v144, 16, v145
	v_and_b32_e32 v145, 0xffff0000, v145
	v_pk_mul_f32 v[144:145], v[240:241], v[144:145] op_sel_hi:[0,1]
	v_pk_mul_f32 v[174:175], v[240:241], v[174:175] op_sel_hi:[0,1]
	v_lshlrev_b32_e32 v158, 16, v148
	v_and_b32_e32 v159, 0xffff0000, v148
	v_lshlrev_b32_e32 v148, 16, v149
	v_and_b32_e32 v149, 0xffff0000, v149
	v_pk_mul_f32 v[174:175], v[44:45], v[174:175]
	v_pk_mul_f32 v[144:145], v[46:47], v[144:145]
	v_pk_fma_f32 v[132:133], v[132:133], v[174:175], v[158:159]
	v_pk_fma_f32 v[134:135], v[134:135], v[144:145], v[148:149]
	global_store_dwordx4 v[152:153], v[132:135], off offset:512 nt
	v_lshlrev_b32_e32 v144, 16, v151
	v_and_b32_e32 v145, 0xffff0000, v151
	v_lshlrev_b32_e32 v134, 16, v146
	v_and_b32_e32 v135, 0xffff0000, v146
	v_lshlrev_b32_e32 v146, 16, v147
	v_and_b32_e32 v147, 0xffff0000, v147
	v_pk_mul_f32 v[146:147], v[240:241], v[146:147] op_sel_hi:[0,1]
	v_pk_mul_f32 v[134:135], v[240:241], v[134:135] op_sel_hi:[0,1]
	v_lshlrev_b32_e32 v132, 16, v150
	v_and_b32_e32 v133, 0xffff0000, v150
	v_pk_mul_f32 v[134:135], v[36:37], v[134:135]
	v_pk_mul_f32 v[146:147], v[38:39], v[146:147]
	v_pk_fma_f32 v[128:129], v[128:129], v[134:135], v[132:133]
	v_pk_fma_f32 v[130:131], v[130:131], v[146:147], v[144:145]
	global_store_dwordx4 v[152:153], v[128:131], off offset:528 nt
	global_load_dwordx4 v[132:135], v[154:155], off offset:256
	s_nop 0
	global_load_dwordx4 v[128:131], v[156:157], off offset:256
	v_lshlrev_b64 v[144:145], 12, v[238:239]
	v_exp_f32_e32 v88, v88
	v_exp_f32_e32 v89, v89
	v_rcp_f32_e32 v92, v92
	v_rcp_f32_e32 v93, v93
	v_pk_add_f32 v[90:91], v[90:91], 1.0 op_sel_hi:[1,0]
	v_pk_add_f32 v[88:89], v[88:89], 1.0 op_sel_hi:[1,0]
	v_rcp_f32_e32 v90, v90
	v_rcp_f32_e32 v91, v91
	v_rcp_f32_e32 v88, v88
	v_rcp_f32_e32 v89, v89
	v_pk_fma_f32 v[84:85], v[84:85], v[224:225], v[182:183] op_sel_hi:[1,0,1]
	v_pk_fma_f32 v[86:87], v[86:87], v[224:225], v[180:181] op_sel_hi:[1,0,1]
	v_exp_f32_e32 v84, v84
	v_exp_f32_e32 v85, v85
	v_exp_f32_e32 v86, v86
	v_exp_f32_e32 v87, v87
	v_pk_fma_f32 v[80:81], v[80:81], v[224:225], v[178:179] op_sel_hi:[1,0,1]
	v_pk_fma_f32 v[82:83], v[82:83], v[224:225], v[176:177] op_sel_hi:[1,0,1]
	v_pk_add_f32 v[84:85], v[84:85], 1.0 op_sel_hi:[1,0]
	v_pk_add_f32 v[86:87], v[86:87], 1.0 op_sel_hi:[1,0]
	v_exp_f32_e32 v80, v80
	v_exp_f32_e32 v81, v81
	v_exp_f32_e32 v82, v82
	v_exp_f32_e32 v83, v83
	v_rcp_f32_e32 v84, v84
	v_rcp_f32_e32 v85, v85
	v_rcp_f32_e32 v86, v86
	v_rcp_f32_e32 v87, v87
	v_pk_add_f32 v[80:81], v[80:81], 1.0 op_sel_hi:[1,0]
	v_pk_add_f32 v[82:83], v[82:83], 1.0 op_sel_hi:[1,0]
	v_rcp_f32_e32 v80, v80
	v_rcp_f32_e32 v81, v81
	v_rcp_f32_e32 v82, v82
	v_rcp_f32_e32 v83, v83
	v_pk_fma_f32 v[78:79], v[78:79], v[214:215], v[190:191] op_sel_hi:[1,0,1]
	v_pk_fma_f32 v[76:77], v[76:77], v[214:215], v[192:193] op_sel_hi:[1,0,1]
	v_exp_f32_e32 v78, v78
	v_exp_f32_e32 v79, v79
	v_exp_f32_e32 v76, v76
	v_exp_f32_e32 v77, v77
	v_pk_fma_f32 v[74:75], v[74:75], v[214:215], v[184:185] op_sel_hi:[1,0,1]
	v_pk_add_f32 v[78:79], v[78:79], 1.0 op_sel_hi:[1,0]
	v_exp_f32_e32 v74, v74
	v_exp_f32_e32 v75, v75
	v_pk_fma_f32 v[72:73], v[72:73], v[214:215], v[186:187] op_sel_hi:[1,0,1]
	s_waitcnt vmcnt(5)
	v_lshlrev_b32_e32 v146, 16, v136
	s_waitcnt vmcnt(4)
	v_lshlrev_b32_e32 v148, 16, v140
	v_and_b32_e32 v149, 0xffff0000, v140
	v_lshlrev_b32_e32 v140, 16, v141
	v_and_b32_e32 v141, 0xffff0000, v141
	v_pk_mul_f32 v[140:141], v[234:235], v[140:141] op_sel_hi:[0,1]
	v_and_b32_e32 v147, 0xffff0000, v136
	v_lshlrev_b32_e32 v136, 16, v137
	v_and_b32_e32 v137, 0xffff0000, v137
	v_pk_mul_f32 v[148:149], v[234:235], v[148:149] op_sel_hi:[0,1]
	v_pk_mul_f32 v[140:141], v[58:59], v[140:141]
	v_pk_mul_f32 v[148:149], v[56:57], v[148:149]
	v_pk_fma_f32 v[126:127], v[126:127], v[140:141], v[136:137]
	v_lshl_add_u64 v[136:137], s[36:37], 0, v[144:145]
	v_lshlrev_b32_e32 v140, 16, v143
	v_and_b32_e32 v141, 0xffff0000, v143
	v_pk_fma_f32 v[124:125], v[124:125], v[148:149], v[146:147]
	v_lshl_add_u64 v[136:137], v[136:137], 0, v[188:189]
	v_pk_mul_f32 v[140:141], v[234:235], v[140:141] op_sel_hi:[0,1]
	global_store_dwordx4 v[136:137], v[124:127], off nt
	v_pk_mul_f32 v[140:141], v[50:51], v[140:141]
	v_pk_add_f32 v[76:77], v[76:77], 1.0 op_sel_hi:[1,0]
	v_lshlrev_b32_e32 v124, 16, v138
	v_and_b32_e32 v125, 0xffff0000, v138
	v_lshlrev_b32_e32 v126, 16, v142
	v_and_b32_e32 v127, 0xffff0000, v142
	v_lshlrev_b32_e32 v138, 16, v139
	v_and_b32_e32 v139, 0xffff0000, v139
	v_pk_mul_f32 v[126:127], v[234:235], v[126:127] op_sel_hi:[0,1]
	v_pk_fma_f32 v[122:123], v[122:123], v[140:141], v[138:139]
	v_add_co_u32_e32 v138, vcc, s47, v216
	v_pk_mul_f32 v[126:127], v[48:49], v[126:127]
	s_nop 0
	v_addc_co_u32_e32 v139, vcc, 0, v217, vcc
	v_pk_fma_f32 v[120:121], v[120:121], v[126:127], v[124:125]
	v_add_co_u32_e32 v140, vcc, s47, v218
	global_store_dwordx4 v[136:137], v[120:123], off offset:16 nt
	s_nop 0
	v_addc_co_u32_e32 v141, vcc, 0, v219, vcc
	global_load_dwordx4 v[120:123], v[138:139], off
	global_load_dwordx4 v[124:127], v[140:141], off
	s_waitcnt vmcnt(4)
	v_lshlrev_b32_e32 v144, 16, v128
	v_and_b32_e32 v145, 0xffff0000, v128
	v_lshlrev_b32_e32 v128, 16, v129
	v_and_b32_e32 v129, 0xffff0000, v129
	v_pk_mul_f32 v[128:129], v[234:235], v[128:129] op_sel_hi:[0,1]
	v_pk_mul_f32 v[144:145], v[234:235], v[144:145] op_sel_hi:[0,1]
	v_lshlrev_b32_e32 v142, 16, v132
	v_and_b32_e32 v143, 0xffff0000, v132
	v_lshlrev_b32_e32 v132, 16, v133
	v_and_b32_e32 v133, 0xffff0000, v133
	v_pk_mul_f32 v[144:145], v[44:45], v[144:145]
	v_pk_mul_f32 v[128:129], v[46:47], v[128:129]
	v_pk_fma_f32 v[116:117], v[116:117], v[144:145], v[142:143]
	v_pk_fma_f32 v[118:119], v[118:119], v[128:129], v[132:133]
	global_store_dwordx4 v[136:137], v[116:119], off offset:512 nt
	v_lshlrev_b32_e32 v128, 16, v135
	v_and_b32_e32 v129, 0xffff0000, v135
	v_lshlrev_b32_e32 v118, 16, v130
	v_and_b32_e32 v119, 0xffff0000, v130
	v_lshlrev_b32_e32 v130, 16, v131
	v_and_b32_e32 v131, 0xffff0000, v131
	v_pk_mul_f32 v[130:131], v[234:235], v[130:131] op_sel_hi:[0,1]
	v_pk_mul_f32 v[118:119], v[234:235], v[118:119] op_sel_hi:[0,1]
	v_lshlrev_b32_e32 v116, 16, v134
	v_and_b32_e32 v117, 0xffff0000, v134
	v_pk_mul_f32 v[118:119], v[36:37], v[118:119]
	v_pk_mul_f32 v[130:131], v[38:39], v[130:131]
	v_pk_fma_f32 v[112:113], v[112:113], v[118:119], v[116:117]
	v_pk_fma_f32 v[114:115], v[114:115], v[130:131], v[128:129]
	global_store_dwordx4 v[136:137], v[112:115], off offset:528 nt
	global_load_dwordx4 v[116:119], v[138:139], off offset:256
	s_nop 0
	global_load_dwordx4 v[112:115], v[140:141], off offset:256
	v_lshlrev_b64 v[128:129], 12, v[232:233]
	v_rcp_f32_e32 v78, v78
	v_rcp_f32_e32 v79, v79
	v_exp_f32_e32 v72, v72
	v_exp_f32_e32 v73, v73
	v_rcp_f32_e32 v76, v76
	v_rcp_f32_e32 v77, v77
	v_pk_add_f32 v[74:75], v[74:75], 1.0 op_sel_hi:[1,0]
	v_pk_add_f32 v[72:73], v[72:73], 1.0 op_sel_hi:[1,0]
	v_rcp_f32_e32 v74, v74
	v_rcp_f32_e32 v75, v75
	v_pk_fma_f32 v[68:69], v[68:69], v[214:215], v[182:183] op_sel_hi:[1,0,1]
	v_pk_fma_f32 v[70:71], v[70:71], v[214:215], v[180:181] op_sel_hi:[1,0,1]
	v_rcp_f32_e32 v72, v72
	v_rcp_f32_e32 v73, v73
	v_exp_f32_e32 v68, v68
	v_exp_f32_e32 v69, v69
	v_exp_f32_e32 v70, v70
	v_exp_f32_e32 v71, v71
	v_pk_fma_f32 v[64:65], v[64:65], v[214:215], v[178:179] op_sel_hi:[1,0,1]
	v_pk_fma_f32 v[66:67], v[66:67], v[214:215], v[176:177] op_sel_hi:[1,0,1]
	v_pk_add_f32 v[68:69], v[68:69], 1.0 op_sel_hi:[1,0]
	v_pk_add_f32 v[70:71], v[70:71], 1.0 op_sel_hi:[1,0]
	v_exp_f32_e32 v64, v64
	v_exp_f32_e32 v65, v65
	v_exp_f32_e32 v66, v66
	v_exp_f32_e32 v67, v67
	v_rcp_f32_e32 v68, v68
	v_rcp_f32_e32 v69, v69
	v_rcp_f32_e32 v70, v70
	v_rcp_f32_e32 v71, v71
	v_pk_add_f32 v[64:65], v[64:65], 1.0 op_sel_hi:[1,0]
	v_pk_add_f32 v[66:67], v[66:67], 1.0 op_sel_hi:[1,0]
	v_rcp_f32_e32 v64, v64
	v_rcp_f32_e32 v65, v65
	v_rcp_f32_e32 v66, v66
	v_rcp_f32_e32 v67, v67
	v_pk_fma_f32 v[62:63], v[62:63], v[208:209], v[190:191] op_sel_hi:[1,0,1]
	v_pk_fma_f32 v[60:61], v[60:61], v[208:209], v[192:193] op_sel_hi:[1,0,1]
	v_exp_f32_e32 v62, v62
	v_exp_f32_e32 v63, v63
	v_exp_f32_e32 v60, v60
	v_exp_f32_e32 v61, v61
	v_pk_fma_f32 v[54:55], v[54:55], v[208:209], v[184:185] op_sel_hi:[1,0,1]
	v_pk_add_f32 v[62:63], v[62:63], 1.0 op_sel_hi:[1,0]
	s_waitcnt vmcnt(5)
	v_lshlrev_b32_e32 v130, 16, v120
	s_waitcnt vmcnt(4)
	v_lshlrev_b32_e32 v132, 16, v124
	v_and_b32_e32 v133, 0xffff0000, v124
	v_lshlrev_b32_e32 v124, 16, v125
	v_and_b32_e32 v125, 0xffff0000, v125
	v_pk_mul_f32 v[124:125], v[228:229], v[124:125] op_sel_hi:[0,1]
	v_and_b32_e32 v131, 0xffff0000, v120
	v_lshlrev_b32_e32 v120, 16, v121
	v_and_b32_e32 v121, 0xffff0000, v121
	v_pk_mul_f32 v[132:133], v[228:229], v[132:133] op_sel_hi:[0,1]
	v_pk_mul_f32 v[124:125], v[58:59], v[124:125]
	v_pk_mul_f32 v[132:133], v[56:57], v[132:133]
	v_pk_fma_f32 v[110:111], v[110:111], v[124:125], v[120:121]
	v_lshl_add_u64 v[120:121], s[36:37], 0, v[128:129]
	v_lshlrev_b32_e32 v124, 16, v127
	v_and_b32_e32 v125, 0xffff0000, v127
	v_pk_fma_f32 v[108:109], v[108:109], v[132:133], v[130:131]
	v_lshl_add_u64 v[120:121], v[120:121], 0, v[188:189]
	v_pk_mul_f32 v[124:125], v[228:229], v[124:125] op_sel_hi:[0,1]
	global_store_dwordx4 v[120:121], v[108:111], off nt
	v_pk_mul_f32 v[124:125], v[50:51], v[124:125]
	v_exp_f32_e32 v54, v54
	v_lshlrev_b32_e32 v108, 16, v122
	v_and_b32_e32 v109, 0xffff0000, v122
	v_lshlrev_b32_e32 v110, 16, v126
	v_and_b32_e32 v111, 0xffff0000, v126
	v_lshlrev_b32_e32 v122, 16, v123
	v_and_b32_e32 v123, 0xffff0000, v123
	v_pk_mul_f32 v[110:111], v[228:229], v[110:111] op_sel_hi:[0,1]
	v_pk_fma_f32 v[106:107], v[106:107], v[124:125], v[122:123]
	v_add_co_u32_e32 v122, vcc, s52, v216
	v_pk_mul_f32 v[110:111], v[48:49], v[110:111]
	s_nop 0
	v_addc_co_u32_e32 v123, vcc, 0, v217, vcc
	v_pk_fma_f32 v[104:105], v[104:105], v[110:111], v[108:109]
	v_add_co_u32_e32 v124, vcc, s52, v218
	global_store_dwordx4 v[120:121], v[104:107], off offset:16 nt
	s_nop 0
	v_addc_co_u32_e32 v125, vcc, 0, v219, vcc
	global_load_dwordx4 v[104:107], v[122:123], off
	global_load_dwordx4 v[108:111], v[124:125], off
	s_waitcnt vmcnt(4)
	v_lshlrev_b32_e32 v128, 16, v112
	v_and_b32_e32 v129, 0xffff0000, v112
	v_lshlrev_b32_e32 v112, 16, v113
	v_and_b32_e32 v113, 0xffff0000, v113
	v_pk_mul_f32 v[112:113], v[228:229], v[112:113] op_sel_hi:[0,1]
	v_pk_mul_f32 v[128:129], v[228:229], v[128:129] op_sel_hi:[0,1]
	v_lshlrev_b32_e32 v126, 16, v116
	v_and_b32_e32 v127, 0xffff0000, v116
	v_lshlrev_b32_e32 v116, 16, v117
	v_and_b32_e32 v117, 0xffff0000, v117
	v_pk_mul_f32 v[128:129], v[44:45], v[128:129]
	v_pk_mul_f32 v[112:113], v[46:47], v[112:113]
	v_pk_fma_f32 v[100:101], v[100:101], v[128:129], v[126:127]
	v_pk_fma_f32 v[102:103], v[102:103], v[112:113], v[116:117]
	global_store_dwordx4 v[120:121], v[100:103], off offset:512 nt
	v_lshlrev_b32_e32 v112, 16, v119
	v_and_b32_e32 v113, 0xffff0000, v119
	v_lshlrev_b32_e32 v102, 16, v114
	v_and_b32_e32 v103, 0xffff0000, v114
	v_lshlrev_b32_e32 v114, 16, v115
	v_and_b32_e32 v115, 0xffff0000, v115
	v_pk_mul_f32 v[114:115], v[228:229], v[114:115] op_sel_hi:[0,1]
	v_pk_mul_f32 v[102:103], v[228:229], v[102:103] op_sel_hi:[0,1]
	v_lshlrev_b32_e32 v100, 16, v118
	v_and_b32_e32 v101, 0xffff0000, v118
	v_pk_mul_f32 v[102:103], v[36:37], v[102:103]
	v_pk_mul_f32 v[114:115], v[38:39], v[114:115]
	v_pk_fma_f32 v[96:97], v[96:97], v[102:103], v[100:101]
	v_pk_fma_f32 v[98:99], v[98:99], v[114:115], v[112:113]
	global_store_dwordx4 v[120:121], v[96:99], off offset:528 nt
	global_load_dwordx4 v[100:103], v[122:123], off offset:256
	s_nop 0
	global_load_dwordx4 v[96:99], v[124:125], off offset:256
	v_lshlrev_b64 v[112:113], 12, v[226:227]
	v_exp_f32_e32 v55, v55
	v_pk_fma_f32 v[52:53], v[52:53], v[208:209], v[186:187] op_sel_hi:[1,0,1]
	v_pk_add_f32 v[60:61], v[60:61], 1.0 op_sel_hi:[1,0]
	v_rcp_f32_e32 v62, v62
	v_rcp_f32_e32 v63, v63
	v_exp_f32_e32 v52, v52
	v_exp_f32_e32 v53, v53
	v_rcp_f32_e32 v60, v60
	v_rcp_f32_e32 v61, v61
	v_pk_add_f32 v[54:55], v[54:55], 1.0 op_sel_hi:[1,0]
	v_pk_fma_f32 v[40:41], v[40:41], v[208:209], v[182:183] op_sel_hi:[1,0,1]
	v_rcp_f32_e32 v54, v54
	v_rcp_f32_e32 v55, v55
	v_pk_fma_f32 v[42:43], v[42:43], v[208:209], v[180:181] op_sel_hi:[1,0,1]
	v_pk_add_f32 v[52:53], v[52:53], 1.0 op_sel_hi:[1,0]
	v_exp_f32_e32 v40, v40
	v_exp_f32_e32 v41, v41
	v_exp_f32_e32 v42, v42
	v_exp_f32_e32 v43, v43
	v_rcp_f32_e32 v52, v52
	v_rcp_f32_e32 v53, v53
	v_pk_fma_f32 v[32:33], v[32:33], v[208:209], v[178:179] op_sel_hi:[1,0,1]
	v_pk_fma_f32 v[34:35], v[34:35], v[208:209], v[176:177] op_sel_hi:[1,0,1]
	v_pk_add_f32 v[40:41], v[40:41], 1.0 op_sel_hi:[1,0]
	v_pk_add_f32 v[42:43], v[42:43], 1.0 op_sel_hi:[1,0]
	v_exp_f32_e32 v32, v32
	v_exp_f32_e32 v33, v33
	v_exp_f32_e32 v34, v34
	v_exp_f32_e32 v35, v35
	v_rcp_f32_e32 v40, v40
	v_rcp_f32_e32 v41, v41
	v_rcp_f32_e32 v42, v42
	v_rcp_f32_e32 v43, v43
	v_pk_add_f32 v[32:33], v[32:33], 1.0 op_sel_hi:[1,0]
	v_pk_add_f32 v[34:35], v[34:35], 1.0 op_sel_hi:[1,0]
	v_rcp_f32_e32 v32, v32
	v_rcp_f32_e32 v33, v33
	v_rcp_f32_e32 v34, v34
	v_rcp_f32_e32 v35, v35
	v_pk_fma_f32 v[30:31], v[30:31], v[202:203], v[190:191] op_sel_hi:[1,0,1]
	v_pk_fma_f32 v[28:29], v[28:29], v[202:203], v[192:193] op_sel_hi:[1,0,1]
	v_exp_f32_e32 v30, v30
	v_exp_f32_e32 v31, v31
	v_exp_f32_e32 v28, v28
	s_waitcnt vmcnt(5)
	v_lshlrev_b32_e32 v114, 16, v104
	s_waitcnt vmcnt(4)
	v_lshlrev_b32_e32 v116, 16, v108
	v_and_b32_e32 v117, 0xffff0000, v108
	v_lshlrev_b32_e32 v108, 16, v109
	v_and_b32_e32 v109, 0xffff0000, v109
	v_pk_mul_f32 v[108:109], v[222:223], v[108:109] op_sel_hi:[0,1]
	v_and_b32_e32 v115, 0xffff0000, v104
	v_lshlrev_b32_e32 v104, 16, v105
	v_and_b32_e32 v105, 0xffff0000, v105
	v_pk_mul_f32 v[116:117], v[222:223], v[116:117] op_sel_hi:[0,1]
	v_pk_mul_f32 v[108:109], v[58:59], v[108:109]
	v_pk_mul_f32 v[116:117], v[56:57], v[116:117]
	v_pk_fma_f32 v[94:95], v[94:95], v[108:109], v[104:105]
	v_lshl_add_u64 v[104:105], s[36:37], 0, v[112:113]
	v_lshlrev_b32_e32 v108, 16, v111
	v_and_b32_e32 v109, 0xffff0000, v111
	v_pk_fma_f32 v[92:93], v[92:93], v[116:117], v[114:115]
	v_lshl_add_u64 v[104:105], v[104:105], 0, v[188:189]
	v_pk_mul_f32 v[108:109], v[222:223], v[108:109] op_sel_hi:[0,1]
	global_store_dwordx4 v[104:105], v[92:95], off nt
	v_pk_mul_f32 v[108:109], v[50:51], v[108:109]
	v_exp_f32_e32 v29, v29
	v_lshlrev_b32_e32 v92, 16, v106
	v_and_b32_e32 v93, 0xffff0000, v106
	v_lshlrev_b32_e32 v94, 16, v110
	v_and_b32_e32 v95, 0xffff0000, v110
	v_lshlrev_b32_e32 v106, 16, v107
	v_and_b32_e32 v107, 0xffff0000, v107
	v_pk_mul_f32 v[94:95], v[222:223], v[94:95] op_sel_hi:[0,1]
	v_pk_fma_f32 v[90:91], v[90:91], v[108:109], v[106:107]
	v_add_co_u32_e32 v106, vcc, s57, v216
	v_pk_mul_f32 v[94:95], v[48:49], v[94:95]
	s_nop 0
	v_addc_co_u32_e32 v107, vcc, 0, v217, vcc
	v_pk_fma_f32 v[88:89], v[88:89], v[94:95], v[92:93]
	v_add_co_u32_e32 v108, vcc, s57, v218
	global_store_dwordx4 v[104:105], v[88:91], off offset:16 nt
	s_nop 0
	v_addc_co_u32_e32 v109, vcc, 0, v219, vcc
	global_load_dwordx4 v[88:91], v[106:107], off
	global_load_dwordx4 v[92:95], v[108:109], off
	s_waitcnt vmcnt(4)
	v_lshlrev_b32_e32 v112, 16, v96
	v_and_b32_e32 v113, 0xffff0000, v96
	v_lshlrev_b32_e32 v96, 16, v97
	v_and_b32_e32 v97, 0xffff0000, v97
	v_pk_mul_f32 v[96:97], v[222:223], v[96:97] op_sel_hi:[0,1]
	v_pk_mul_f32 v[112:113], v[222:223], v[112:113] op_sel_hi:[0,1]
	v_lshlrev_b32_e32 v110, 16, v100
	v_and_b32_e32 v111, 0xffff0000, v100
	v_lshlrev_b32_e32 v100, 16, v101
	v_and_b32_e32 v101, 0xffff0000, v101
	v_pk_mul_f32 v[112:113], v[44:45], v[112:113]
	v_pk_mul_f32 v[96:97], v[46:47], v[96:97]
	v_pk_fma_f32 v[84:85], v[84:85], v[112:113], v[110:111]
	v_pk_fma_f32 v[86:87], v[86:87], v[96:97], v[100:101]
	global_store_dwordx4 v[104:105], v[84:87], off offset:512 nt
	v_lshlrev_b32_e32 v96, 16, v103
	v_and_b32_e32 v97, 0xffff0000, v103
	v_lshlrev_b32_e32 v86, 16, v98
	v_and_b32_e32 v87, 0xffff0000, v98
	v_lshlrev_b32_e32 v98, 16, v99
	v_and_b32_e32 v99, 0xffff0000, v99
	v_pk_mul_f32 v[98:99], v[222:223], v[98:99] op_sel_hi:[0,1]
	v_pk_mul_f32 v[86:87], v[222:223], v[86:87] op_sel_hi:[0,1]
	v_lshlrev_b32_e32 v84, 16, v102
	v_and_b32_e32 v85, 0xffff0000, v102
	v_pk_mul_f32 v[86:87], v[36:37], v[86:87]
	v_pk_mul_f32 v[98:99], v[38:39], v[98:99]
	v_pk_fma_f32 v[80:81], v[80:81], v[86:87], v[84:85]
	v_pk_fma_f32 v[82:83], v[82:83], v[98:99], v[96:97]
	global_store_dwordx4 v[104:105], v[80:83], off offset:528 nt
	global_load_dwordx4 v[84:87], v[106:107], off offset:256
	s_nop 0
	global_load_dwordx4 v[80:83], v[108:109], off offset:256
	v_lshlrev_b64 v[96:97], 12, v[220:221]
	v_pk_fma_f32 v[26:27], v[26:27], v[202:203], v[184:185] op_sel_hi:[1,0,1]
	v_pk_add_f32 v[30:31], v[30:31], 1.0 op_sel_hi:[1,0]
	v_exp_f32_e32 v26, v26
	v_exp_f32_e32 v27, v27
	v_pk_fma_f32 v[24:25], v[24:25], v[202:203], v[186:187] op_sel_hi:[1,0,1]
	v_pk_add_f32 v[28:29], v[28:29], 1.0 op_sel_hi:[1,0]
	v_rcp_f32_e32 v30, v30
	v_rcp_f32_e32 v31, v31
	v_exp_f32_e32 v24, v24
	v_exp_f32_e32 v25, v25
	v_rcp_f32_e32 v28, v28
	v_rcp_f32_e32 v29, v29
	v_pk_add_f32 v[26:27], v[26:27], 1.0 op_sel_hi:[1,0]
	v_pk_fma_f32 v[20:21], v[20:21], v[202:203], v[182:183] op_sel_hi:[1,0,1]
	v_pk_fma_f32 v[22:23], v[22:23], v[202:203], v[180:181] op_sel_hi:[1,0,1]
	v_rcp_f32_e32 v26, v26
	v_rcp_f32_e32 v27, v27
	v_exp_f32_e32 v20, v20
	v_exp_f32_e32 v21, v21
	v_exp_f32_e32 v22, v22
	v_exp_f32_e32 v23, v23
	v_pk_add_f32 v[24:25], v[24:25], 1.0 op_sel_hi:[1,0]
	v_pk_fma_f32 v[16:17], v[16:17], v[202:203], v[178:179] op_sel_hi:[1,0,1]
	v_rcp_f32_e32 v24, v24
	v_rcp_f32_e32 v25, v25
	v_pk_fma_f32 v[18:19], v[18:19], v[202:203], v[176:177] op_sel_hi:[1,0,1]
	v_pk_add_f32 v[20:21], v[20:21], 1.0 op_sel_hi:[1,0]
	v_pk_add_f32 v[22:23], v[22:23], 1.0 op_sel_hi:[1,0]
	v_exp_f32_e32 v16, v16
	v_exp_f32_e32 v17, v17
	v_exp_f32_e32 v18, v18
	v_exp_f32_e32 v19, v19
	v_rcp_f32_e32 v20, v20
	v_rcp_f32_e32 v21, v21
	v_rcp_f32_e32 v22, v22
	v_rcp_f32_e32 v23, v23
	v_pk_add_f32 v[16:17], v[16:17], 1.0 op_sel_hi:[1,0]
	v_pk_add_f32 v[18:19], v[18:19], 1.0 op_sel_hi:[1,0]
	v_rcp_f32_e32 v16, v16
	v_rcp_f32_e32 v17, v17
	v_rcp_f32_e32 v18, v18
	v_rcp_f32_e32 v19, v19
	v_pk_fma_f32 v[14:15], v[14:15], v[172:173], v[190:191] op_sel_hi:[1,0,1]
	v_pk_fma_f32 v[12:13], v[12:13], v[172:173], v[192:193] op_sel_hi:[1,0,1]
	s_waitcnt vmcnt(5)
	v_lshlrev_b32_e32 v98, 16, v88
	s_waitcnt vmcnt(4)
	v_lshlrev_b32_e32 v100, 16, v92
	v_and_b32_e32 v101, 0xffff0000, v92
	v_lshlrev_b32_e32 v92, 16, v93
	v_and_b32_e32 v93, 0xffff0000, v93
	v_pk_mul_f32 v[92:93], v[212:213], v[92:93] op_sel_hi:[0,1]
	v_and_b32_e32 v99, 0xffff0000, v88
	v_lshlrev_b32_e32 v88, 16, v89
	v_and_b32_e32 v89, 0xffff0000, v89
	v_pk_mul_f32 v[100:101], v[212:213], v[100:101] op_sel_hi:[0,1]
	v_pk_mul_f32 v[92:93], v[58:59], v[92:93]
	v_pk_mul_f32 v[100:101], v[56:57], v[100:101]
	v_pk_fma_f32 v[78:79], v[78:79], v[92:93], v[88:89]
	v_lshl_add_u64 v[88:89], s[36:37], 0, v[96:97]
	v_lshlrev_b32_e32 v92, 16, v95
	v_and_b32_e32 v93, 0xffff0000, v95
	v_pk_fma_f32 v[76:77], v[76:77], v[100:101], v[98:99]
	v_lshl_add_u64 v[88:89], v[88:89], 0, v[188:189]
	v_pk_mul_f32 v[92:93], v[212:213], v[92:93] op_sel_hi:[0,1]
	global_store_dwordx4 v[88:89], v[76:79], off nt
	v_pk_mul_f32 v[92:93], v[50:51], v[92:93]
	v_exp_f32_e32 v14, v14
	v_lshlrev_b32_e32 v76, 16, v90
	v_and_b32_e32 v77, 0xffff0000, v90
	v_lshlrev_b32_e32 v78, 16, v94
	v_and_b32_e32 v79, 0xffff0000, v94
	v_lshlrev_b32_e32 v90, 16, v91
	v_and_b32_e32 v91, 0xffff0000, v91
	v_pk_mul_f32 v[78:79], v[212:213], v[78:79] op_sel_hi:[0,1]
	v_pk_fma_f32 v[74:75], v[74:75], v[92:93], v[90:91]
	v_add_co_u32_e32 v90, vcc, s58, v216
	v_pk_mul_f32 v[78:79], v[48:49], v[78:79]
	s_nop 0
	v_addc_co_u32_e32 v91, vcc, 0, v217, vcc
	v_pk_fma_f32 v[72:73], v[72:73], v[78:79], v[76:77]
	v_add_co_u32_e32 v92, vcc, s58, v218
	global_store_dwordx4 v[88:89], v[72:75], off offset:16 nt
	s_nop 0
	v_addc_co_u32_e32 v93, vcc, 0, v219, vcc
	global_load_dwordx4 v[72:75], v[90:91], off
	global_load_dwordx4 v[76:79], v[92:93], off
	s_waitcnt vmcnt(4)
	v_lshlrev_b32_e32 v96, 16, v80
	v_and_b32_e32 v97, 0xffff0000, v80
	v_lshlrev_b32_e32 v80, 16, v81
	v_and_b32_e32 v81, 0xffff0000, v81
	v_pk_mul_f32 v[80:81], v[212:213], v[80:81] op_sel_hi:[0,1]
	v_pk_mul_f32 v[96:97], v[212:213], v[96:97] op_sel_hi:[0,1]
	v_lshlrev_b32_e32 v94, 16, v84
	v_and_b32_e32 v95, 0xffff0000, v84
	v_lshlrev_b32_e32 v84, 16, v85
	v_and_b32_e32 v85, 0xffff0000, v85
	v_pk_mul_f32 v[96:97], v[44:45], v[96:97]
	v_pk_mul_f32 v[80:81], v[46:47], v[80:81]
	v_pk_fma_f32 v[68:69], v[68:69], v[96:97], v[94:95]
	v_pk_fma_f32 v[70:71], v[70:71], v[80:81], v[84:85]
	global_store_dwordx4 v[88:89], v[68:71], off offset:512 nt
	v_lshlrev_b32_e32 v80, 16, v87
	v_and_b32_e32 v81, 0xffff0000, v87
	v_lshlrev_b32_e32 v70, 16, v82
	v_and_b32_e32 v71, 0xffff0000, v82
	v_lshlrev_b32_e32 v82, 16, v83
	v_and_b32_e32 v83, 0xffff0000, v83
	v_pk_mul_f32 v[82:83], v[212:213], v[82:83] op_sel_hi:[0,1]
	v_pk_mul_f32 v[70:71], v[212:213], v[70:71] op_sel_hi:[0,1]
	v_lshlrev_b32_e32 v68, 16, v86
	v_and_b32_e32 v69, 0xffff0000, v86
	v_pk_mul_f32 v[70:71], v[36:37], v[70:71]
	v_pk_mul_f32 v[82:83], v[38:39], v[82:83]
	v_pk_fma_f32 v[64:65], v[64:65], v[70:71], v[68:69]
	v_pk_fma_f32 v[66:67], v[66:67], v[82:83], v[80:81]
	global_store_dwordx4 v[88:89], v[64:67], off offset:528 nt
	global_load_dwordx4 v[64:67], v[90:91], off offset:256
	s_nop 0
	global_load_dwordx4 v[68:71], v[92:93], off offset:256
	v_lshlrev_b64 v[80:81], 12, v[210:211]
	v_exp_f32_e32 v15, v15
	v_exp_f32_e32 v12, v12
	v_exp_f32_e32 v13, v13
	v_pk_fma_f32 v[8:9], v[8:9], v[172:173], v[186:187] op_sel_hi:[1,0,1]
	v_pk_fma_f32 v[10:11], v[10:11], v[172:173], v[184:185] op_sel_hi:[1,0,1]
	v_exp_f32_e32 v8, v8
	v_exp_f32_e32 v9, v9
	v_exp_f32_e32 v10, v10
	v_exp_f32_e32 v11, v11
	v_pk_add_f32 v[14:15], v[14:15], 1.0 op_sel_hi:[1,0]
	v_pk_add_f32 v[12:13], v[12:13], 1.0 op_sel_hi:[1,0]
	v_rcp_f32_e32 v14, v14
	v_rcp_f32_e32 v15, v15
	v_pk_fma_f32 v[4:5], v[4:5], v[172:173], v[182:183] op_sel_hi:[1,0,1]
	v_pk_fma_f32 v[6:7], v[6:7], v[172:173], v[180:181] op_sel_hi:[1,0,1]
	v_rcp_f32_e32 v12, v12
	v_rcp_f32_e32 v13, v13
	v_pk_add_f32 v[8:9], v[8:9], 1.0 op_sel_hi:[1,0]
	v_pk_add_f32 v[10:11], v[10:11], 1.0 op_sel_hi:[1,0]
	v_exp_f32_e32 v4, v4
	v_exp_f32_e32 v5, v5
	v_exp_f32_e32 v6, v6
	v_exp_f32_e32 v7, v7
	v_rcp_f32_e32 v8, v8
	v_rcp_f32_e32 v9, v9
	v_rcp_f32_e32 v10, v10
	v_rcp_f32_e32 v11, v11
	v_pk_fma_f32 v[0:1], v[0:1], v[172:173], v[178:179] op_sel_hi:[1,0,1]
	v_pk_fma_f32 v[2:3], v[2:3], v[172:173], v[176:177] op_sel_hi:[1,0,1]
	v_pk_add_f32 v[4:5], v[4:5], 1.0 op_sel_hi:[1,0]
	v_pk_add_f32 v[6:7], v[6:7], 1.0 op_sel_hi:[1,0]
	v_exp_f32_e32 v0, v0
	v_exp_f32_e32 v1, v1
	v_exp_f32_e32 v2, v2
	v_exp_f32_e32 v3, v3
	v_rcp_f32_e32 v4, v4
	v_rcp_f32_e32 v5, v5
	v_rcp_f32_e32 v6, v6
	v_rcp_f32_e32 v7, v7
	v_pk_add_f32 v[0:1], v[0:1], 1.0 op_sel_hi:[1,0]
	v_pk_add_f32 v[2:3], v[2:3], 1.0 op_sel_hi:[1,0]
	v_rcp_f32_e32 v0, v0
	v_rcp_f32_e32 v1, v1
	v_rcp_f32_e32 v2, v2
	s_waitcnt vmcnt(5)
	v_lshlrev_b32_e32 v82, 16, v72
	s_waitcnt vmcnt(4)
	v_lshlrev_b32_e32 v84, 16, v76
	v_and_b32_e32 v85, 0xffff0000, v76
	v_lshlrev_b32_e32 v76, 16, v77
	v_and_b32_e32 v77, 0xffff0000, v77
	v_pk_mul_f32 v[76:77], v[206:207], v[76:77] op_sel_hi:[0,1]
	v_and_b32_e32 v83, 0xffff0000, v72
	v_lshlrev_b32_e32 v72, 16, v73
	v_and_b32_e32 v73, 0xffff0000, v73
	v_pk_mul_f32 v[84:85], v[206:207], v[84:85] op_sel_hi:[0,1]
	v_pk_mul_f32 v[76:77], v[58:59], v[76:77]
	v_pk_mul_f32 v[84:85], v[56:57], v[84:85]
	v_pk_fma_f32 v[62:63], v[62:63], v[76:77], v[72:73]
	v_lshl_add_u64 v[72:73], s[36:37], 0, v[80:81]
	v_lshlrev_b32_e32 v76, 16, v79
	v_and_b32_e32 v77, 0xffff0000, v79
	v_pk_fma_f32 v[60:61], v[60:61], v[84:85], v[82:83]
	v_lshl_add_u64 v[72:73], v[72:73], 0, v[188:189]
	v_pk_mul_f32 v[76:77], v[206:207], v[76:77] op_sel_hi:[0,1]
	global_store_dwordx4 v[72:73], v[60:63], off nt
	v_pk_mul_f32 v[76:77], v[50:51], v[76:77]
	v_rcp_f32_e32 v3, v3
	v_lshlrev_b32_e32 v60, 16, v74
	v_and_b32_e32 v61, 0xffff0000, v74
	v_lshlrev_b32_e32 v62, 16, v78
	v_and_b32_e32 v63, 0xffff0000, v78
	v_lshlrev_b32_e32 v74, 16, v75
	v_and_b32_e32 v75, 0xffff0000, v75
	v_pk_mul_f32 v[62:63], v[206:207], v[62:63] op_sel_hi:[0,1]
	v_pk_fma_f32 v[54:55], v[54:55], v[76:77], v[74:75]
	v_add_co_u32_e32 v74, vcc, s59, v216
	v_pk_mul_f32 v[62:63], v[48:49], v[62:63]
	s_nop 0
	v_addc_co_u32_e32 v75, vcc, 0, v217, vcc
	v_pk_fma_f32 v[52:53], v[52:53], v[62:63], v[60:61]
	v_add_co_u32_e32 v76, vcc, s59, v218
	global_store_dwordx4 v[72:73], v[52:55], off offset:16 nt
	s_nop 0
	v_addc_co_u32_e32 v77, vcc, 0, v219, vcc
	s_waitcnt vmcnt(2)
	v_lshlrev_b32_e32 v80, 16, v68
	v_and_b32_e32 v81, 0xffff0000, v68
	v_lshlrev_b32_e32 v68, 16, v69
	v_and_b32_e32 v69, 0xffff0000, v69
	global_load_dwordx4 v[52:55], v[74:75], off
	global_load_dwordx4 v[60:63], v[76:77], off
	v_pk_mul_f32 v[68:69], v[206:207], v[68:69] op_sel_hi:[0,1]
	v_pk_mul_f32 v[80:81], v[206:207], v[80:81] op_sel_hi:[0,1]
	v_lshlrev_b32_e32 v78, 16, v64
	v_and_b32_e32 v79, 0xffff0000, v64
	v_lshlrev_b32_e32 v64, 16, v65
	v_and_b32_e32 v65, 0xffff0000, v65
	v_pk_mul_f32 v[80:81], v[44:45], v[80:81]
	v_pk_mul_f32 v[68:69], v[46:47], v[68:69]
	v_pk_fma_f32 v[40:41], v[40:41], v[80:81], v[78:79]
	v_pk_fma_f32 v[42:43], v[42:43], v[68:69], v[64:65]
	global_store_dwordx4 v[72:73], v[40:43], off offset:512 nt
	v_lshlrev_b32_e32 v64, 16, v67
	v_and_b32_e32 v65, 0xffff0000, v67
	v_lshlrev_b32_e32 v40, 16, v66
	v_and_b32_e32 v41, 0xffff0000, v66
	v_lshlrev_b32_e32 v42, 16, v70
	v_and_b32_e32 v43, 0xffff0000, v70
	v_lshlrev_b32_e32 v66, 16, v71
	v_and_b32_e32 v67, 0xffff0000, v71
	v_pk_mul_f32 v[66:67], v[206:207], v[66:67] op_sel_hi:[0,1]
	v_pk_mul_f32 v[42:43], v[206:207], v[42:43] op_sel_hi:[0,1]
	v_pk_mul_f32 v[42:43], v[36:37], v[42:43]
	v_pk_mul_f32 v[66:67], v[38:39], v[66:67]
	v_pk_fma_f32 v[32:33], v[32:33], v[42:43], v[40:41]
	v_pk_fma_f32 v[34:35], v[34:35], v[66:67], v[64:65]
	global_store_dwordx4 v[72:73], v[32:35], off offset:528 nt
	global_load_dwordx4 v[32:35], v[74:75], off offset:256
	s_nop 0
	global_load_dwordx4 v[40:43], v[76:77], off offset:256
	v_lshlrev_b64 v[64:65], 12, v[204:205]
	s_waitcnt vmcnt(5)
	v_lshlrev_b32_e32 v66, 16, v52
	s_waitcnt vmcnt(4)
	v_lshlrev_b32_e32 v68, 16, v60
	v_and_b32_e32 v69, 0xffff0000, v60
	v_lshlrev_b32_e32 v60, 16, v61
	v_and_b32_e32 v61, 0xffff0000, v61
	v_pk_mul_f32 v[60:61], v[200:201], v[60:61] op_sel_hi:[0,1]
	v_and_b32_e32 v67, 0xffff0000, v52
	v_lshlrev_b32_e32 v52, 16, v53
	v_and_b32_e32 v53, 0xffff0000, v53
	v_pk_mul_f32 v[68:69], v[200:201], v[68:69] op_sel_hi:[0,1]
	v_pk_mul_f32 v[60:61], v[58:59], v[60:61]
	v_pk_mul_f32 v[68:69], v[56:57], v[68:69]
	v_pk_fma_f32 v[30:31], v[30:31], v[60:61], v[52:53]
	v_lshl_add_u64 v[52:53], s[36:37], 0, v[64:65]
	v_lshlrev_b32_e32 v60, 16, v63
	v_and_b32_e32 v61, 0xffff0000, v63
	v_pk_fma_f32 v[28:29], v[28:29], v[68:69], v[66:67]
	v_lshl_add_u64 v[52:53], v[52:53], 0, v[188:189]
	v_pk_mul_f32 v[60:61], v[200:201], v[60:61] op_sel_hi:[0,1]
	global_store_dwordx4 v[52:53], v[28:31], off nt
	v_pk_mul_f32 v[60:61], v[50:51], v[60:61]
	s_waitcnt vmcnt(2)
	v_and_b32_e32 v63, 0xffff0000, v32
	v_lshlrev_b32_e32 v28, 16, v54
	v_and_b32_e32 v29, 0xffff0000, v54
	v_lshlrev_b32_e32 v30, 16, v62
	v_and_b32_e32 v31, 0xffff0000, v62
	v_lshlrev_b32_e32 v54, 16, v55
	v_and_b32_e32 v55, 0xffff0000, v55
	v_pk_mul_f32 v[30:31], v[200:201], v[30:31] op_sel_hi:[0,1]
	v_pk_fma_f32 v[26:27], v[26:27], v[60:61], v[54:55]
	v_add_co_u32_e32 v54, vcc, s60, v216
	v_pk_mul_f32 v[30:31], v[48:49], v[30:31]
	s_nop 0
	v_addc_co_u32_e32 v55, vcc, 0, v217, vcc
	v_pk_fma_f32 v[24:25], v[24:25], v[30:31], v[28:29]
	v_add_co_u32_e32 v60, vcc, s60, v218
	s_waitcnt vmcnt(1)
	v_lshlrev_b32_e32 v64, 16, v40
	v_and_b32_e32 v65, 0xffff0000, v40
	v_lshlrev_b32_e32 v40, 16, v41
	v_and_b32_e32 v41, 0xffff0000, v41
	global_store_dwordx4 v[52:53], v[24:27], off offset:16 nt
	v_addc_co_u32_e32 v61, vcc, 0, v219, vcc
	v_pk_mul_f32 v[40:41], v[200:201], v[40:41] op_sel_hi:[0,1]
	v_pk_mul_f32 v[64:65], v[200:201], v[64:65] op_sel_hi:[0,1]
	global_load_dwordx4 v[24:27], v[54:55], off
	global_load_dwordx4 v[28:31], v[60:61], off
	v_lshlrev_b32_e32 v62, 16, v32
	v_lshlrev_b32_e32 v32, 16, v33
	v_and_b32_e32 v33, 0xffff0000, v33
	v_pk_mul_f32 v[64:65], v[44:45], v[64:65]
	v_pk_mul_f32 v[40:41], v[46:47], v[40:41]
	v_pk_fma_f32 v[20:21], v[20:21], v[64:65], v[62:63]
	v_pk_fma_f32 v[22:23], v[22:23], v[40:41], v[32:33]
	global_store_dwordx4 v[52:53], v[20:23], off offset:512 nt
	v_lshlrev_b32_e32 v32, 16, v35
	v_and_b32_e32 v33, 0xffff0000, v35
	v_lshlrev_b32_e32 v20, 16, v34
	v_and_b32_e32 v21, 0xffff0000, v34
	v_lshlrev_b32_e32 v22, 16, v42
	v_and_b32_e32 v23, 0xffff0000, v42
	v_lshlrev_b32_e32 v34, 16, v43
	v_and_b32_e32 v35, 0xffff0000, v43
	v_pk_mul_f32 v[34:35], v[200:201], v[34:35] op_sel_hi:[0,1]
	v_pk_mul_f32 v[22:23], v[200:201], v[22:23] op_sel_hi:[0,1]
	v_pk_mul_f32 v[22:23], v[36:37], v[22:23]
	v_pk_mul_f32 v[34:35], v[38:39], v[34:35]
	v_pk_fma_f32 v[16:17], v[16:17], v[22:23], v[20:21]
	v_pk_fma_f32 v[18:19], v[18:19], v[34:35], v[32:33]
	global_store_dwordx4 v[52:53], v[16:19], off offset:528 nt
	global_load_dwordx4 v[16:19], v[54:55], off offset:256
	s_nop 0
	global_load_dwordx4 v[20:23], v[60:61], off offset:256
	v_lshlrev_b64 v[40:41], 12, v[198:199]
	s_and_b64 vcc, exec, s[0:1]
	s_waitcnt vmcnt(5)
	v_lshlrev_b32_e32 v32, 16, v24
	s_waitcnt vmcnt(4)
	v_lshlrev_b32_e32 v34, 16, v28
	v_and_b32_e32 v35, 0xffff0000, v28
	v_lshlrev_b32_e32 v28, 16, v29
	v_and_b32_e32 v29, 0xffff0000, v29
	v_pk_mul_f32 v[28:29], v[194:195], v[28:29] op_sel_hi:[0,1]
	v_and_b32_e32 v33, 0xffff0000, v24
	v_lshlrev_b32_e32 v24, 16, v25
	v_and_b32_e32 v25, 0xffff0000, v25
	v_pk_mul_f32 v[34:35], v[194:195], v[34:35] op_sel_hi:[0,1]
	v_pk_mul_f32 v[28:29], v[58:59], v[28:29]
	v_pk_mul_f32 v[42:43], v[56:57], v[34:35]
	v_pk_fma_f32 v[34:35], v[14:15], v[28:29], v[24:25]
	v_lshlrev_b32_e32 v24, 16, v30
	v_and_b32_e32 v25, 0xffff0000, v30
	v_lshlrev_b32_e32 v28, 16, v31
	v_and_b32_e32 v29, 0xffff0000, v31
	v_pk_mul_f32 v[28:29], v[194:195], v[28:29] op_sel_hi:[0,1]
	v_pk_mul_f32 v[24:25], v[194:195], v[24:25] op_sel_hi:[0,1]
	v_pk_fma_f32 v[32:33], v[12:13], v[42:43], v[32:33]
	v_lshl_add_u64 v[12:13], s[36:37], 0, v[40:41]
	v_lshlrev_b32_e32 v14, 16, v26
	v_and_b32_e32 v15, 0xffff0000, v26
	v_lshlrev_b32_e32 v26, 16, v27
	v_and_b32_e32 v27, 0xffff0000, v27
	v_pk_mul_f32 v[24:25], v[48:49], v[24:25]
	v_pk_mul_f32 v[28:29], v[50:51], v[28:29]
	v_lshl_add_u64 v[12:13], v[12:13], 0, v[188:189]
	v_pk_fma_f32 v[10:11], v[10:11], v[28:29], v[26:27]
	v_pk_fma_f32 v[8:9], v[8:9], v[24:25], v[14:15]
	global_store_dwordx4 v[12:13], v[8:11], off offset:16 nt
	s_waitcnt vmcnt(2)
	v_lshlrev_b32_e32 v14, 16, v17
	v_and_b32_e32 v15, 0xffff0000, v17
	v_lshlrev_b32_e32 v8, 16, v16
	v_and_b32_e32 v9, 0xffff0000, v16
	s_waitcnt vmcnt(1)
	v_lshlrev_b32_e32 v10, 16, v20
	v_and_b32_e32 v11, 0xffff0000, v20
	v_lshlrev_b32_e32 v16, 16, v21
	v_and_b32_e32 v17, 0xffff0000, v21
	v_pk_mul_f32 v[16:17], v[194:195], v[16:17] op_sel_hi:[0,1]
	v_pk_mul_f32 v[10:11], v[194:195], v[10:11] op_sel_hi:[0,1]
	v_pk_mul_f32 v[10:11], v[44:45], v[10:11]
	v_pk_mul_f32 v[16:17], v[46:47], v[16:17]
	v_pk_fma_f32 v[4:5], v[4:5], v[10:11], v[8:9]
	v_pk_fma_f32 v[6:7], v[6:7], v[16:17], v[14:15]
	global_store_dwordx4 v[12:13], v[4:7], off offset:512 nt
	v_lshlrev_b32_e32 v10, 16, v23
	v_and_b32_e32 v11, 0xffff0000, v23
	v_lshlrev_b32_e32 v6, 16, v22
	v_and_b32_e32 v7, 0xffff0000, v22
	v_pk_mul_f32 v[10:11], v[194:195], v[10:11] op_sel_hi:[0,1]
	v_pk_mul_f32 v[6:7], v[194:195], v[6:7] op_sel_hi:[0,1]
	v_lshlrev_b32_e32 v4, 16, v18
	v_and_b32_e32 v5, 0xffff0000, v18
	v_lshlrev_b32_e32 v8, 16, v19
	v_and_b32_e32 v9, 0xffff0000, v19
	v_pk_mul_f32 v[6:7], v[36:37], v[6:7]
	v_pk_mul_f32 v[10:11], v[38:39], v[10:11]
	v_pk_fma_f32 v[0:1], v[0:1], v[6:7], v[4:5]
	v_pk_fma_f32 v[2:3], v[2:3], v[10:11], v[8:9]
	global_store_dwordx4 v[12:13], v[32:35], off nt
	global_store_dwordx4 v[12:13], v[0:3], off offset:528 nt
	s_cbranch_vccz .LBB0_2024
	s_waitcnt vmcnt(0)
	s_cmpk_gt_u32 s19, 0xff
	s_cbranch_scc1 .LBB0_2035
	s_barrier
